# EpiX1 epilogue: residual loads batched with counted waits; LRU pass-1 item constants: 11 loads issued together + hw exp2/log2 softplus; attention QK^T+bias: pipelined LDS reads
# speedup vs baseline: 1.0217x; 1.0217x over previous
; #define PG8_STAGE(bufoff, gbase, voff) do { _Pragma("unroll") for (int _i = 0; _i < 2; ++_i) \
;         __builtin_amdgcn_global_load_lds((const unsigned*)((const char*)(gbase) + (voff)[_i]), (PG8_LAS unsigned*)(lds + (bufoff) + ldsw + _i * 8192), 16, 0, 0); } while (0)
; #define PG8_LDA(dst, b, h) do { _Pragma("unroll") for (int m = 0; m < 4; ++m) _Pragma("unroll") for (int k = 0; k < 2; ++k) dst[m][k] = *(const PG8_LAS bf16x8*)(lds + PG8_SA(b, h) + aoff + m * 2048 + k * 1024); } while (0)
; #define PG8_LDB(dst, b, h) do { _Pragma("unroll") for (int n = 0; n < 2; ++n) _Pragma("unroll") for (int k = 0; k < 2; ++k) dst[n][k] = *(const PG8_LAS bf16x8*)(lds + PG8_SB(b, h) + boff + n * 2048 + k * 1024); } while (0)
; #define PG8_MMA(ai, bj, At, Bt) do { __builtin_amdgcn_s_setprio(1); _Pragma("unroll") for (int m = 0; m < 4; ++m) _Pragma("unroll") for (int n = 0; n < 2; ++n) _Pragma("unroll") for (int k = 0; k < 2; ++k) \
;         acc[ai][bj][m][n] = __builtin_amdgcn_mfma_f32_16x16x32_bf16(Bt[n][k], At[m][k], acc[ai][bj][m][n], 0, 0, 0); __builtin_amdgcn_s_setprio(0); } while (0)
; #define PG8_WAIT_V(n) asm volatile("s_waitcnt vmcnt(" #n ")" ::: "memory")
; #define PG8_WAIT_L(n) asm volatile("s_waitcnt lgkmcnt(" #n ")" ::: "memory")
; template <class Epi, class Sched, bool ALIGN_EPI = false, bool SP2 = false>
; __device__ __forceinline__ void gemm_phase(PG8_LAS unsigned char* lds, const Gemm g, const Sched& S, const Epi& E) {
;     ...
;             const bool last = (t == nt - 2);
;             const char* a1 = cA + (size_t)(t + 1) * kstep;
;             const char* a2 = last ? nA : cA + (size_t)(t + 2) * kstep; const char* b2 = last ? nB : cB + (size_t)(t + 2) * kstep;
;             const char* a3 = a2 + kstep; const char* b3 = b2 + kstep;
;             if (last && has_next) S.a_ready(nxt);
;             if constexpr (SP2) {
;             PG8_LDB(B0, 0, 0); PG8_LDB(B1, 0, 1); PG8_SCHED; PG8_LDA(At, 0, 0); PG8_STAGE(PG8_SA(1, 1), a1 + hstep, voffA);
;             PG8_WAIT_V(8); PG8_WAIT_L(0); PG8_BAR; PG8_MMA(0, 0, At, B0); PG8_MMA(0, 1, At, B1); PG8_BAR; PG8_SCHED;
;             PG8_LDA(At, 0, 1); PG8_STAGE(PG8_SB(0, 0), b2, voffB); PG8_STAGE(PG8_SB(0, 1), b2 + hstep, voffB); PG8_STAGE(PG8_SA(0, 0), a2, voffA);
;             PG8_WAIT_V(8); PG8_WAIT_L(0); PG8_BAR; PG8_MMA(1, 0, At, B0); PG8_MMA(1, 1, At, B1); PG8_BAR; PG8_SCHED;
.LBB0_76:
	s_add_u32 s18, s0, 0xfff80080
	s_addc_u32 s19, s1, -1
	s_add_i32 s47, 0, 0x10000
	s_cmp_eq_u32 s46, 28
	s_cselect_b32 s59, s60, s19
	s_cselect_b32 s58, s73, s18
	v_add_u32_e32 v158, s47, v143
	s_cselect_b32 s19, s45, s79
	s_cselect_b32 s18, s84, s78
	s_add_i32 s80, 0, 0x14000
	ds_read_b128 v[162:165], v158
	ds_read_b128 v[166:169], v158 offset:1024
	ds_read_b128 v[170:173], v158 offset:2048
	ds_read_b128 v[174:177], v158 offset:3072
	v_add_u32_e32 v158, s80, v143
	ds_read_b128 v[178:181], v158
	ds_read_b128 v[182:185], v158 offset:1024
	ds_read_b128 v[204:207], v158 offset:2048
	ds_read_b128 v[208:211], v158 offset:3072
	v_lshl_add_u64 v[158:159], s[0:1], 0, v[154:155]
	s_add_i32 m0, s62, 0xc000
	ds_read_b128 v[212:215], v161
	ds_read_b128 v[216:219], v161 offset:1024
	ds_read_b128 v[220:223], v161 offset:2048
	ds_read_b128 v[224:227], v161 offset:3072
	ds_read_b128 v[228:231], v161 offset:4096
	ds_read_b128 v[232:235], v161 offset:5120
	ds_read_b128 v[236:239], v161 offset:6144
	ds_read_b128 v[240:243], v161 offset:7168
	global_load_lds_dwordx4 v[158:159], off
	v_lshl_add_u64 v[158:159], s[0:1], 0, v[156:157]
	s_add_i32 m0, s62, 0xe000
	s_nop 0
	global_load_lds_dwordx4 v[158:159], off
	s_waitcnt vmcnt(8)
	s_waitcnt lgkmcnt(0)
	s_barrier
	s_setprio 1
	s_waitcnt lgkmcnt(0)
	v_mfma_f32_16x16x32_bf16 v[126:129], v[162:165], v[212:215], v[126:129]
	v_mfma_f32_16x16x32_bf16 v[122:125], v[170:173], v[212:215], v[122:125]
	v_mfma_f32_16x16x32_bf16 v[110:113], v[162:165], v[220:223], v[110:113]
	v_mfma_f32_16x16x32_bf16 v[106:109], v[170:173], v[220:223], v[106:109]
	v_mfma_f32_16x16x32_bf16 v[94:97], v[162:165], v[228:231], v[94:97]
	v_mfma_f32_16x16x32_bf16 v[90:93], v[170:173], v[228:231], v[90:93]
	v_mfma_f32_16x16x32_bf16 v[78:81], v[162:165], v[236:239], v[78:81]
	v_mfma_f32_16x16x32_bf16 v[74:77], v[170:173], v[236:239], v[74:77]
	v_mfma_f32_16x16x32_bf16 v[126:129], v[166:169], v[216:219], v[126:129]
	v_mfma_f32_16x16x32_bf16 v[122:125], v[174:177], v[216:219], v[122:125]
	v_mfma_f32_16x16x32_bf16 v[110:113], v[166:169], v[224:227], v[110:113]
	v_mfma_f32_16x16x32_bf16 v[106:109], v[174:177], v[224:227], v[106:109]
	v_mfma_f32_16x16x32_bf16 v[94:97], v[166:169], v[232:235], v[94:97]
	v_mfma_f32_16x16x32_bf16 v[90:93], v[174:177], v[232:235], v[90:93]
	v_mfma_f32_16x16x32_bf16 v[78:81], v[166:169], v[240:243], v[78:81]
	v_mfma_f32_16x16x32_bf16 v[74:77], v[174:177], v[240:243], v[74:77]
	s_setprio 0
	s_setprio 1
	v_mfma_f32_16x16x32_bf16 v[118:121], v[178:181], v[212:215], v[118:121]
	v_mfma_f32_16x16x32_bf16 v[114:117], v[204:207], v[212:215], v[114:117]
	v_mfma_f32_16x16x32_bf16 v[102:105], v[178:181], v[220:223], v[102:105]
	v_mfma_f32_16x16x32_bf16 v[98:101], v[204:207], v[220:223], v[98:101]
	v_mfma_f32_16x16x32_bf16 v[86:89], v[178:181], v[228:231], v[86:89]
	v_mfma_f32_16x16x32_bf16 v[82:85], v[204:207], v[228:231], v[82:85]
	v_mfma_f32_16x16x32_bf16 v[70:73], v[178:181], v[236:239], v[70:73]
	v_mfma_f32_16x16x32_bf16 v[66:69], v[204:207], v[236:239], v[66:69]
	v_mfma_f32_16x16x32_bf16 v[118:121], v[182:185], v[216:219], v[118:121]
	v_mfma_f32_16x16x32_bf16 v[114:117], v[208:211], v[216:219], v[114:117]
	v_mfma_f32_16x16x32_bf16 v[102:105], v[182:185], v[224:227], v[102:105]
	v_mfma_f32_16x16x32_bf16 v[98:101], v[208:211], v[224:227], v[98:101]
	v_mfma_f32_16x16x32_bf16 v[86:89], v[182:185], v[232:235], v[86:89]
	v_mfma_f32_16x16x32_bf16 v[82:85], v[208:211], v[232:235], v[82:85]
	v_mfma_f32_16x16x32_bf16 v[70:73], v[182:185], v[240:243], v[70:73]
	v_mfma_f32_16x16x32_bf16 v[66:69], v[208:211], v[240:243], v[66:69]
	s_setprio 0
	s_barrier
	s_add_i32 s47, s47, s54
	v_lshl_add_u64 v[158:159], s[18:19], 0, v[148:149]
	s_mov_b32 m0, s47
	ds_read_b128 v[212:215], v161 offset:16384
	ds_read_b128 v[216:219], v161 offset:17408
	ds_read_b128 v[220:223], v161 offset:18432
	ds_read_b128 v[224:227], v161 offset:19456
	ds_read_b128 v[228:231], v161 offset:20480
	ds_read_b128 v[232:235], v161 offset:21504
	ds_read_b128 v[236:239], v161 offset:22528
	ds_read_b128 v[240:243], v161 offset:23552
	global_load_lds_dwordx4 v[158:159], off
	s_add_i32 m0, s47, 0x2000
	s_add_u32 s76, s18, 0x80000
	v_lshl_add_u64 v[186:187], s[18:19], 0, v[144:145]
	s_addc_u32 s77, s19, 0
	s_add_i32 s47, s80, s54
	global_load_lds_dwordx4 v[186:187], off
	v_lshl_add_u64 v[244:245], s[76:77], 0, v[148:149]
	s_mov_b32 m0, s47
	v_lshl_add_u64 v[246:247], s[58:59], 0, v[146:147]
	global_load_lds_dwordx4 v[244:245], off
	v_lshl_add_u64 v[244:245], s[76:77], 0, v[144:145]
	s_add_i32 m0, s47, 0x2000
	s_nop 0
	global_load_lds_dwordx4 v[244:245], off
	v_lshl_add_u64 v[244:245], s[58:59], 0, v[150:151]
	s_mov_b32 m0, s62
	s_nop 0
	global_load_lds_dwordx4 v[244:245], off
	s_mov_b32 m0, s63
	s_nop 0
	global_load_lds_dwordx4 v[246:247], off
	s_waitcnt vmcnt(8)
	s_waitcnt lgkmcnt(0)
	s_barrier
; #define PG8_STAGE(bufoff, gbase, voff) do { _Pragma("unroll") for (int _i = 0; _i < 2; ++_i) \
;         __builtin_amdgcn_global_load_lds((const unsigned*)((const char*)(gbase) + (voff)[_i]), (PG8_LAS unsigned*)(lds + (bufoff) + ldsw + _i * 8192), 16, 0, 0); } while (0)
; #define PG8_LDA(dst, b, h) do { _Pragma("unroll") for (int m = 0; m < 4; ++m) _Pragma("unroll") for (int k = 0; k < 2; ++k) dst[m][k] = *(const PG8_LAS bf16x8*)(lds + PG8_SA(b, h) + aoff + m * 2048 + k * 1024); } while (0)
; #define PG8_LDB(dst, b, h) do { _Pragma("unroll") for (int n = 0; n < 2; ++n) _Pragma("unroll") for (int k = 0; k < 2; ++k) dst[n][k] = *(const PG8_LAS bf16x8*)(lds + PG8_SB(b, h) + boff + n * 2048 + k * 1024); } while (0)
; #define PG8_MMA(ai, bj, At, Bt) do { __builtin_amdgcn_s_setprio(1); _Pragma("unroll") for (int m = 0; m < 4; ++m) _Pragma("unroll") for (int n = 0; n < 2; ++n) _Pragma("unroll") for (int k = 0; k < 2; ++k) \
;         acc[ai][bj][m][n] = __builtin_amdgcn_mfma_f32_16x16x32_bf16(Bt[n][k], At[m][k], acc[ai][bj][m][n], 0, 0, 0); __builtin_amdgcn_s_setprio(0); } while (0)
; #define PG8_WAIT_V(n) asm volatile("s_waitcnt vmcnt(" #n ")" ::: "memory")
; #define PG8_WAIT_L(n) asm volatile("s_waitcnt lgkmcnt(" #n ")" ::: "memory")
; #define PG8_BAR __builtin_amdgcn_s_barrier()
; #define PG8_SCHED __builtin_amdgcn_sched_barrier(0)
; template <class Epi, class Sched, bool ALIGN_EPI = false, bool SP2 = false>
; __device__ __forceinline__ void gemm_phase(PG8_LAS unsigned char* lds, const Gemm g, const Sched& S, const Epi& E) {
;     ...
;             PG8_WAIT_V(8); PG8_WAIT_L(0); PG8_BAR; PG8_MMA(1, 0, At, B0); PG8_MMA(1, 1, At, B1); PG8_BAR; PG8_SCHED;
;             PG8_LDB(B0, 1, 0); PG8_LDB(B1, 1, 1); PG8_SCHED; PG8_LDA(At, 1, 0); PG8_STAGE(PG8_SA(0, 1), a2 + hstep, voffA);
;             PG8_WAIT_V(8); PG8_WAIT_L(0); PG8_BAR; PG8_MMA(0, 0, At, B0); PG8_MMA(0, 1, At, B1); PG8_BAR; PG8_SCHED;
;             PG8_LDA(At, 1, 1); PG8_STAGE(PG8_SB(1, 0), b3, voffB); PG8_STAGE(PG8_SB(1, 1), b3 + hstep, voffB); PG8_STAGE(PG8_SA(1, 0), a3, voffA);
;             PG8_WAIT_V(8); PG8_WAIT_L(0); PG8_BAR; PG8_MMA(1, 0, At, B0); PG8_MMA(1, 1, At, B1); PG8_BAR; PG8_SCHED;
	s_setprio 1
	s_waitcnt lgkmcnt(0)
	v_mfma_f32_16x16x32_bf16 v[62:65], v[162:165], v[212:215], v[62:65]
	v_mfma_f32_16x16x32_bf16 v[58:61], v[170:173], v[212:215], v[58:61]
	v_mfma_f32_16x16x32_bf16 v[46:49], v[162:165], v[220:223], v[46:49]
	v_mfma_f32_16x16x32_bf16 v[42:45], v[170:173], v[220:223], v[42:45]
	v_mfma_f32_16x16x32_bf16 v[30:33], v[162:165], v[228:231], v[30:33]
	v_mfma_f32_16x16x32_bf16 v[26:29], v[170:173], v[228:231], v[26:29]
	v_mfma_f32_16x16x32_bf16 v[14:17], v[162:165], v[236:239], v[14:17]
	v_mfma_f32_16x16x32_bf16 v[10:13], v[170:173], v[236:239], v[10:13]
	v_mfma_f32_16x16x32_bf16 v[62:65], v[166:169], v[216:219], v[62:65]
	v_mfma_f32_16x16x32_bf16 v[58:61], v[174:177], v[216:219], v[58:61]
	v_mfma_f32_16x16x32_bf16 v[46:49], v[166:169], v[224:227], v[46:49]
	v_mfma_f32_16x16x32_bf16 v[42:45], v[174:177], v[224:227], v[42:45]
	v_mfma_f32_16x16x32_bf16 v[30:33], v[166:169], v[232:235], v[30:33]
	v_mfma_f32_16x16x32_bf16 v[26:29], v[174:177], v[232:235], v[26:29]
	v_mfma_f32_16x16x32_bf16 v[14:17], v[166:169], v[240:243], v[14:17]
	v_mfma_f32_16x16x32_bf16 v[10:13], v[174:177], v[240:243], v[10:13]
	s_setprio 0
	s_setprio 1
	v_mfma_f32_16x16x32_bf16 v[54:57], v[178:181], v[212:215], v[54:57]
	v_mfma_f32_16x16x32_bf16 v[50:53], v[204:207], v[212:215], v[50:53]
	v_mfma_f32_16x16x32_bf16 v[38:41], v[178:181], v[220:223], v[38:41]
	v_mfma_f32_16x16x32_bf16 v[34:37], v[204:207], v[220:223], v[34:37]
	v_mfma_f32_16x16x32_bf16 v[22:25], v[178:181], v[228:231], v[22:25]
	v_mfma_f32_16x16x32_bf16 v[18:21], v[204:207], v[228:231], v[18:21]
	v_mfma_f32_16x16x32_bf16 v[6:9], v[178:181], v[236:239], v[6:9]
	v_mfma_f32_16x16x32_bf16 v[2:5], v[204:207], v[236:239], v[2:5]
	v_mfma_f32_16x16x32_bf16 v[54:57], v[182:185], v[216:219], v[54:57]
	v_mfma_f32_16x16x32_bf16 v[50:53], v[208:211], v[216:219], v[50:53]
	v_mfma_f32_16x16x32_bf16 v[38:41], v[182:185], v[224:227], v[38:41]
	v_mfma_f32_16x16x32_bf16 v[34:37], v[208:211], v[224:227], v[34:37]
	v_mfma_f32_16x16x32_bf16 v[22:25], v[182:185], v[232:235], v[22:25]
	v_mfma_f32_16x16x32_bf16 v[18:21], v[208:211], v[232:235], v[18:21]
	v_mfma_f32_16x16x32_bf16 v[6:9], v[182:185], v[240:243], v[6:9]
	v_mfma_f32_16x16x32_bf16 v[2:5], v[208:211], v[240:243], v[2:5]
	s_setprio 0
	s_barrier
	s_add_i32 s47, 0, 0x18000
	s_add_i32 s76, 0, 0x1c000
	v_add_u32_e32 v174, s47, v143
	v_add_u32_e32 v203, s76, v143
	ds_read_b128 v[162:165], v174
	ds_read_b128 v[166:169], v174 offset:1024
	ds_read_b128 v[170:173], v174 offset:2048
	ds_read_b128 v[174:177], v174 offset:3072
	ds_read_b128 v[178:181], v203
	ds_read_b128 v[182:185], v203 offset:1024
	ds_read_b128 v[204:207], v203 offset:2048
	ds_read_b128 v[208:211], v203 offset:3072
	s_add_u32 s58, s58, 0x80000
	s_addc_u32 s59, s59, 0
	s_mov_b32 m0, s67
	v_lshl_add_u64 v[248:249], s[58:59], 0, v[150:151]
	ds_read_b128 v[212:215], v161 offset:32768
	ds_read_b128 v[216:219], v161 offset:33792
	ds_read_b128 v[220:223], v161 offset:34816
	ds_read_b128 v[224:227], v161 offset:35840
	ds_read_b128 v[228:231], v161 offset:36864
	ds_read_b128 v[232:235], v161 offset:37888
	ds_read_b128 v[236:239], v161 offset:38912
	ds_read_b128 v[240:243], v161 offset:39936
	global_load_lds_dwordx4 v[248:249], off
	v_lshl_add_u64 v[248:249], s[58:59], 0, v[146:147]
	s_mov_b32 m0, s4
	s_nop 0
	global_load_lds_dwordx4 v[248:249], off
	s_waitcnt vmcnt(8)
	s_waitcnt lgkmcnt(0)
	s_barrier
	s_setprio 1
	s_waitcnt lgkmcnt(0)
	v_mfma_f32_16x16x32_bf16 v[126:129], v[162:165], v[212:215], v[126:129]
	v_mfma_f32_16x16x32_bf16 v[122:125], v[170:173], v[212:215], v[122:125]
	v_mfma_f32_16x16x32_bf16 v[110:113], v[162:165], v[220:223], v[110:113]
	v_mfma_f32_16x16x32_bf16 v[106:109], v[170:173], v[220:223], v[106:109]
	v_mfma_f32_16x16x32_bf16 v[94:97], v[162:165], v[228:231], v[94:97]
	v_mfma_f32_16x16x32_bf16 v[90:93], v[170:173], v[228:231], v[90:93]
	v_mfma_f32_16x16x32_bf16 v[78:81], v[162:165], v[236:239], v[78:81]
	v_mfma_f32_16x16x32_bf16 v[74:77], v[170:173], v[236:239], v[74:77]
	v_mfma_f32_16x16x32_bf16 v[126:129], v[166:169], v[216:219], v[126:129]
	v_mfma_f32_16x16x32_bf16 v[122:125], v[174:177], v[216:219], v[122:125]
	v_mfma_f32_16x16x32_bf16 v[110:113], v[166:169], v[224:227], v[110:113]
	v_mfma_f32_16x16x32_bf16 v[106:109], v[174:177], v[224:227], v[106:109]
	v_mfma_f32_16x16x32_bf16 v[94:97], v[166:169], v[232:235], v[94:97]
	v_mfma_f32_16x16x32_bf16 v[90:93], v[174:177], v[232:235], v[90:93]
	v_mfma_f32_16x16x32_bf16 v[78:81], v[166:169], v[240:243], v[78:81]
	v_mfma_f32_16x16x32_bf16 v[74:77], v[174:177], v[240:243], v[74:77]
	s_setprio 0
	s_setprio 1
	v_mfma_f32_16x16x32_bf16 v[118:121], v[178:181], v[212:215], v[118:121]
	v_mfma_f32_16x16x32_bf16 v[114:117], v[204:207], v[212:215], v[114:117]
	v_mfma_f32_16x16x32_bf16 v[102:105], v[178:181], v[220:223], v[102:105]
	v_mfma_f32_16x16x32_bf16 v[98:101], v[204:207], v[220:223], v[98:101]
	v_mfma_f32_16x16x32_bf16 v[86:89], v[178:181], v[228:231], v[86:89]
	v_mfma_f32_16x16x32_bf16 v[82:85], v[204:207], v[228:231], v[82:85]
	v_mfma_f32_16x16x32_bf16 v[70:73], v[178:181], v[236:239], v[70:73]
	v_mfma_f32_16x16x32_bf16 v[66:69], v[204:207], v[236:239], v[66:69]
	v_mfma_f32_16x16x32_bf16 v[118:121], v[182:185], v[216:219], v[118:121]
	v_mfma_f32_16x16x32_bf16 v[114:117], v[208:211], v[216:219], v[114:117]
	v_mfma_f32_16x16x32_bf16 v[102:105], v[182:185], v[224:227], v[102:105]
	v_mfma_f32_16x16x32_bf16 v[98:101], v[208:211], v[224:227], v[98:101]
	v_mfma_f32_16x16x32_bf16 v[86:89], v[182:185], v[232:235], v[86:89]
	v_mfma_f32_16x16x32_bf16 v[82:85], v[208:211], v[232:235], v[82:85]
	v_mfma_f32_16x16x32_bf16 v[70:73], v[182:185], v[240:243], v[70:73]
	v_mfma_f32_16x16x32_bf16 v[66:69], v[208:211], v[240:243], v[66:69]
	s_setprio 0
	s_barrier
; #define PG8_STAGE(bufoff, gbase, voff) do { _Pragma("unroll") for (int _i = 0; _i < 2; ++_i) \
;         __builtin_amdgcn_global_load_lds((const unsigned*)((const char*)(gbase) + (voff)[_i]), (PG8_LAS unsigned*)(lds + (bufoff) + ldsw + _i * 8192), 16, 0, 0); } while (0)
; #define PG8_LDA(dst, b, h) do { _Pragma("unroll") for (int m = 0; m < 4; ++m) _Pragma("unroll") for (int k = 0; k < 2; ++k) dst[m][k] = *(const PG8_LAS bf16x8*)(lds + PG8_SA(b, h) + aoff + m * 2048 + k * 1024); } while (0)
; #define PG8_LDB(dst, b, h) do { _Pragma("unroll") for (int n = 0; n < 2; ++n) _Pragma("unroll") for (int k = 0; k < 2; ++k) dst[n][k] = *(const PG8_LAS bf16x8*)(lds + PG8_SB(b, h) + boff + n * 2048 + k * 1024); } while (0)
; #define PG8_WAIT_V(n) asm volatile("s_waitcnt vmcnt(" #n ")" ::: "memory")
; #define PG8_WAIT_L(n) asm volatile("s_waitcnt lgkmcnt(" #n ")" ::: "memory")
; #define PG8_BAR __builtin_amdgcn_s_barrier()
; #define PG8_SCHED __builtin_amdgcn_sched_barrier(0)
;     __device__ __forceinline__ void operator()(const f32x4 (&acc)[2][2][4][2], const Unit& u, int wr, int wc, int fr, int fq) const {
;     ...
;             for (int m = 0; m < 4; ++m) { const size_t row = (size_t)(row0 + ai * HALF + m * 16);
;                 const f32x4* sp = (const f32x4*)(SS + row * 32) + 2 * fq; float s;
;                 { const f32x4 t0 = sp[0], t1 = sp[1]; s = ((t0[0] + t0[1]) + (t0[2] + t0[3])) + ((t1[0] + t1[1]) + (t1[2] + t1[3])); }
;                 s += __shfl_xor(s, 16); s += __shfl_xor(s, 32);
;                 const float rstd = 1.0f / sqrtf(s * (1.0f / DM) + NORM_EPS);
; template <class Epi, class Sched, bool ALIGN_EPI = false, bool SP2 = false>
; __device__ __forceinline__ void gemm_phase(PG8_LAS unsigned char* lds, const Gemm g, const Sched& S, const Epi& E) {
;     ...
;             PG8_LDB(B0, 1, 0); PG8_LDB(B1, 1, 1); PG8_SCHED; PG8_LDA(At, 1, 0); PG8_STAGE(PG8_SA(0, 1), a2 + hstep, voffA);
;             PG8_WAIT_V(8); PG8_WAIT_L(0); PG8_BAR; PG8_MMA(0, 0, At, B0); PG8_MMA(0, 1, At, B1); PG8_BAR; PG8_SCHED;
;             PG8_LDA(At, 1, 1); PG8_STAGE(PG8_SB(1, 0), b3, voffB); PG8_STAGE(PG8_SB(1, 1), b3 + hstep, voffB); PG8_STAGE(PG8_SA(1, 0), a3, voffA);
;             PG8_WAIT_V(8); PG8_WAIT_L(0); PG8_BAR; PG8_MMA(1, 0, At, B0); PG8_MMA(1, 1, At, B1); PG8_BAR; PG8_SCHED;
	s_add_i32 s47, s47, s54
	v_lshl_add_u64 v[158:159], v[158:159], 0, s[68:69]
	s_mov_b32 m0, s47
	ds_read_b128 v[212:215], v161 offset:49152
	ds_read_b128 v[216:219], v161 offset:50176
	ds_read_b128 v[220:223], v161 offset:51200
	ds_read_b128 v[224:227], v161 offset:52224
	ds_read_b128 v[228:231], v161 offset:53248
	ds_read_b128 v[232:235], v161 offset:54272
	ds_read_b128 v[236:239], v161 offset:55296
	ds_read_b128 v[240:243], v161 offset:56320
	global_load_lds_dwordx4 v[158:159], off
	s_add_i32 m0, s47, 0x2000
	s_add_u32 s18, s18, 0x80080
	v_lshl_add_u64 v[158:159], v[186:187], 0, s[68:69]
	s_addc_u32 s19, s19, 0
	s_add_i32 s47, s76, s54
	global_load_lds_dwordx4 v[158:159], off
	v_lshl_add_u64 v[158:159], s[18:19], 0, v[148:149]
	s_mov_b32 m0, s47
	s_nop 0
	global_load_lds_dwordx4 v[158:159], off
	v_lshl_add_u64 v[158:159], s[18:19], 0, v[144:145]
	s_add_i32 m0, s47, 0x2000
	s_nop 0
	global_load_lds_dwordx4 v[158:159], off
	v_lshl_add_u64 v[158:159], v[244:245], 0, s[68:69]
	s_mov_b32 m0, s5
	s_nop 0
	global_load_lds_dwordx4 v[158:159], off
	v_lshl_add_u64 v[158:159], v[246:247], 0, s[68:69]
	s_mov_b32 m0, s57
	s_nop 0
	global_load_lds_dwordx4 v[158:159], off
	s_waitcnt vmcnt(8)
	s_waitcnt lgkmcnt(0)
	s_barrier
	s_setprio 1
	s_waitcnt lgkmcnt(0)
	v_mfma_f32_16x16x32_bf16 v[62:65], v[162:165], v[212:215], v[62:65]
	v_mfma_f32_16x16x32_bf16 v[58:61], v[170:173], v[212:215], v[58:61]
	v_mfma_f32_16x16x32_bf16 v[46:49], v[162:165], v[220:223], v[46:49]
	v_mfma_f32_16x16x32_bf16 v[42:45], v[170:173], v[220:223], v[42:45]
	v_mfma_f32_16x16x32_bf16 v[30:33], v[162:165], v[228:231], v[30:33]
	v_mfma_f32_16x16x32_bf16 v[26:29], v[170:173], v[228:231], v[26:29]
	v_mfma_f32_16x16x32_bf16 v[14:17], v[162:165], v[236:239], v[14:17]
	v_mfma_f32_16x16x32_bf16 v[10:13], v[170:173], v[236:239], v[10:13]
	v_mfma_f32_16x16x32_bf16 v[62:65], v[166:169], v[216:219], v[62:65]
	v_mfma_f32_16x16x32_bf16 v[58:61], v[174:177], v[216:219], v[58:61]
	v_mfma_f32_16x16x32_bf16 v[46:49], v[166:169], v[224:227], v[46:49]
	v_mfma_f32_16x16x32_bf16 v[42:45], v[174:177], v[224:227], v[42:45]
	v_mfma_f32_16x16x32_bf16 v[30:33], v[166:169], v[232:235], v[30:33]
	v_mfma_f32_16x16x32_bf16 v[26:29], v[174:177], v[232:235], v[26:29]
	v_mfma_f32_16x16x32_bf16 v[14:17], v[166:169], v[240:243], v[14:17]
	v_mfma_f32_16x16x32_bf16 v[10:13], v[174:177], v[240:243], v[10:13]
	s_setprio 0
	s_setprio 1
	v_mfma_f32_16x16x32_bf16 v[54:57], v[178:181], v[212:215], v[54:57]
	v_mfma_f32_16x16x32_bf16 v[50:53], v[204:207], v[212:215], v[50:53]
	v_mfma_f32_16x16x32_bf16 v[38:41], v[178:181], v[220:223], v[38:41]
	v_mfma_f32_16x16x32_bf16 v[34:37], v[204:207], v[220:223], v[34:37]
	v_mfma_f32_16x16x32_bf16 v[22:25], v[178:181], v[228:231], v[22:25]
	v_mfma_f32_16x16x32_bf16 v[18:21], v[204:207], v[228:231], v[18:21]
	v_mfma_f32_16x16x32_bf16 v[6:9], v[178:181], v[236:239], v[6:9]
	v_mfma_f32_16x16x32_bf16 v[2:5], v[204:207], v[236:239], v[2:5]
	v_mfma_f32_16x16x32_bf16 v[54:57], v[182:185], v[216:219], v[54:57]
	v_mfma_f32_16x16x32_bf16 v[50:53], v[208:211], v[216:219], v[50:53]
	v_mfma_f32_16x16x32_bf16 v[38:41], v[182:185], v[224:227], v[38:41]
	v_mfma_f32_16x16x32_bf16 v[34:37], v[208:211], v[224:227], v[34:37]
	v_mfma_f32_16x16x32_bf16 v[22:25], v[182:185], v[232:235], v[22:25]
	v_mfma_f32_16x16x32_bf16 v[18:21], v[208:211], v[232:235], v[18:21]
	v_mfma_f32_16x16x32_bf16 v[6:9], v[182:185], v[240:243], v[6:9]
	v_mfma_f32_16x16x32_bf16 v[2:5], v[208:211], v[240:243], v[2:5]
	s_setprio 0
	s_barrier
	s_add_i32 s46, s46, 2
	s_add_u32 s0, s0, 0x100
	s_addc_u32 s1, s1, 0
	s_add_u32 s78, s78, 0x100
	s_addc_u32 s79, s79, 0
	s_cmp_gt_u32 s46, 29
	s_cbranch_scc0 .LBB0_76
	s_and_b64 vcc, exec, s[42:43]
	s_cbranch_vccz .LBB0_79
	s_barrier
.LBB0_79:
	v_xor_b32_e32 v159, 16, v192
	v_add_u32_e32 v163, 64, v193
	v_cmp_lt_i32_e32 vcc, v159, v163
	v_lshl_add_u32 v158, s34, 8, v1
	v_lshl_or_b32 v172, s28, 8, v160
	v_cndmask_b32_e32 v159, v192, v159, vcc
	v_lshlrev_b32_e32 v162, 2, v159
	v_xor_b32_e32 v159, 32, v192
	v_cmp_lt_i32_e32 vcc, v159, v163
	v_ashrrev_i32_e32 v173, 31, v172
	s_nop 0
	v_cndmask_b32_e32 v159, v192, v159, vcc
	v_lshlrev_b32_e32 v163, 2, v159
	v_ashrrev_i32_e32 v159, 31, v158
	v_lshlrev_b64 v[164:165], 7, v[158:159]
	v_lshl_add_u64 v[168:169], v[152:153], 0, v[164:165]
	global_load_dwordx4 v[164:167], v[168:169], off
	s_nop 0
	global_load_dwordx4 v[168:171], v[168:169], off offset:16
	s_waitcnt vmcnt(0)
	v_mov_b32_e32 v174, v164
	v_mov_b32_e32 v175, v168
	v_mov_b32_e32 v168, v165
	v_pk_add_f32 v[164:165], v[174:175], v[168:169]
	v_mov_b32_e32 v168, v166
	v_mov_b32_e32 v169, v170
	v_mov_b32_e32 v170, v167
	v_pk_add_f32 v[166:167], v[168:169], v[170:171]
	s_nop 0
	v_pk_add_f32 v[164:165], v[164:165], v[166:167]
	s_nop 0
	v_add_f32_e32 v164, v164, v165
	ds_bpermute_b32 v165, v162, v164
	s_waitcnt lgkmcnt(0)
	v_add_f32_e32 v164, v164, v165
	ds_bpermute_b32 v165, v163, v164
	s_waitcnt lgkmcnt(0)
; __device__ __forceinline__ unsigned cvt_pk_bf16(float lo, float hi) { const f32x2c_t v = {lo, hi}; const bf16x2c_t b = __builtin_convertvector(v, bf16x2c_t); return __builtin_bit_cast(unsigned, b); }
;     __device__ __forceinline__ void operator()(const f32x4 (&acc)[2][2][4][2], const Unit& u, int wr, int wc, int fr, int fq) const {
;     ...
;             for (int m = 0; m < 4; ++m) { const size_t row = (size_t)(row0 + ai * HALF + m * 16);
;                 const f32x4* sp = (const f32x4*)(SS + row * 32) + 2 * fq; float s;
;                 { const f32x4 t0 = sp[0], t1 = sp[1]; s = ((t0[0] + t0[1]) + (t0[2] + t0[3])) + ((t1[0] + t1[1]) + (t1[2] + t1[3])); }
;                 s += __shfl_xor(s, 16); s += __shfl_xor(s, 32);
;                 const float rstd = 1.0f / sqrtf(s * (1.0f / DM) + NORM_EPS);
; #pragma unroll
;                 for (int bj = 0; bj < 2; ++bj) { f32x4 v0 = acc[ai][bj][m][0] * rstd, v1 = acc[ai][bj][m][1] * rstd;
; #pragma unroll
;                     for (int e = 0; e < 4; ++e) { const float a = fmaxf(v0[e], 0.f), b = fmaxf(v1[e], 0.f); v0[e] = a * a; v1[e] = b * b; }
;                     u32x4 w; w.x = cvt_pk_bf16(v0[0], v0[1]); w.y = cvt_pk_bf16(v0[2], v0[3]); w.z = cvt_pk_bf16(v1[0], v1[1]); w.w = cvt_pk_bf16(v1[2], v1[3]);
;                     *(u32x4*)(H + row * DFF + col0 + bj * HALF) = w; } }
	v_add_f32_e32 v164, v164, v165
	v_fmamk_f32 v164, v164, 0x3a000000, v190
	v_cmp_gt_f32_e32 vcc, s72, v164
	v_mul_f32_e32 v165, 0x4f800000, v164
	s_nop 0
	v_cndmask_b32_e32 v164, v164, v165, vcc
	v_sqrt_f32_e32 v165, v164
	s_nop 0
	v_add_u32_e32 v166, -1, v165
	v_fma_f32 v167, -v166, v165, v164
	v_cmp_ge_f32_e64 s[0:1], 0, v167
	v_add_u32_e32 v167, 1, v165
	s_nop 0
	v_cndmask_b32_e64 v166, v165, v166, s[0:1]
	v_fma_f32 v165, -v167, v165, v164
	v_cmp_lt_f32_e64 s[0:1], 0, v165
	s_nop 1
	v_cndmask_b32_e64 v165, v166, v167, s[0:1]
	v_mul_f32_e32 v166, 0x37800000, v165
	v_cndmask_b32_e32 v165, v165, v166, vcc
	v_cmp_class_f32_e32 vcc, v164, v191
	s_nop 1
	v_cndmask_b32_e32 v164, v165, v164, vcc
	v_div_scale_f32 v165, s[0:1], v164, v164, 1.0
	v_rcp_f32_e32 v166, v165
	s_nop 0
	v_fma_f32 v167, -v165, v166, 1.0
	v_fmac_f32_e32 v166, v167, v166
	v_div_scale_f32 v167, vcc, 1.0, v164, 1.0
	v_mul_f32_e32 v168, v167, v166
	v_fma_f32 v169, -v165, v168, v167
	v_fmac_f32_e32 v168, v169, v166
	v_fma_f32 v165, -v165, v168, v167
	v_div_fmas_f32 v165, v165, v166, v168
	v_div_fixup_f32 v164, v165, v164, 1.0
	v_pk_mul_f32 v[128:129], v[128:129], v[164:165] op_sel_hi:[1,0]
	v_pk_mul_f32 v[126:127], v[126:127], v[164:165] op_sel_hi:[1,0]
	v_pk_mul_f32 v[122:123], v[122:123], v[164:165] op_sel_hi:[1,0]
	v_pk_mul_f32 v[124:125], v[124:125], v[164:165] op_sel_hi:[1,0]
	v_max_f32_e32 v126, 0, v126
	v_max_f32_e32 v122, 0, v122
	v_max_f32_e32 v127, 0, v127
	v_max_f32_e32 v123, 0, v123
	v_max_f32_e32 v128, 0, v128
	v_max_f32_e32 v129, 0, v129
	v_lshlrev_b64 v[166:167], 14, v[158:159]
	v_pk_mul_f32 v[126:127], v[126:127], v[126:127]
	v_pk_mul_f32 v[122:123], v[122:123], v[122:123]
	v_max_f32_e32 v124, 0, v124
	v_max_f32_e32 v125, 0, v125
	v_pk_mul_f32 v[128:129], v[128:129], v[128:129]
	v_pk_mul_f32 v[168:169], v[124:125], v[124:125]
	v_cvt_pk_bf16_f32 v124, v126, v127
	v_cvt_pk_bf16_f32 v125, v128, v129
	v_cvt_pk_bf16_f32 v126, v122, v123
	v_lshl_add_u64 v[128:129], s[92:93], 0, v[166:167]
	v_lshlrev_b64 v[122:123], 1, v[172:173]
	v_pk_mul_f32 v[114:115], v[114:115], v[164:165] op_sel_hi:[1,0]
	v_cvt_pk_bf16_f32 v127, v168, v169
	v_lshl_add_u64 v[128:129], v[128:129], 0, v[122:123]
	v_pk_mul_f32 v[120:121], v[120:121], v[164:165] op_sel_hi:[1,0]
	v_pk_mul_f32 v[118:119], v[118:119], v[164:165] op_sel_hi:[1,0]
	v_pk_mul_f32 v[116:117], v[116:117], v[164:165] op_sel_hi:[1,0]
	v_max_f32_e32 v114, 0, v114
	v_max_f32_e32 v115, 0, v115
	global_store_dwordx4 v[128:129], v[124:127], off
	v_max_f32_e32 v118, 0, v118
	v_max_f32_e32 v119, 0, v119
	v_pk_mul_f32 v[124:125], v[114:115], v[114:115]
	v_max_f32_e32 v114, 0, v120
	v_max_f32_e32 v116, 0, v116
	v_max_f32_e32 v115, 0, v121
	v_max_f32_e32 v117, 0, v117
	v_pk_mul_f32 v[118:119], v[118:119], v[118:119]
	v_pk_mul_f32 v[120:121], v[114:115], v[114:115]
	v_pk_mul_f32 v[126:127], v[116:117], v[116:117]
	v_cvt_pk_bf16_f32 v114, v118, v119
	v_cvt_pk_bf16_f32 v115, v120, v121
	v_cvt_pk_bf16_f32 v116, v124, v125
	v_cvt_pk_bf16_f32 v117, v126, v127
	global_store_dwordx4 v[128:129], v[114:117], off offset:256
	s_nop 1
	v_or_b32_e32 v114, 16, v158
	v_ashrrev_i32_e32 v115, 31, v114
	v_lshlrev_b64 v[116:117], 7, v[114:115]
	v_lshl_add_u64 v[120:121], v[152:153], 0, v[116:117]
	global_load_dwordx4 v[116:119], v[120:121], off
	global_load_dwordx4 v[124:127], v[120:121], off offset:16
	v_lshlrev_b64 v[114:115], 14, v[114:115]
	s_waitcnt vmcnt(1)
	v_mov_b32_e32 v120, v116
	s_waitcnt vmcnt(0)
	v_mov_b32_e32 v121, v124
	v_mov_b32_e32 v124, v117
	v_pk_add_f32 v[116:117], v[120:121], v[124:125]
	v_mov_b32_e32 v120, v118
	v_mov_b32_e32 v121, v126
	v_mov_b32_e32 v126, v119
	v_pk_add_f32 v[118:119], v[120:121], v[126:127]
	s_nop 0
	v_pk_add_f32 v[116:117], v[116:117], v[118:119]
	s_nop 0
	v_add_f32_e32 v116, v116, v117
	ds_bpermute_b32 v117, v162, v116
	s_waitcnt lgkmcnt(0)
	v_add_f32_e32 v116, v116, v117
	ds_bpermute_b32 v117, v163, v116
	s_waitcnt lgkmcnt(0)
	v_add_f32_e32 v116, v116, v117
	v_fmamk_f32 v116, v116, 0x3a000000, v190
	v_cmp_gt_f32_e32 vcc, s72, v116
	v_mul_f32_e32 v117, 0x4f800000, v116
	s_nop 0
	v_cndmask_b32_e32 v116, v116, v117, vcc
	v_sqrt_f32_e32 v117, v116
	s_nop 0
	v_add_u32_e32 v118, -1, v117
	v_fma_f32 v119, -v118, v117, v116
	v_cmp_ge_f32_e64 s[0:1], 0, v119
	v_add_u32_e32 v119, 1, v117
	s_nop 0
	v_cndmask_b32_e64 v118, v117, v118, s[0:1]
	v_fma_f32 v117, -v119, v117, v116
	v_cmp_lt_f32_e64 s[0:1], 0, v117
	s_nop 1
	v_cndmask_b32_e64 v117, v118, v119, s[0:1]
	v_mul_f32_e32 v118, 0x37800000, v117
	v_cndmask_b32_e32 v117, v117, v118, vcc
	v_cmp_class_f32_e32 vcc, v116, v191
	s_nop 1
	v_cndmask_b32_e32 v116, v117, v116, vcc
	v_div_scale_f32 v117, s[0:1], v116, v116, 1.0
	v_rcp_f32_e32 v118, v117
	s_nop 0
	v_fma_f32 v119, -v117, v118, 1.0
	v_fmac_f32_e32 v118, v119, v118
	v_div_scale_f32 v119, vcc, 1.0, v116, 1.0
	v_mul_f32_e32 v120, v119, v118
	v_fma_f32 v121, -v117, v120, v119
	v_fmac_f32_e32 v120, v121, v118
	v_fma_f32 v117, -v117, v120, v119
	v_div_fmas_f32 v117, v117, v118, v120
	v_div_fixup_f32 v116, v117, v116, 1.0
	v_pk_mul_f32 v[110:111], v[110:111], v[116:117] op_sel_hi:[1,0]
	v_pk_mul_f32 v[106:107], v[106:107], v[116:117] op_sel_hi:[1,0]
	v_pk_mul_f32 v[112:113], v[112:113], v[116:117] op_sel_hi:[1,0]
	v_pk_mul_f32 v[108:109], v[108:109], v[116:117] op_sel_hi:[1,0]
	v_max_f32_e32 v110, 0, v110
	v_max_f32_e32 v106, 0, v106
	v_max_f32_e32 v111, 0, v111
	v_max_f32_e32 v107, 0, v107
	v_pk_mul_f32 v[110:111], v[110:111], v[110:111]
	v_pk_mul_f32 v[118:119], v[106:107], v[106:107]
	v_max_f32_e32 v106, 0, v112
	v_max_f32_e32 v108, 0, v108
	v_max_f32_e32 v107, 0, v113
	v_max_f32_e32 v109, 0, v109
; __device__ __forceinline__ unsigned cvt_pk_bf16(float lo, float hi) { const f32x2c_t v = {lo, hi}; const bf16x2c_t b = __builtin_convertvector(v, bf16x2c_t); return __builtin_bit_cast(unsigned, b); }
;     __device__ __forceinline__ void operator()(const f32x4 (&acc)[2][2][4][2], const Unit& u, int wr, int wc, int fr, int fq) const {
;     ...
;             for (int m = 0; m < 4; ++m) { const size_t row = (size_t)(row0 + ai * HALF + m * 16);
;                 const f32x4* sp = (const f32x4*)(SS + row * 32) + 2 * fq; float s;
;                 { const f32x4 t0 = sp[0], t1 = sp[1]; s = ((t0[0] + t0[1]) + (t0[2] + t0[3])) + ((t1[0] + t1[1]) + (t1[2] + t1[3])); }
;                 s += __shfl_xor(s, 16); s += __shfl_xor(s, 32);
;                 const float rstd = 1.0f / sqrtf(s * (1.0f / DM) + NORM_EPS);
; #pragma unroll
;                 for (int bj = 0; bj < 2; ++bj) { f32x4 v0 = acc[ai][bj][m][0] * rstd, v1 = acc[ai][bj][m][1] * rstd;
; #pragma unroll
;                     for (int e = 0; e < 4; ++e) { const float a = fmaxf(v0[e], 0.f), b = fmaxf(v1[e], 0.f); v0[e] = a * a; v1[e] = b * b; }
;                     u32x4 w; w.x = cvt_pk_bf16(v0[0], v0[1]); w.y = cvt_pk_bf16(v0[2], v0[3]); w.z = cvt_pk_bf16(v1[0], v1[1]); w.w = cvt_pk_bf16(v1[2], v1[3]);
;                     *(u32x4*)(H + row * DFF + col0 + bj * HALF) = w; } }
	v_pk_mul_f32 v[112:113], v[106:107], v[106:107]
	v_pk_mul_f32 v[120:121], v[108:109], v[108:109]
	v_cvt_pk_bf16_f32 v106, v110, v111
	v_lshl_add_u64 v[110:111], s[92:93], 0, v[114:115]
	v_pk_mul_f32 v[98:99], v[98:99], v[116:117] op_sel_hi:[1,0]
	v_cvt_pk_bf16_f32 v107, v112, v113
	v_cvt_pk_bf16_f32 v108, v118, v119
	v_cvt_pk_bf16_f32 v109, v120, v121
	v_lshl_add_u64 v[110:111], v[110:111], 0, v[122:123]
	v_pk_mul_f32 v[104:105], v[104:105], v[116:117] op_sel_hi:[1,0]
	v_pk_mul_f32 v[102:103], v[102:103], v[116:117] op_sel_hi:[1,0]
	v_pk_mul_f32 v[100:101], v[100:101], v[116:117] op_sel_hi:[1,0]
	v_max_f32_e32 v98, 0, v98
	v_max_f32_e32 v99, 0, v99
	global_store_dwordx4 v[110:111], v[106:109], off
	v_max_f32_e32 v102, 0, v102
	v_max_f32_e32 v103, 0, v103
	v_pk_mul_f32 v[106:107], v[98:99], v[98:99]
	v_max_f32_e32 v98, 0, v104
	v_max_f32_e32 v100, 0, v100
	v_max_f32_e32 v99, 0, v105
	v_max_f32_e32 v101, 0, v101
	v_pk_mul_f32 v[102:103], v[102:103], v[102:103]
	v_pk_mul_f32 v[104:105], v[98:99], v[98:99]
	v_pk_mul_f32 v[108:109], v[100:101], v[100:101]
	v_cvt_pk_bf16_f32 v98, v102, v103
	v_cvt_pk_bf16_f32 v99, v104, v105
	v_cvt_pk_bf16_f32 v100, v106, v107
	v_cvt_pk_bf16_f32 v101, v108, v109
	global_store_dwordx4 v[110:111], v[98:101], off offset:256
	s_nop 1
	v_or_b32_e32 v98, 32, v158
	v_ashrrev_i32_e32 v99, 31, v98
	v_lshlrev_b64 v[100:101], 7, v[98:99]
	v_lshl_add_u64 v[100:101], v[152:153], 0, v[100:101]
	global_load_dwordx4 v[102:105], v[100:101], off
	global_load_dwordx4 v[106:109], v[100:101], off offset:16
	v_lshlrev_b64 v[98:99], 14, v[98:99]
	s_waitcnt vmcnt(1)
	v_mov_b32_e32 v100, v102
	s_waitcnt vmcnt(0)
	v_mov_b32_e32 v101, v106
	v_mov_b32_e32 v106, v103
	v_mov_b32_e32 v102, v104
	v_mov_b32_e32 v103, v108
	v_mov_b32_e32 v108, v105
	v_pk_add_f32 v[100:101], v[100:101], v[106:107]
	v_pk_add_f32 v[102:103], v[102:103], v[108:109]
	s_nop 0
	v_pk_add_f32 v[100:101], v[100:101], v[102:103]
	s_nop 0
	v_add_f32_e32 v100, v100, v101
	ds_bpermute_b32 v101, v162, v100
	s_waitcnt lgkmcnt(0)
	v_add_f32_e32 v100, v100, v101
	ds_bpermute_b32 v101, v163, v100
	s_waitcnt lgkmcnt(0)
	v_add_f32_e32 v100, v100, v101
	v_fmamk_f32 v100, v100, 0x3a000000, v190
	v_cmp_gt_f32_e32 vcc, s72, v100
	v_mul_f32_e32 v101, 0x4f800000, v100
	s_nop 0
	v_cndmask_b32_e32 v100, v100, v101, vcc
	v_sqrt_f32_e32 v101, v100
	s_nop 0
	v_add_u32_e32 v102, -1, v101
	v_fma_f32 v103, -v102, v101, v100
	v_cmp_ge_f32_e64 s[0:1], 0, v103
	v_add_u32_e32 v103, 1, v101
	s_nop 0
	v_cndmask_b32_e64 v102, v101, v102, s[0:1]
	v_fma_f32 v101, -v103, v101, v100
	v_cmp_lt_f32_e64 s[0:1], 0, v101
	s_nop 1
	v_cndmask_b32_e64 v101, v102, v103, s[0:1]
	v_mul_f32_e32 v102, 0x37800000, v101
	v_cndmask_b32_e32 v101, v101, v102, vcc
	v_cmp_class_f32_e32 vcc, v100, v191
	s_nop 1
	v_cndmask_b32_e32 v100, v101, v100, vcc
	v_div_scale_f32 v101, s[0:1], v100, v100, 1.0
	v_rcp_f32_e32 v102, v101
	s_nop 0
	v_fma_f32 v103, -v101, v102, 1.0
	v_fmac_f32_e32 v102, v103, v102
	v_div_scale_f32 v103, vcc, 1.0, v100, 1.0
	v_mul_f32_e32 v104, v103, v102
	v_fma_f32 v105, -v101, v104, v103
	v_fmac_f32_e32 v104, v105, v102
	v_fma_f32 v101, -v101, v104, v103
	v_div_fmas_f32 v101, v101, v102, v104
	v_div_fixup_f32 v100, v101, v100, 1.0
	v_pk_mul_f32 v[94:95], v[94:95], v[100:101] op_sel_hi:[1,0]
	v_pk_mul_f32 v[90:91], v[90:91], v[100:101] op_sel_hi:[1,0]
	v_pk_mul_f32 v[96:97], v[96:97], v[100:101] op_sel_hi:[1,0]
	v_pk_mul_f32 v[92:93], v[92:93], v[100:101] op_sel_hi:[1,0]
	v_max_f32_e32 v94, 0, v94
	v_max_f32_e32 v90, 0, v90
	v_max_f32_e32 v95, 0, v95
	v_max_f32_e32 v91, 0, v91
	v_pk_mul_f32 v[94:95], v[94:95], v[94:95]
	v_pk_mul_f32 v[102:103], v[90:91], v[90:91]
	v_max_f32_e32 v90, 0, v96
	v_max_f32_e32 v92, 0, v92
	v_max_f32_e32 v91, 0, v97
	v_max_f32_e32 v93, 0, v93
	v_pk_mul_f32 v[96:97], v[90:91], v[90:91]
	v_pk_mul_f32 v[104:105], v[92:93], v[92:93]
	v_cvt_pk_bf16_f32 v90, v94, v95
	v_lshl_add_u64 v[94:95], s[92:93], 0, v[98:99]
	v_pk_mul_f32 v[82:83], v[82:83], v[100:101] op_sel_hi:[1,0]
	v_cvt_pk_bf16_f32 v91, v96, v97
	v_cvt_pk_bf16_f32 v92, v102, v103
	v_cvt_pk_bf16_f32 v93, v104, v105
	v_lshl_add_u64 v[94:95], v[94:95], 0, v[122:123]
	v_pk_mul_f32 v[88:89], v[88:89], v[100:101] op_sel_hi:[1,0]
	v_pk_mul_f32 v[86:87], v[86:87], v[100:101] op_sel_hi:[1,0]
	v_pk_mul_f32 v[84:85], v[84:85], v[100:101] op_sel_hi:[1,0]
	v_max_f32_e32 v82, 0, v82
	v_max_f32_e32 v83, 0, v83
	global_store_dwordx4 v[94:95], v[90:93], off
	v_max_f32_e32 v86, 0, v86
	v_max_f32_e32 v87, 0, v87
	v_pk_mul_f32 v[90:91], v[82:83], v[82:83]
	v_max_f32_e32 v82, 0, v88
	v_max_f32_e32 v84, 0, v84
	v_max_f32_e32 v83, 0, v89
	v_max_f32_e32 v85, 0, v85
	v_pk_mul_f32 v[86:87], v[86:87], v[86:87]
	v_pk_mul_f32 v[88:89], v[82:83], v[82:83]
	v_pk_mul_f32 v[92:93], v[84:85], v[84:85]
	v_cvt_pk_bf16_f32 v82, v86, v87
	v_cvt_pk_bf16_f32 v83, v88, v89
	v_cvt_pk_bf16_f32 v84, v90, v91
	v_cvt_pk_bf16_f32 v85, v92, v93
	global_store_dwordx4 v[94:95], v[82:85], off offset:256
	s_nop 1
	v_or_b32_e32 v82, 48, v158
	v_ashrrev_i32_e32 v83, 31, v82
	v_lshlrev_b64 v[84:85], 7, v[82:83]
	v_lshl_add_u64 v[84:85], v[152:153], 0, v[84:85]
	global_load_dwordx4 v[86:89], v[84:85], off
	global_load_dwordx4 v[90:93], v[84:85], off offset:16
	v_lshlrev_b64 v[82:83], 14, v[82:83]
	s_waitcnt vmcnt(1)
	v_mov_b32_e32 v84, v86
	s_waitcnt vmcnt(0)
	v_mov_b32_e32 v85, v90
	v_mov_b32_e32 v90, v87
	v_mov_b32_e32 v86, v88
	v_mov_b32_e32 v87, v92
	v_mov_b32_e32 v92, v89
	v_pk_add_f32 v[84:85], v[84:85], v[90:91]
	v_pk_add_f32 v[86:87], v[86:87], v[92:93]
	s_nop 0
	v_pk_add_f32 v[84:85], v[84:85], v[86:87]
	s_nop 0
	v_add_f32_e32 v84, v84, v85
	ds_bpermute_b32 v85, v162, v84
	s_waitcnt lgkmcnt(0)
; __device__ __forceinline__ unsigned cvt_pk_bf16(float lo, float hi) { const f32x2c_t v = {lo, hi}; const bf16x2c_t b = __builtin_convertvector(v, bf16x2c_t); return __builtin_bit_cast(unsigned, b); }
;     __device__ __forceinline__ void operator()(const f32x4 (&acc)[2][2][4][2], const Unit& u, int wr, int wc, int fr, int fq) const {
;     ...
;             for (int m = 0; m < 4; ++m) { const size_t row = (size_t)(row0 + ai * HALF + m * 16);
;                 const f32x4* sp = (const f32x4*)(SS + row * 32) + 2 * fq; float s;
;                 { const f32x4 t0 = sp[0], t1 = sp[1]; s = ((t0[0] + t0[1]) + (t0[2] + t0[3])) + ((t1[0] + t1[1]) + (t1[2] + t1[3])); }
;                 s += __shfl_xor(s, 16); s += __shfl_xor(s, 32);
;                 const float rstd = 1.0f / sqrtf(s * (1.0f / DM) + NORM_EPS);
; #pragma unroll
;                 for (int bj = 0; bj < 2; ++bj) { f32x4 v0 = acc[ai][bj][m][0] * rstd, v1 = acc[ai][bj][m][1] * rstd;
; #pragma unroll
;                     for (int e = 0; e < 4; ++e) { const float a = fmaxf(v0[e], 0.f), b = fmaxf(v1[e], 0.f); v0[e] = a * a; v1[e] = b * b; }
;                     u32x4 w; w.x = cvt_pk_bf16(v0[0], v0[1]); w.y = cvt_pk_bf16(v0[2], v0[3]); w.z = cvt_pk_bf16(v1[0], v1[1]); w.w = cvt_pk_bf16(v1[2], v1[3]);
;                     *(u32x4*)(H + row * DFF + col0 + bj * HALF) = w; } }
	v_add_f32_e32 v84, v84, v85
	ds_bpermute_b32 v85, v163, v84
	s_waitcnt lgkmcnt(0)
	v_add_f32_e32 v84, v84, v85
	v_fmamk_f32 v84, v84, 0x3a000000, v190
	v_cmp_gt_f32_e32 vcc, s72, v84
	v_mul_f32_e32 v85, 0x4f800000, v84
	s_nop 0
	v_cndmask_b32_e32 v84, v84, v85, vcc
	v_sqrt_f32_e32 v85, v84
	s_nop 0
	v_add_u32_e32 v86, -1, v85
	v_fma_f32 v87, -v86, v85, v84
	v_cmp_ge_f32_e64 s[0:1], 0, v87
	v_add_u32_e32 v87, 1, v85
	s_nop 0
	v_cndmask_b32_e64 v86, v85, v86, s[0:1]
	v_fma_f32 v85, -v87, v85, v84
	v_cmp_lt_f32_e64 s[0:1], 0, v85
	s_nop 1
	v_cndmask_b32_e64 v85, v86, v87, s[0:1]
	v_mul_f32_e32 v86, 0x37800000, v85
	v_cndmask_b32_e32 v85, v85, v86, vcc
	v_cmp_class_f32_e32 vcc, v84, v191
	s_nop 1
	v_cndmask_b32_e32 v84, v85, v84, vcc
	v_div_scale_f32 v85, s[0:1], v84, v84, 1.0
	v_rcp_f32_e32 v86, v85
	s_nop 0
	v_fma_f32 v87, -v85, v86, 1.0
	v_fmac_f32_e32 v86, v87, v86
	v_div_scale_f32 v87, vcc, 1.0, v84, 1.0
	v_mul_f32_e32 v88, v87, v86
	v_fma_f32 v89, -v85, v88, v87
	v_fmac_f32_e32 v88, v89, v86
	v_fma_f32 v85, -v85, v88, v87
	v_div_fmas_f32 v85, v85, v86, v88
	v_div_fixup_f32 v84, v85, v84, 1.0
	v_pk_mul_f32 v[78:79], v[78:79], v[84:85] op_sel_hi:[1,0]
	v_pk_mul_f32 v[74:75], v[74:75], v[84:85] op_sel_hi:[1,0]
	v_pk_mul_f32 v[80:81], v[80:81], v[84:85] op_sel_hi:[1,0]
	v_pk_mul_f32 v[76:77], v[76:77], v[84:85] op_sel_hi:[1,0]
	v_max_f32_e32 v78, 0, v78
	v_max_f32_e32 v74, 0, v74
	v_max_f32_e32 v79, 0, v79
	v_max_f32_e32 v75, 0, v75
	v_pk_mul_f32 v[78:79], v[78:79], v[78:79]
	v_pk_mul_f32 v[86:87], v[74:75], v[74:75]
	v_max_f32_e32 v74, 0, v80
	v_max_f32_e32 v76, 0, v76
	v_max_f32_e32 v75, 0, v81
	v_max_f32_e32 v77, 0, v77
	v_pk_mul_f32 v[80:81], v[74:75], v[74:75]
	v_pk_mul_f32 v[88:89], v[76:77], v[76:77]
	v_cvt_pk_bf16_f32 v74, v78, v79
	v_lshl_add_u64 v[78:79], s[92:93], 0, v[82:83]
	v_pk_mul_f32 v[66:67], v[66:67], v[84:85] op_sel_hi:[1,0]
	v_cvt_pk_bf16_f32 v75, v80, v81
	v_cvt_pk_bf16_f32 v76, v86, v87
	v_cvt_pk_bf16_f32 v77, v88, v89
	v_lshl_add_u64 v[78:79], v[78:79], 0, v[122:123]
	v_pk_mul_f32 v[72:73], v[72:73], v[84:85] op_sel_hi:[1,0]
	v_pk_mul_f32 v[70:71], v[70:71], v[84:85] op_sel_hi:[1,0]
	v_pk_mul_f32 v[68:69], v[68:69], v[84:85] op_sel_hi:[1,0]
	v_max_f32_e32 v66, 0, v66
	v_max_f32_e32 v67, 0, v67
	global_store_dwordx4 v[78:79], v[74:77], off
	v_max_f32_e32 v70, 0, v70
	v_max_f32_e32 v71, 0, v71
	v_pk_mul_f32 v[74:75], v[66:67], v[66:67]
	v_max_f32_e32 v66, 0, v72
	v_max_f32_e32 v68, 0, v68
	v_max_f32_e32 v67, 0, v73
	v_max_f32_e32 v69, 0, v69
	v_pk_mul_f32 v[70:71], v[70:71], v[70:71]
	v_pk_mul_f32 v[72:73], v[66:67], v[66:67]
	v_pk_mul_f32 v[76:77], v[68:69], v[68:69]
	v_cvt_pk_bf16_f32 v66, v70, v71
	v_cvt_pk_bf16_f32 v67, v72, v73
	v_cvt_pk_bf16_f32 v68, v74, v75
	v_cvt_pk_bf16_f32 v69, v76, v77
	global_store_dwordx4 v[78:79], v[66:69], off offset:256
	s_nop 1
	v_add_u32_e32 v66, 0x80, v158
	v_ashrrev_i32_e32 v67, 31, v66
	v_lshlrev_b64 v[68:69], 7, v[66:67]
	v_lshl_add_u64 v[68:69], v[152:153], 0, v[68:69]
	global_load_dwordx4 v[70:73], v[68:69], off
	global_load_dwordx4 v[74:77], v[68:69], off offset:16
	v_lshlrev_b64 v[66:67], 14, v[66:67]
	s_waitcnt vmcnt(1)
	v_mov_b32_e32 v68, v70
	s_waitcnt vmcnt(0)
	v_mov_b32_e32 v69, v74
	v_mov_b32_e32 v74, v71
	v_mov_b32_e32 v70, v72
	v_mov_b32_e32 v71, v76
	v_mov_b32_e32 v76, v73
	v_pk_add_f32 v[68:69], v[68:69], v[74:75]
	v_pk_add_f32 v[70:71], v[70:71], v[76:77]
	s_nop 0
	v_pk_add_f32 v[68:69], v[68:69], v[70:71]
	s_nop 0
	v_add_f32_e32 v68, v68, v69
	ds_bpermute_b32 v69, v162, v68
	s_waitcnt lgkmcnt(0)
	v_add_f32_e32 v68, v68, v69
	ds_bpermute_b32 v69, v163, v68
	s_waitcnt lgkmcnt(0)
	v_add_f32_e32 v68, v68, v69
	v_fmamk_f32 v68, v68, 0x3a000000, v190
	v_cmp_gt_f32_e32 vcc, s72, v68
	v_mul_f32_e32 v69, 0x4f800000, v68
	s_nop 0
	v_cndmask_b32_e32 v68, v68, v69, vcc
	v_sqrt_f32_e32 v69, v68
	s_nop 0
	v_add_u32_e32 v70, -1, v69
	v_fma_f32 v71, -v70, v69, v68
	v_cmp_ge_f32_e64 s[0:1], 0, v71
	v_add_u32_e32 v71, 1, v69
	s_nop 0
	v_cndmask_b32_e64 v70, v69, v70, s[0:1]
	v_fma_f32 v69, -v71, v69, v68
	v_cmp_lt_f32_e64 s[0:1], 0, v69
	s_nop 1
	v_cndmask_b32_e64 v69, v70, v71, s[0:1]
	v_mul_f32_e32 v70, 0x37800000, v69
	v_cndmask_b32_e32 v69, v69, v70, vcc
	v_cmp_class_f32_e32 vcc, v68, v191
	s_nop 1
	v_cndmask_b32_e32 v68, v69, v68, vcc
	v_div_scale_f32 v69, s[0:1], v68, v68, 1.0
	v_rcp_f32_e32 v70, v69
	s_nop 0
	v_fma_f32 v71, -v69, v70, 1.0
	v_fmac_f32_e32 v70, v71, v70
	v_div_scale_f32 v71, vcc, 1.0, v68, 1.0
	v_mul_f32_e32 v72, v71, v70
	v_fma_f32 v73, -v69, v72, v71
	v_fmac_f32_e32 v72, v73, v70
	v_fma_f32 v69, -v69, v72, v71
	v_div_fmas_f32 v69, v69, v70, v72
	v_div_fixup_f32 v68, v69, v68, 1.0
	v_pk_mul_f32 v[62:63], v[62:63], v[68:69] op_sel_hi:[1,0]
	v_pk_mul_f32 v[58:59], v[58:59], v[68:69] op_sel_hi:[1,0]
	v_pk_mul_f32 v[64:65], v[64:65], v[68:69] op_sel_hi:[1,0]
	v_pk_mul_f32 v[60:61], v[60:61], v[68:69] op_sel_hi:[1,0]
	v_max_f32_e32 v62, 0, v62
	v_max_f32_e32 v58, 0, v58
	v_max_f32_e32 v63, 0, v63
	v_max_f32_e32 v59, 0, v59
	v_pk_mul_f32 v[62:63], v[62:63], v[62:63]
	v_pk_mul_f32 v[70:71], v[58:59], v[58:59]
	v_max_f32_e32 v58, 0, v64
	v_max_f32_e32 v60, 0, v60
	v_max_f32_e32 v59, 0, v65
	v_max_f32_e32 v61, 0, v61
	v_pk_mul_f32 v[64:65], v[58:59], v[58:59]
	v_pk_mul_f32 v[72:73], v[60:61], v[60:61]
	v_cvt_pk_bf16_f32 v58, v62, v63
	v_lshl_add_u64 v[62:63], s[92:93], 0, v[66:67]
	v_pk_mul_f32 v[50:51], v[50:51], v[68:69] op_sel_hi:[1,0]
	v_cvt_pk_bf16_f32 v59, v64, v65
	v_cvt_pk_bf16_f32 v60, v70, v71
	v_cvt_pk_bf16_f32 v61, v72, v73
	v_lshl_add_u64 v[62:63], v[62:63], 0, v[122:123]
	v_pk_mul_f32 v[56:57], v[56:57], v[68:69] op_sel_hi:[1,0]
	v_pk_mul_f32 v[54:55], v[54:55], v[68:69] op_sel_hi:[1,0]
	v_pk_mul_f32 v[52:53], v[52:53], v[68:69] op_sel_hi:[1,0]
	v_max_f32_e32 v50, 0, v50
	v_max_f32_e32 v51, 0, v51
	global_store_dwordx4 v[62:63], v[58:61], off
	v_max_f32_e32 v54, 0, v54
	v_max_f32_e32 v55, 0, v55
	v_pk_mul_f32 v[58:59], v[50:51], v[50:51]
	v_max_f32_e32 v50, 0, v56
	v_max_f32_e32 v52, 0, v52
	v_max_f32_e32 v51, 0, v57
	v_max_f32_e32 v53, 0, v53
	v_pk_mul_f32 v[54:55], v[54:55], v[54:55]
	v_pk_mul_f32 v[56:57], v[50:51], v[50:51]
	v_pk_mul_f32 v[60:61], v[52:53], v[52:53]
	v_cvt_pk_bf16_f32 v50, v54, v55
	v_cvt_pk_bf16_f32 v51, v56, v57
	v_cvt_pk_bf16_f32 v52, v58, v59
	v_cvt_pk_bf16_f32 v53, v60, v61
	global_store_dwordx4 v[62:63], v[50:53], off offset:256
	s_nop 1
	v_add_u32_e32 v50, 0x90, v158
	v_ashrrev_i32_e32 v51, 31, v50
	v_lshlrev_b64 v[52:53], 7, v[50:51]
	v_lshl_add_u64 v[52:53], v[152:153], 0, v[52:53]
	global_load_dwordx4 v[54:57], v[52:53], off
	global_load_dwordx4 v[58:61], v[52:53], off offset:16
	v_lshlrev_b64 v[50:51], 14, v[50:51]
	s_waitcnt vmcnt(1)
; __device__ __forceinline__ unsigned cvt_pk_bf16(float lo, float hi) { const f32x2c_t v = {lo, hi}; const bf16x2c_t b = __builtin_convertvector(v, bf16x2c_t); return __builtin_bit_cast(unsigned, b); }
;     __device__ __forceinline__ void operator()(const f32x4 (&acc)[2][2][4][2], const Unit& u, int wr, int wc, int fr, int fq) const {
;     ...
;             for (int m = 0; m < 4; ++m) { const size_t row = (size_t)(row0 + ai * HALF + m * 16);
;                 const f32x4* sp = (const f32x4*)(SS + row * 32) + 2 * fq; float s;
;                 { const f32x4 t0 = sp[0], t1 = sp[1]; s = ((t0[0] + t0[1]) + (t0[2] + t0[3])) + ((t1[0] + t1[1]) + (t1[2] + t1[3])); }
;                 s += __shfl_xor(s, 16); s += __shfl_xor(s, 32);
;                 const float rstd = 1.0f / sqrtf(s * (1.0f / DM) + NORM_EPS);
; #pragma unroll
;                 for (int bj = 0; bj < 2; ++bj) { f32x4 v0 = acc[ai][bj][m][0] * rstd, v1 = acc[ai][bj][m][1] * rstd;
; #pragma unroll
;                     for (int e = 0; e < 4; ++e) { const float a = fmaxf(v0[e], 0.f), b = fmaxf(v1[e], 0.f); v0[e] = a * a; v1[e] = b * b; }
;                     u32x4 w; w.x = cvt_pk_bf16(v0[0], v0[1]); w.y = cvt_pk_bf16(v0[2], v0[3]); w.z = cvt_pk_bf16(v1[0], v1[1]); w.w = cvt_pk_bf16(v1[2], v1[3]);
;                     *(u32x4*)(H + row * DFF + col0 + bj * HALF) = w; } }
	v_mov_b32_e32 v52, v54
	s_waitcnt vmcnt(0)
	v_mov_b32_e32 v53, v58
	v_mov_b32_e32 v58, v55
	v_mov_b32_e32 v54, v56
	v_mov_b32_e32 v55, v60
	v_mov_b32_e32 v60, v57
	v_pk_add_f32 v[52:53], v[52:53], v[58:59]
	v_pk_add_f32 v[54:55], v[54:55], v[60:61]
	s_nop 0
	v_pk_add_f32 v[52:53], v[52:53], v[54:55]
	s_nop 0
	v_add_f32_e32 v52, v52, v53
	ds_bpermute_b32 v53, v162, v52
	s_waitcnt lgkmcnt(0)
	v_add_f32_e32 v52, v52, v53
	ds_bpermute_b32 v53, v163, v52
	s_waitcnt lgkmcnt(0)
	v_add_f32_e32 v52, v52, v53
	v_fmamk_f32 v52, v52, 0x3a000000, v190
	v_cmp_gt_f32_e32 vcc, s72, v52
	v_mul_f32_e32 v53, 0x4f800000, v52
	s_nop 0
	v_cndmask_b32_e32 v52, v52, v53, vcc
	v_sqrt_f32_e32 v53, v52
	s_nop 0
	v_add_u32_e32 v54, -1, v53
	v_fma_f32 v55, -v54, v53, v52
	v_cmp_ge_f32_e64 s[0:1], 0, v55
	v_add_u32_e32 v55, 1, v53
	s_nop 0
	v_cndmask_b32_e64 v54, v53, v54, s[0:1]
	v_fma_f32 v53, -v55, v53, v52
	v_cmp_lt_f32_e64 s[0:1], 0, v53
	s_nop 1
	v_cndmask_b32_e64 v53, v54, v55, s[0:1]
	v_mul_f32_e32 v54, 0x37800000, v53
	v_cndmask_b32_e32 v53, v53, v54, vcc
	v_cmp_class_f32_e32 vcc, v52, v191
	s_nop 1
	v_cndmask_b32_e32 v52, v53, v52, vcc
	v_div_scale_f32 v53, s[0:1], v52, v52, 1.0
	v_rcp_f32_e32 v54, v53
	s_nop 0
	v_fma_f32 v55, -v53, v54, 1.0
	v_fmac_f32_e32 v54, v55, v54
	v_div_scale_f32 v55, vcc, 1.0, v52, 1.0
	v_mul_f32_e32 v56, v55, v54
	v_fma_f32 v57, -v53, v56, v55
	v_fmac_f32_e32 v56, v57, v54
	v_fma_f32 v53, -v53, v56, v55
	v_div_fmas_f32 v53, v53, v54, v56
	v_div_fixup_f32 v52, v53, v52, 1.0
	v_pk_mul_f32 v[46:47], v[46:47], v[52:53] op_sel_hi:[1,0]
	v_pk_mul_f32 v[42:43], v[42:43], v[52:53] op_sel_hi:[1,0]
	v_pk_mul_f32 v[48:49], v[48:49], v[52:53] op_sel_hi:[1,0]
	v_pk_mul_f32 v[44:45], v[44:45], v[52:53] op_sel_hi:[1,0]
	v_max_f32_e32 v46, 0, v46
	v_max_f32_e32 v42, 0, v42
	v_max_f32_e32 v47, 0, v47
	v_max_f32_e32 v43, 0, v43
	v_pk_mul_f32 v[46:47], v[46:47], v[46:47]
	v_pk_mul_f32 v[54:55], v[42:43], v[42:43]
	v_max_f32_e32 v42, 0, v48
	v_max_f32_e32 v44, 0, v44
	v_max_f32_e32 v43, 0, v49
	v_max_f32_e32 v45, 0, v45
	v_pk_mul_f32 v[48:49], v[42:43], v[42:43]
	v_pk_mul_f32 v[56:57], v[44:45], v[44:45]
	v_cvt_pk_bf16_f32 v42, v46, v47
	v_lshl_add_u64 v[46:47], s[92:93], 0, v[50:51]
	v_pk_mul_f32 v[34:35], v[34:35], v[52:53] op_sel_hi:[1,0]
	v_cvt_pk_bf16_f32 v43, v48, v49
	v_cvt_pk_bf16_f32 v44, v54, v55
	v_cvt_pk_bf16_f32 v45, v56, v57
	v_lshl_add_u64 v[46:47], v[46:47], 0, v[122:123]
	v_pk_mul_f32 v[40:41], v[40:41], v[52:53] op_sel_hi:[1,0]
	v_pk_mul_f32 v[38:39], v[38:39], v[52:53] op_sel_hi:[1,0]
	v_pk_mul_f32 v[36:37], v[36:37], v[52:53] op_sel_hi:[1,0]
	v_max_f32_e32 v34, 0, v34
	v_max_f32_e32 v35, 0, v35
	global_store_dwordx4 v[46:47], v[42:45], off
	v_max_f32_e32 v38, 0, v38
	v_max_f32_e32 v39, 0, v39
	v_pk_mul_f32 v[42:43], v[34:35], v[34:35]
	v_max_f32_e32 v34, 0, v40
	v_max_f32_e32 v36, 0, v36
	v_max_f32_e32 v35, 0, v41
	v_max_f32_e32 v37, 0, v37
	v_pk_mul_f32 v[38:39], v[38:39], v[38:39]
	v_pk_mul_f32 v[40:41], v[34:35], v[34:35]
	v_pk_mul_f32 v[44:45], v[36:37], v[36:37]
	v_cvt_pk_bf16_f32 v34, v38, v39
	v_cvt_pk_bf16_f32 v35, v40, v41
	v_cvt_pk_bf16_f32 v36, v42, v43
	v_cvt_pk_bf16_f32 v37, v44, v45
	global_store_dwordx4 v[46:47], v[34:37], off offset:256
	s_nop 1
	v_add_u32_e32 v34, 0xa0, v158
	v_ashrrev_i32_e32 v35, 31, v34
	v_lshlrev_b64 v[36:37], 7, v[34:35]
	v_lshl_add_u64 v[36:37], v[152:153], 0, v[36:37]
	global_load_dwordx4 v[38:41], v[36:37], off
	global_load_dwordx4 v[42:45], v[36:37], off offset:16
	v_lshlrev_b64 v[34:35], 14, v[34:35]
	s_waitcnt vmcnt(1)
	v_mov_b32_e32 v36, v38
	s_waitcnt vmcnt(0)
	v_mov_b32_e32 v37, v42
	v_mov_b32_e32 v42, v39
	v_mov_b32_e32 v38, v40
	v_mov_b32_e32 v39, v44
	v_mov_b32_e32 v44, v41
	v_pk_add_f32 v[36:37], v[36:37], v[42:43]
	v_pk_add_f32 v[38:39], v[38:39], v[44:45]
	s_nop 0
	v_pk_add_f32 v[36:37], v[36:37], v[38:39]
	s_nop 0
	v_add_f32_e32 v36, v36, v37
	ds_bpermute_b32 v37, v162, v36
	s_waitcnt lgkmcnt(0)
	v_add_f32_e32 v36, v36, v37
	ds_bpermute_b32 v37, v163, v36
	s_waitcnt lgkmcnt(0)
; __device__ __forceinline__ unsigned cvt_pk_bf16(float lo, float hi) { const f32x2c_t v = {lo, hi}; const bf16x2c_t b = __builtin_convertvector(v, bf16x2c_t); return __builtin_bit_cast(unsigned, b); }
;     __device__ __forceinline__ void operator()(const f32x4 (&acc)[2][2][4][2], const Unit& u, int wr, int wc, int fr, int fq) const {
;     ...
;             for (int m = 0; m < 4; ++m) { const size_t row = (size_t)(row0 + ai * HALF + m * 16);
;                 const f32x4* sp = (const f32x4*)(SS + row * 32) + 2 * fq; float s;
;                 { const f32x4 t0 = sp[0], t1 = sp[1]; s = ((t0[0] + t0[1]) + (t0[2] + t0[3])) + ((t1[0] + t1[1]) + (t1[2] + t1[3])); }
;                 s += __shfl_xor(s, 16); s += __shfl_xor(s, 32);
;                 const float rstd = 1.0f / sqrtf(s * (1.0f / DM) + NORM_EPS);
; #pragma unroll
;                 for (int bj = 0; bj < 2; ++bj) { f32x4 v0 = acc[ai][bj][m][0] * rstd, v1 = acc[ai][bj][m][1] * rstd;
; #pragma unroll
;                     for (int e = 0; e < 4; ++e) { const float a = fmaxf(v0[e], 0.f), b = fmaxf(v1[e], 0.f); v0[e] = a * a; v1[e] = b * b; }
;                     u32x4 w; w.x = cvt_pk_bf16(v0[0], v0[1]); w.y = cvt_pk_bf16(v0[2], v0[3]); w.z = cvt_pk_bf16(v1[0], v1[1]); w.w = cvt_pk_bf16(v1[2], v1[3]);
;                     *(u32x4*)(H + row * DFF + col0 + bj * HALF) = w; } }
	v_add_f32_e32 v36, v36, v37
	v_fmamk_f32 v36, v36, 0x3a000000, v190
	v_cmp_gt_f32_e32 vcc, s72, v36
	v_mul_f32_e32 v37, 0x4f800000, v36
	s_nop 0
	v_cndmask_b32_e32 v36, v36, v37, vcc
	v_sqrt_f32_e32 v37, v36
	s_nop 0
	v_add_u32_e32 v38, -1, v37
	v_fma_f32 v39, -v38, v37, v36
	v_cmp_ge_f32_e64 s[0:1], 0, v39
	v_add_u32_e32 v39, 1, v37
	s_nop 0
	v_cndmask_b32_e64 v38, v37, v38, s[0:1]
	v_fma_f32 v37, -v39, v37, v36
	v_cmp_lt_f32_e64 s[0:1], 0, v37
	s_nop 1
	v_cndmask_b32_e64 v37, v38, v39, s[0:1]
	v_mul_f32_e32 v38, 0x37800000, v37
	v_cndmask_b32_e32 v37, v37, v38, vcc
	v_cmp_class_f32_e32 vcc, v36, v191
	s_nop 1
	v_cndmask_b32_e32 v36, v37, v36, vcc
	v_div_scale_f32 v37, s[0:1], v36, v36, 1.0
	v_rcp_f32_e32 v38, v37
	s_nop 0
	v_fma_f32 v39, -v37, v38, 1.0
	v_fmac_f32_e32 v38, v39, v38
	v_div_scale_f32 v39, vcc, 1.0, v36, 1.0
	v_mul_f32_e32 v40, v39, v38
	v_fma_f32 v41, -v37, v40, v39
	v_fmac_f32_e32 v40, v41, v38
	v_fma_f32 v37, -v37, v40, v39
	v_div_fmas_f32 v37, v37, v38, v40
	v_div_fixup_f32 v36, v37, v36, 1.0
	v_pk_mul_f32 v[30:31], v[30:31], v[36:37] op_sel_hi:[1,0]
	v_pk_mul_f32 v[26:27], v[26:27], v[36:37] op_sel_hi:[1,0]
	v_pk_mul_f32 v[32:33], v[32:33], v[36:37] op_sel_hi:[1,0]
	v_pk_mul_f32 v[28:29], v[28:29], v[36:37] op_sel_hi:[1,0]
	v_max_f32_e32 v30, 0, v30
	v_max_f32_e32 v26, 0, v26
	v_max_f32_e32 v31, 0, v31
	v_max_f32_e32 v27, 0, v27
	v_pk_mul_f32 v[30:31], v[30:31], v[30:31]
	v_pk_mul_f32 v[38:39], v[26:27], v[26:27]
	v_max_f32_e32 v26, 0, v32
	v_max_f32_e32 v28, 0, v28
	v_max_f32_e32 v27, 0, v33
	v_max_f32_e32 v29, 0, v29
	v_pk_mul_f32 v[32:33], v[26:27], v[26:27]
	v_pk_mul_f32 v[40:41], v[28:29], v[28:29]
	v_cvt_pk_bf16_f32 v26, v30, v31
	v_lshl_add_u64 v[30:31], s[92:93], 0, v[34:35]
	v_pk_mul_f32 v[18:19], v[18:19], v[36:37] op_sel_hi:[1,0]
	v_cvt_pk_bf16_f32 v27, v32, v33
	v_cvt_pk_bf16_f32 v28, v38, v39
	v_cvt_pk_bf16_f32 v29, v40, v41
	v_lshl_add_u64 v[30:31], v[30:31], 0, v[122:123]
	v_pk_mul_f32 v[24:25], v[24:25], v[36:37] op_sel_hi:[1,0]
	v_pk_mul_f32 v[22:23], v[22:23], v[36:37] op_sel_hi:[1,0]
	v_pk_mul_f32 v[20:21], v[20:21], v[36:37] op_sel_hi:[1,0]
	v_max_f32_e32 v18, 0, v18
	v_max_f32_e32 v19, 0, v19
	global_store_dwordx4 v[30:31], v[26:29], off
	v_max_f32_e32 v22, 0, v22
	v_max_f32_e32 v23, 0, v23
	v_pk_mul_f32 v[26:27], v[18:19], v[18:19]
	v_max_f32_e32 v18, 0, v24
	v_max_f32_e32 v20, 0, v20
	v_max_f32_e32 v19, 0, v25
	v_max_f32_e32 v21, 0, v21
	v_pk_mul_f32 v[22:23], v[22:23], v[22:23]
	v_pk_mul_f32 v[24:25], v[18:19], v[18:19]
	v_pk_mul_f32 v[28:29], v[20:21], v[20:21]
	v_cvt_pk_bf16_f32 v18, v22, v23
	v_cvt_pk_bf16_f32 v19, v24, v25
	v_cvt_pk_bf16_f32 v20, v26, v27
	v_cvt_pk_bf16_f32 v21, v28, v29
	global_store_dwordx4 v[30:31], v[18:21], off offset:256
	s_nop 1
	v_add_u32_e32 v18, 0xb0, v158
	v_ashrrev_i32_e32 v19, 31, v18
	v_lshlrev_b64 v[20:21], 7, v[18:19]
	v_lshl_add_u64 v[20:21], v[152:153], 0, v[20:21]
	global_load_dwordx4 v[22:25], v[20:21], off
	global_load_dwordx4 v[26:29], v[20:21], off offset:16
	v_lshlrev_b64 v[18:19], 14, v[18:19]
	s_waitcnt vmcnt(1)
	v_mov_b32_e32 v20, v22
	s_waitcnt vmcnt(0)
	v_mov_b32_e32 v21, v26
	v_mov_b32_e32 v26, v23
	v_mov_b32_e32 v22, v24
	v_mov_b32_e32 v23, v28
	v_mov_b32_e32 v28, v25
	v_pk_add_f32 v[20:21], v[20:21], v[26:27]
	v_pk_add_f32 v[22:23], v[22:23], v[28:29]
	s_nop 0
	v_pk_add_f32 v[20:21], v[20:21], v[22:23]
	s_nop 0
	v_add_f32_e32 v20, v20, v21
	ds_bpermute_b32 v21, v162, v20
	s_waitcnt lgkmcnt(0)
	v_add_f32_e32 v20, v20, v21
	ds_bpermute_b32 v21, v163, v20
	s_waitcnt lgkmcnt(0)
	v_add_f32_e32 v20, v20, v21
	v_fmamk_f32 v20, v20, 0x3a000000, v190
	v_cmp_gt_f32_e32 vcc, s72, v20
	v_mul_f32_e32 v21, 0x4f800000, v20
	s_nop 0
	v_cndmask_b32_e32 v20, v20, v21, vcc
	v_sqrt_f32_e32 v21, v20
	s_nop 0
	v_add_u32_e32 v22, -1, v21
	v_fma_f32 v23, -v22, v21, v20
	v_cmp_ge_f32_e64 s[0:1], 0, v23
	v_add_u32_e32 v23, 1, v21
	s_nop 0
	v_cndmask_b32_e64 v22, v21, v22, s[0:1]
	v_fma_f32 v21, -v23, v21, v20
	v_cmp_lt_f32_e64 s[0:1], 0, v21
	s_nop 1
	v_cndmask_b32_e64 v21, v22, v23, s[0:1]
	v_mul_f32_e32 v22, 0x37800000, v21
	v_cndmask_b32_e32 v21, v21, v22, vcc
	v_cmp_class_f32_e32 vcc, v20, v191
	s_nop 1
	v_cndmask_b32_e32 v20, v21, v20, vcc
	v_div_scale_f32 v21, s[0:1], v20, v20, 1.0
	v_rcp_f32_e32 v22, v21
	s_mov_b64 s[0:1], -1
	v_fma_f32 v23, -v21, v22, 1.0
	v_fmac_f32_e32 v22, v23, v22
	v_div_scale_f32 v23, vcc, 1.0, v20, 1.0
	v_mul_f32_e32 v24, v23, v22
	v_fma_f32 v25, -v21, v24, v23
	v_fmac_f32_e32 v24, v25, v22
	v_fma_f32 v21, -v21, v24, v23
	v_div_fmas_f32 v21, v21, v22, v24
	v_div_fixup_f32 v20, v21, v20, 1.0
	v_pk_mul_f32 v[14:15], v[14:15], v[20:21] op_sel_hi:[1,0]
	v_pk_mul_f32 v[10:11], v[10:11], v[20:21] op_sel_hi:[1,0]
	v_pk_mul_f32 v[16:17], v[16:17], v[20:21] op_sel_hi:[1,0]
	v_pk_mul_f32 v[12:13], v[12:13], v[20:21] op_sel_hi:[1,0]
	v_max_f32_e32 v14, 0, v14
	v_max_f32_e32 v10, 0, v10
	v_max_f32_e32 v15, 0, v15
	v_max_f32_e32 v11, 0, v11
	v_pk_mul_f32 v[14:15], v[14:15], v[14:15]
	v_pk_mul_f32 v[22:23], v[10:11], v[10:11]
	v_max_f32_e32 v10, 0, v16
	v_max_f32_e32 v12, 0, v12
	v_max_f32_e32 v11, 0, v17
	v_max_f32_e32 v13, 0, v13
	v_pk_mul_f32 v[16:17], v[10:11], v[10:11]
	v_pk_mul_f32 v[24:25], v[12:13], v[12:13]
	v_cvt_pk_bf16_f32 v10, v14, v15
	v_lshl_add_u64 v[14:15], s[92:93], 0, v[18:19]
	v_pk_mul_f32 v[2:3], v[2:3], v[20:21] op_sel_hi:[1,0]
	v_cvt_pk_bf16_f32 v11, v16, v17
	v_cvt_pk_bf16_f32 v12, v22, v23
	v_cvt_pk_bf16_f32 v13, v24, v25
	v_lshl_add_u64 v[14:15], v[14:15], 0, v[122:123]
	v_pk_mul_f32 v[8:9], v[8:9], v[20:21] op_sel_hi:[1,0]
	v_pk_mul_f32 v[6:7], v[6:7], v[20:21] op_sel_hi:[1,0]
	v_pk_mul_f32 v[4:5], v[4:5], v[20:21] op_sel_hi:[1,0]
	v_max_f32_e32 v2, 0, v2
	v_max_f32_e32 v3, 0, v3
	global_store_dwordx4 v[14:15], v[10:13], off
	v_max_f32_e32 v6, 0, v6
	v_max_f32_e32 v7, 0, v7
	v_pk_mul_f32 v[10:11], v[2:3], v[2:3]
	v_max_f32_e32 v2, 0, v8
	v_max_f32_e32 v4, 0, v4
	v_max_f32_e32 v3, 0, v9
	v_max_f32_e32 v5, 0, v5
	v_pk_mul_f32 v[6:7], v[6:7], v[6:7]
	v_pk_mul_f32 v[8:9], v[2:3], v[2:3]
	v_pk_mul_f32 v[12:13], v[4:5], v[4:5]
	v_cvt_pk_bf16_f32 v2, v6, v7
	v_cvt_pk_bf16_f32 v3, v8, v9
	v_cvt_pk_bf16_f32 v4, v10, v11
	v_cvt_pk_bf16_f32 v5, v12, v13
	s_andn2_b64 vcc, exec, s[40:41]
	global_store_dwordx4 v[14:15], v[2:5], off offset:256
	s_cbranch_vccnz .LBB0_68
	s_andn2_b64 vcc, exec, s[12:13]
	s_cbranch_vccnz .LBB0_67
	s_barrier
	s_branch .LBB0_67

; #define PG8_STAGE(bufoff, gbase, voff) do { _Pragma("unroll") for (int _i = 0; _i < 2; ++_i) \
;         __builtin_amdgcn_global_load_lds((const unsigned*)((const char*)(gbase) + (voff)[_i]), (PG8_LAS unsigned*)(lds + (bufoff) + ldsw + _i * 8192), 16, 0, 0); } while (0)
; #define PG8_LDA(dst, b, h) do { _Pragma("unroll") for (int m = 0; m < 4; ++m) _Pragma("unroll") for (int k = 0; k < 2; ++k) dst[m][k] = *(const PG8_LAS bf16x8*)(lds + PG8_SA(b, h) + aoff + m * 2048 + k * 1024); } while (0)
; #define PG8_LDB(dst, b, h) do { _Pragma("unroll") for (int n = 0; n < 2; ++n) _Pragma("unroll") for (int k = 0; k < 2; ++k) dst[n][k] = *(const PG8_LAS bf16x8*)(lds + PG8_SB(b, h) + boff + n * 2048 + k * 1024); } while (0)
; #define PG8_MMA(ai, bj, At, Bt) do { __builtin_amdgcn_s_setprio(1); _Pragma("unroll") for (int m = 0; m < 4; ++m) _Pragma("unroll") for (int n = 0; n < 2; ++n) _Pragma("unroll") for (int k = 0; k < 2; ++k) \
;         acc[ai][bj][m][n] = __builtin_amdgcn_mfma_f32_16x16x32_bf16(Bt[n][k], At[m][k], acc[ai][bj][m][n], 0, 0, 0); __builtin_amdgcn_s_setprio(0); } while (0)
; #define PG8_WAIT_V(n) asm volatile("s_waitcnt vmcnt(" #n ")" ::: "memory")
; #define PG8_WAIT_L(n) asm volatile("s_waitcnt lgkmcnt(" #n ")" ::: "memory")
; template <class Epi, class Sched, bool ALIGN_EPI = false, bool SP2 = false>
; __device__ __forceinline__ void gemm_phase(PG8_LAS unsigned char* lds, const Gemm g, const Sched& S, const Epi& E) {
;     ...
;             const bool last = (t == nt - 2);
;             const char* a1 = cA + (size_t)(t + 1) * kstep;
;             const char* a2 = last ? nA : cA + (size_t)(t + 2) * kstep; const char* b2 = last ? nB : cB + (size_t)(t + 2) * kstep;
;             const char* a3 = a2 + kstep; const char* b3 = b2 + kstep;
;             if (last && has_next) S.a_ready(nxt);
;             if constexpr (SP2) {
;             PG8_LDB(B0, 0, 0); PG8_LDB(B1, 0, 1); PG8_SCHED; PG8_LDA(At, 0, 0); PG8_STAGE(PG8_SA(1, 1), a1 + hstep, voffA);
;             PG8_WAIT_V(8); PG8_WAIT_L(0); PG8_BAR; PG8_MMA(0, 0, At, B0); PG8_MMA(0, 1, At, B1); PG8_BAR; PG8_SCHED;
;             PG8_LDA(At, 0, 1); PG8_STAGE(PG8_SB(0, 0), b2, voffB); PG8_STAGE(PG8_SB(0, 1), b2 + hstep, voffB); PG8_STAGE(PG8_SA(0, 0), a2, voffA);
;             PG8_WAIT_V(8); PG8_WAIT_L(0); PG8_BAR; PG8_MMA(1, 0, At, B0); PG8_MMA(1, 1, At, B1); PG8_BAR; PG8_SCHED;
.LBB0_98:
	s_add_u32 s40, vcc_lo, 0xfff80080
	s_addc_u32 s41, vcc_hi, -1
	s_add_i32 s47, 0, 0x10000
	s_cmp_eq_u32 s46, 28
	s_cselect_b32 s59, s97, s41
	s_cselect_b32 s58, s84, s40
	s_cselect_b32 s41, s85, s79
	s_cselect_b32 s40, s95, s78
	s_add_i32 s80, 0, 0x14000
	v_add_u32_e32 v170, s47, v143
	v_add_u32_e32 v186, s80, v143
	ds_read_b128 v[156:159], v170
	ds_read_b128 v[162:165], v170 offset:1024
	ds_read_b128 v[166:169], v170 offset:2048
	ds_read_b128 v[170:173], v170 offset:3072
	ds_read_b128 v[174:177], v186
	ds_read_b128 v[178:181], v186 offset:1024
	ds_read_b128 v[182:185], v186 offset:2048
	ds_read_b128 v[204:207], v186 offset:3072
	v_lshl_add_u64 v[186:187], vcc, 0, v[152:153]
	s_add_i32 m0, s5, 0xc000
	ds_read_b128 v[208:211], v161
	ds_read_b128 v[212:215], v161 offset:1024
	ds_read_b128 v[216:219], v161 offset:2048
	ds_read_b128 v[220:223], v161 offset:3072
	ds_read_b128 v[224:227], v161 offset:4096
	ds_read_b128 v[228:231], v161 offset:5120
	ds_read_b128 v[232:235], v161 offset:6144
	ds_read_b128 v[236:239], v161 offset:7168
	global_load_lds_dwordx4 v[186:187], off
	v_lshl_add_u64 v[186:187], vcc, 0, v[154:155]
	s_add_i32 m0, s5, 0xe000
	s_nop 0
	global_load_lds_dwordx4 v[186:187], off
	s_waitcnt vmcnt(8)
	s_waitcnt lgkmcnt(0)
	s_barrier
	s_setprio 1
	s_waitcnt lgkmcnt(0)
	v_mfma_f32_16x16x32_bf16 v[126:129], v[156:159], v[208:211], v[126:129]
	v_mfma_f32_16x16x32_bf16 v[122:125], v[166:169], v[208:211], v[122:125]
	v_mfma_f32_16x16x32_bf16 v[110:113], v[156:159], v[216:219], v[110:113]
	v_mfma_f32_16x16x32_bf16 v[106:109], v[166:169], v[216:219], v[106:109]
	v_mfma_f32_16x16x32_bf16 v[94:97], v[156:159], v[224:227], v[94:97]
	v_mfma_f32_16x16x32_bf16 v[90:93], v[166:169], v[224:227], v[90:93]
	v_mfma_f32_16x16x32_bf16 v[78:81], v[156:159], v[232:235], v[78:81]
	v_mfma_f32_16x16x32_bf16 v[74:77], v[166:169], v[232:235], v[74:77]
	v_mfma_f32_16x16x32_bf16 v[126:129], v[162:165], v[212:215], v[126:129]
	v_mfma_f32_16x16x32_bf16 v[122:125], v[170:173], v[212:215], v[122:125]
	v_mfma_f32_16x16x32_bf16 v[110:113], v[162:165], v[220:223], v[110:113]
	v_mfma_f32_16x16x32_bf16 v[106:109], v[170:173], v[220:223], v[106:109]
	v_mfma_f32_16x16x32_bf16 v[94:97], v[162:165], v[228:231], v[94:97]
	v_mfma_f32_16x16x32_bf16 v[90:93], v[170:173], v[228:231], v[90:93]
	v_mfma_f32_16x16x32_bf16 v[78:81], v[162:165], v[236:239], v[78:81]
	v_mfma_f32_16x16x32_bf16 v[74:77], v[170:173], v[236:239], v[74:77]
	s_setprio 0
	s_setprio 1
	v_mfma_f32_16x16x32_bf16 v[118:121], v[174:177], v[208:211], v[118:121]
	v_mfma_f32_16x16x32_bf16 v[114:117], v[182:185], v[208:211], v[114:117]
	v_mfma_f32_16x16x32_bf16 v[102:105], v[174:177], v[216:219], v[102:105]
	v_mfma_f32_16x16x32_bf16 v[98:101], v[182:185], v[216:219], v[98:101]
	v_mfma_f32_16x16x32_bf16 v[86:89], v[174:177], v[224:227], v[86:89]
	v_mfma_f32_16x16x32_bf16 v[82:85], v[182:185], v[224:227], v[82:85]
	v_mfma_f32_16x16x32_bf16 v[70:73], v[174:177], v[232:235], v[70:73]
	v_mfma_f32_16x16x32_bf16 v[66:69], v[182:185], v[232:235], v[66:69]
	v_mfma_f32_16x16x32_bf16 v[118:121], v[178:181], v[212:215], v[118:121]
	v_mfma_f32_16x16x32_bf16 v[114:117], v[204:207], v[212:215], v[114:117]
	v_mfma_f32_16x16x32_bf16 v[102:105], v[178:181], v[220:223], v[102:105]
	v_mfma_f32_16x16x32_bf16 v[98:101], v[204:207], v[220:223], v[98:101]
	v_mfma_f32_16x16x32_bf16 v[86:89], v[178:181], v[228:231], v[86:89]
	v_mfma_f32_16x16x32_bf16 v[82:85], v[204:207], v[228:231], v[82:85]
	v_mfma_f32_16x16x32_bf16 v[70:73], v[178:181], v[236:239], v[70:73]
	v_mfma_f32_16x16x32_bf16 v[66:69], v[204:207], v[236:239], v[66:69]
	s_setprio 0
	s_barrier
	s_add_i32 s47, s47, s4
	v_lshl_add_u64 v[186:187], s[40:41], 0, v[148:149]
	s_mov_b32 m0, s47
	ds_read_b128 v[208:211], v161 offset:16384
	ds_read_b128 v[212:215], v161 offset:17408
	ds_read_b128 v[216:219], v161 offset:18432
	ds_read_b128 v[220:223], v161 offset:19456
	ds_read_b128 v[224:227], v161 offset:20480
	ds_read_b128 v[228:231], v161 offset:21504
	ds_read_b128 v[232:235], v161 offset:22528
	ds_read_b128 v[236:239], v161 offset:23552
	global_load_lds_dwordx4 v[186:187], off
	s_add_i32 m0, s47, 0x2000
	s_add_u32 s76, s40, 0x80000
	v_lshl_add_u64 v[240:241], s[40:41], 0, v[144:145]
	s_addc_u32 s77, s41, 0
	s_add_i32 s47, s80, s4
	global_load_lds_dwordx4 v[240:241], off
	v_lshl_add_u64 v[242:243], s[76:77], 0, v[148:149]
	s_mov_b32 m0, s47
	v_lshl_add_u64 v[244:245], s[58:59], 0, v[146:147]
	global_load_lds_dwordx4 v[242:243], off
	v_lshl_add_u64 v[242:243], s[76:77], 0, v[144:145]
	s_add_i32 m0, s47, 0x2000
	s_nop 0
	global_load_lds_dwordx4 v[242:243], off
	v_lshl_add_u64 v[242:243], s[58:59], 0, v[150:151]
	s_mov_b32 m0, s5
	s_nop 0
	global_load_lds_dwordx4 v[242:243], off
	s_mov_b32 m0, s30
	s_nop 0
	global_load_lds_dwordx4 v[244:245], off
	s_waitcnt vmcnt(8)
	s_waitcnt lgkmcnt(0)
	s_barrier
; #define PG8_STAGE(bufoff, gbase, voff) do { _Pragma("unroll") for (int _i = 0; _i < 2; ++_i) \
;         __builtin_amdgcn_global_load_lds((const unsigned*)((const char*)(gbase) + (voff)[_i]), (PG8_LAS unsigned*)(lds + (bufoff) + ldsw + _i * 8192), 16, 0, 0); } while (0)
; #define PG8_LDA(dst, b, h) do { _Pragma("unroll") for (int m = 0; m < 4; ++m) _Pragma("unroll") for (int k = 0; k < 2; ++k) dst[m][k] = *(const PG8_LAS bf16x8*)(lds + PG8_SA(b, h) + aoff + m * 2048 + k * 1024); } while (0)
; #define PG8_LDB(dst, b, h) do { _Pragma("unroll") for (int n = 0; n < 2; ++n) _Pragma("unroll") for (int k = 0; k < 2; ++k) dst[n][k] = *(const PG8_LAS bf16x8*)(lds + PG8_SB(b, h) + boff + n * 2048 + k * 1024); } while (0)
; #define PG8_MMA(ai, bj, At, Bt) do { __builtin_amdgcn_s_setprio(1); _Pragma("unroll") for (int m = 0; m < 4; ++m) _Pragma("unroll") for (int n = 0; n < 2; ++n) _Pragma("unroll") for (int k = 0; k < 2; ++k) \
;         acc[ai][bj][m][n] = __builtin_amdgcn_mfma_f32_16x16x32_bf16(Bt[n][k], At[m][k], acc[ai][bj][m][n], 0, 0, 0); __builtin_amdgcn_s_setprio(0); } while (0)
; #define PG8_WAIT_V(n) asm volatile("s_waitcnt vmcnt(" #n ")" ::: "memory")
; #define PG8_WAIT_L(n) asm volatile("s_waitcnt lgkmcnt(" #n ")" ::: "memory")
; #define PG8_BAR __builtin_amdgcn_s_barrier()
; #define PG8_SCHED __builtin_amdgcn_sched_barrier(0)
; template <class Epi, class Sched, bool ALIGN_EPI = false, bool SP2 = false>
; __device__ __forceinline__ void gemm_phase(PG8_LAS unsigned char* lds, const Gemm g, const Sched& S, const Epi& E) {
;     ...
;             PG8_WAIT_V(8); PG8_WAIT_L(0); PG8_BAR; PG8_MMA(1, 0, At, B0); PG8_MMA(1, 1, At, B1); PG8_BAR; PG8_SCHED;
;             PG8_LDB(B0, 1, 0); PG8_LDB(B1, 1, 1); PG8_SCHED; PG8_LDA(At, 1, 0); PG8_STAGE(PG8_SA(0, 1), a2 + hstep, voffA);
;             PG8_WAIT_V(8); PG8_WAIT_L(0); PG8_BAR; PG8_MMA(0, 0, At, B0); PG8_MMA(0, 1, At, B1); PG8_BAR; PG8_SCHED;
;             PG8_LDA(At, 1, 1); PG8_STAGE(PG8_SB(1, 0), b3, voffB); PG8_STAGE(PG8_SB(1, 1), b3 + hstep, voffB); PG8_STAGE(PG8_SA(1, 0), a3, voffA);
;             PG8_WAIT_V(8); PG8_WAIT_L(0); PG8_BAR; PG8_MMA(1, 0, At, B0); PG8_MMA(1, 1, At, B1); PG8_BAR; PG8_SCHED;
	s_setprio 1
	s_waitcnt lgkmcnt(0)
	v_mfma_f32_16x16x32_bf16 v[62:65], v[156:159], v[208:211], v[62:65]
	v_mfma_f32_16x16x32_bf16 v[58:61], v[166:169], v[208:211], v[58:61]
	v_mfma_f32_16x16x32_bf16 v[46:49], v[156:159], v[216:219], v[46:49]
	v_mfma_f32_16x16x32_bf16 v[42:45], v[166:169], v[216:219], v[42:45]
	v_mfma_f32_16x16x32_bf16 v[30:33], v[156:159], v[224:227], v[30:33]
	v_mfma_f32_16x16x32_bf16 v[26:29], v[166:169], v[224:227], v[26:29]
	v_mfma_f32_16x16x32_bf16 v[14:17], v[156:159], v[232:235], v[14:17]
	v_mfma_f32_16x16x32_bf16 v[10:13], v[166:169], v[232:235], v[10:13]
	v_mfma_f32_16x16x32_bf16 v[62:65], v[162:165], v[212:215], v[62:65]
	v_mfma_f32_16x16x32_bf16 v[58:61], v[170:173], v[212:215], v[58:61]
	v_mfma_f32_16x16x32_bf16 v[46:49], v[162:165], v[220:223], v[46:49]
	v_mfma_f32_16x16x32_bf16 v[42:45], v[170:173], v[220:223], v[42:45]
	v_mfma_f32_16x16x32_bf16 v[30:33], v[162:165], v[228:231], v[30:33]
	v_mfma_f32_16x16x32_bf16 v[26:29], v[170:173], v[228:231], v[26:29]
	v_mfma_f32_16x16x32_bf16 v[14:17], v[162:165], v[236:239], v[14:17]
	v_mfma_f32_16x16x32_bf16 v[10:13], v[170:173], v[236:239], v[10:13]
	s_setprio 0
	s_setprio 1
	v_mfma_f32_16x16x32_bf16 v[54:57], v[174:177], v[208:211], v[54:57]
	v_mfma_f32_16x16x32_bf16 v[50:53], v[182:185], v[208:211], v[50:53]
	v_mfma_f32_16x16x32_bf16 v[38:41], v[174:177], v[216:219], v[38:41]
	v_mfma_f32_16x16x32_bf16 v[34:37], v[182:185], v[216:219], v[34:37]
	v_mfma_f32_16x16x32_bf16 v[22:25], v[174:177], v[224:227], v[22:25]
	v_mfma_f32_16x16x32_bf16 v[18:21], v[182:185], v[224:227], v[18:21]
	v_mfma_f32_16x16x32_bf16 v[6:9], v[174:177], v[232:235], v[6:9]
	v_mfma_f32_16x16x32_bf16 v[2:5], v[182:185], v[232:235], v[2:5]
	v_mfma_f32_16x16x32_bf16 v[54:57], v[178:181], v[212:215], v[54:57]
	v_mfma_f32_16x16x32_bf16 v[50:53], v[204:207], v[212:215], v[50:53]
	v_mfma_f32_16x16x32_bf16 v[38:41], v[178:181], v[220:223], v[38:41]
	v_mfma_f32_16x16x32_bf16 v[34:37], v[204:207], v[220:223], v[34:37]
	v_mfma_f32_16x16x32_bf16 v[22:25], v[178:181], v[228:231], v[22:25]
	v_mfma_f32_16x16x32_bf16 v[18:21], v[204:207], v[228:231], v[18:21]
	v_mfma_f32_16x16x32_bf16 v[6:9], v[178:181], v[236:239], v[6:9]
	v_mfma_f32_16x16x32_bf16 v[2:5], v[204:207], v[236:239], v[2:5]
	s_setprio 0
	s_barrier
	s_add_i32 s47, 0, 0x18000
	s_add_i32 s76, 0, 0x1c000
	v_add_u32_e32 v170, s47, v143
	v_add_u32_e32 v203, s76, v143
	ds_read_b128 v[156:159], v170
	ds_read_b128 v[162:165], v170 offset:1024
	ds_read_b128 v[166:169], v170 offset:2048
	ds_read_b128 v[170:173], v170 offset:3072
	ds_read_b128 v[174:177], v203
	ds_read_b128 v[178:181], v203 offset:1024
	ds_read_b128 v[182:185], v203 offset:2048
	ds_read_b128 v[204:207], v203 offset:3072
	s_add_u32 s58, s58, 0x80000
	s_addc_u32 s59, s59, 0
	s_mov_b32 m0, s34
	v_lshl_add_u64 v[246:247], s[58:59], 0, v[150:151]
	ds_read_b128 v[208:211], v161 offset:32768
	ds_read_b128 v[212:215], v161 offset:33792
	ds_read_b128 v[216:219], v161 offset:34816
	ds_read_b128 v[220:223], v161 offset:35840
	ds_read_b128 v[224:227], v161 offset:36864
	ds_read_b128 v[228:231], v161 offset:37888
	ds_read_b128 v[232:235], v161 offset:38912
	ds_read_b128 v[236:239], v161 offset:39936
	global_load_lds_dwordx4 v[246:247], off
	v_lshl_add_u64 v[246:247], s[58:59], 0, v[146:147]
	s_mov_b32 m0, s57
	s_nop 0
	global_load_lds_dwordx4 v[246:247], off
	s_waitcnt vmcnt(8)
	s_waitcnt lgkmcnt(0)
	s_barrier
	s_setprio 1
	s_waitcnt lgkmcnt(0)
	v_mfma_f32_16x16x32_bf16 v[126:129], v[156:159], v[208:211], v[126:129]
	v_mfma_f32_16x16x32_bf16 v[122:125], v[166:169], v[208:211], v[122:125]
	v_mfma_f32_16x16x32_bf16 v[110:113], v[156:159], v[216:219], v[110:113]
	v_mfma_f32_16x16x32_bf16 v[106:109], v[166:169], v[216:219], v[106:109]
	v_mfma_f32_16x16x32_bf16 v[94:97], v[156:159], v[224:227], v[94:97]
	v_mfma_f32_16x16x32_bf16 v[90:93], v[166:169], v[224:227], v[90:93]
	v_mfma_f32_16x16x32_bf16 v[78:81], v[156:159], v[232:235], v[78:81]
	v_mfma_f32_16x16x32_bf16 v[74:77], v[166:169], v[232:235], v[74:77]
	v_mfma_f32_16x16x32_bf16 v[126:129], v[162:165], v[212:215], v[126:129]
	v_mfma_f32_16x16x32_bf16 v[122:125], v[170:173], v[212:215], v[122:125]
	v_mfma_f32_16x16x32_bf16 v[110:113], v[162:165], v[220:223], v[110:113]
	v_mfma_f32_16x16x32_bf16 v[106:109], v[170:173], v[220:223], v[106:109]
	v_mfma_f32_16x16x32_bf16 v[94:97], v[162:165], v[228:231], v[94:97]
	v_mfma_f32_16x16x32_bf16 v[90:93], v[170:173], v[228:231], v[90:93]
	v_mfma_f32_16x16x32_bf16 v[78:81], v[162:165], v[236:239], v[78:81]
	v_mfma_f32_16x16x32_bf16 v[74:77], v[170:173], v[236:239], v[74:77]
	s_setprio 0
	s_setprio 1
	v_mfma_f32_16x16x32_bf16 v[118:121], v[174:177], v[208:211], v[118:121]
	v_mfma_f32_16x16x32_bf16 v[114:117], v[182:185], v[208:211], v[114:117]
	v_mfma_f32_16x16x32_bf16 v[102:105], v[174:177], v[216:219], v[102:105]
	v_mfma_f32_16x16x32_bf16 v[98:101], v[182:185], v[216:219], v[98:101]
	v_mfma_f32_16x16x32_bf16 v[86:89], v[174:177], v[224:227], v[86:89]
	v_mfma_f32_16x16x32_bf16 v[82:85], v[182:185], v[224:227], v[82:85]
	v_mfma_f32_16x16x32_bf16 v[70:73], v[174:177], v[232:235], v[70:73]
	v_mfma_f32_16x16x32_bf16 v[66:69], v[182:185], v[232:235], v[66:69]
	v_mfma_f32_16x16x32_bf16 v[118:121], v[178:181], v[212:215], v[118:121]
	v_mfma_f32_16x16x32_bf16 v[114:117], v[204:207], v[212:215], v[114:117]
	v_mfma_f32_16x16x32_bf16 v[102:105], v[178:181], v[220:223], v[102:105]
	v_mfma_f32_16x16x32_bf16 v[98:101], v[204:207], v[220:223], v[98:101]
	v_mfma_f32_16x16x32_bf16 v[86:89], v[178:181], v[228:231], v[86:89]
	v_mfma_f32_16x16x32_bf16 v[82:85], v[204:207], v[228:231], v[82:85]
	v_mfma_f32_16x16x32_bf16 v[70:73], v[178:181], v[236:239], v[70:73]
	v_mfma_f32_16x16x32_bf16 v[66:69], v[204:207], v[236:239], v[66:69]
	s_setprio 0
	s_barrier
; #define PG8_STAGE(bufoff, gbase, voff) do { _Pragma("unroll") for (int _i = 0; _i < 2; ++_i) \
;         __builtin_amdgcn_global_load_lds((const unsigned*)((const char*)(gbase) + (voff)[_i]), (PG8_LAS unsigned*)(lds + (bufoff) + ldsw + _i * 8192), 16, 0, 0); } while (0)
; #define PG8_LDA(dst, b, h) do { _Pragma("unroll") for (int m = 0; m < 4; ++m) _Pragma("unroll") for (int k = 0; k < 2; ++k) dst[m][k] = *(const PG8_LAS bf16x8*)(lds + PG8_SA(b, h) + aoff + m * 2048 + k * 1024); } while (0)
; #define PG8_LDB(dst, b, h) do { _Pragma("unroll") for (int n = 0; n < 2; ++n) _Pragma("unroll") for (int k = 0; k < 2; ++k) dst[n][k] = *(const PG8_LAS bf16x8*)(lds + PG8_SB(b, h) + boff + n * 2048 + k * 1024); } while (0)
; #define PG8_MMA(ai, bj, At, Bt) do { __builtin_amdgcn_s_setprio(1); _Pragma("unroll") for (int m = 0; m < 4; ++m) _Pragma("unroll") for (int n = 0; n < 2; ++n) _Pragma("unroll") for (int k = 0; k < 2; ++k) \
;         acc[ai][bj][m][n] = __builtin_amdgcn_mfma_f32_16x16x32_bf16(Bt[n][k], At[m][k], acc[ai][bj][m][n], 0, 0, 0); __builtin_amdgcn_s_setprio(0); } while (0)
; #define PG8_WAIT_V(n) asm volatile("s_waitcnt vmcnt(" #n ")" ::: "memory")
;     __device__ __forceinline__ void operator()(const f32x4 (&acc)[2][2][4][2], const Unit& u, int wr, int wc, int fr, int fq) const {
;     ...
;             for (int m = 0; m < 4; ++m) { const size_t row = (size_t)(row0 + ai * HALF + m * 16); float ss = 0.f;
; #pragma unroll
;                 for (int bj = 0; bj < 2; ++bj) { const size_t off = row * DM + col0 + bj * HALF;
;                     f32x4 v0 = acc[ai][bj][m][0] + *(const f32x4*)(base + off), v1 = acc[ai][bj][m][1] + *(const f32x4*)(base + off + 4);
; template <class Epi, class Sched, bool ALIGN_EPI = false, bool SP2 = false>
; __device__ __forceinline__ void gemm_phase(PG8_LAS unsigned char* lds, const Gemm g, const Sched& S, const Epi& E) {
;     ...
;             PG8_LDB(B0, 1, 0); PG8_LDB(B1, 1, 1); PG8_SCHED; PG8_LDA(At, 1, 0); PG8_STAGE(PG8_SA(0, 1), a2 + hstep, voffA);
;             PG8_WAIT_V(8); PG8_WAIT_L(0); PG8_BAR; PG8_MMA(0, 0, At, B0); PG8_MMA(0, 1, At, B1); PG8_BAR; PG8_SCHED;
;             PG8_LDA(At, 1, 1); PG8_STAGE(PG8_SB(1, 0), b3, voffB); PG8_STAGE(PG8_SB(1, 1), b3 + hstep, voffB); PG8_STAGE(PG8_SA(1, 0), a3, voffA);
;             PG8_WAIT_V(8); PG8_WAIT_L(0); PG8_BAR; PG8_MMA(1, 0, At, B0); PG8_MMA(1, 1, At, B1); PG8_BAR; PG8_SCHED;
	s_add_i32 s47, s47, s4
	v_lshl_add_u64 v[186:187], v[186:187], 0, s[68:69]
	s_mov_b32 m0, s47
	ds_read_b128 v[208:211], v161 offset:49152
	ds_read_b128 v[212:215], v161 offset:50176
	ds_read_b128 v[216:219], v161 offset:51200
	ds_read_b128 v[220:223], v161 offset:52224
	ds_read_b128 v[224:227], v161 offset:53248
	ds_read_b128 v[228:231], v161 offset:54272
	ds_read_b128 v[232:235], v161 offset:55296
	ds_read_b128 v[236:239], v161 offset:56320
	global_load_lds_dwordx4 v[186:187], off
	s_add_i32 m0, s47, 0x2000
	s_add_u32 s40, s40, 0x80080
	v_lshl_add_u64 v[186:187], v[240:241], 0, s[68:69]
	s_addc_u32 s41, s41, 0
	s_add_i32 s47, s76, s4
	global_load_lds_dwordx4 v[186:187], off
	v_lshl_add_u64 v[186:187], s[40:41], 0, v[148:149]
	s_mov_b32 m0, s47
	s_nop 0
	global_load_lds_dwordx4 v[186:187], off
	v_lshl_add_u64 v[186:187], s[40:41], 0, v[144:145]
	s_add_i32 m0, s47, 0x2000
	s_nop 0
	global_load_lds_dwordx4 v[186:187], off
	v_lshl_add_u64 v[186:187], v[242:243], 0, s[68:69]
	s_mov_b32 m0, s67
	s_nop 0
	global_load_lds_dwordx4 v[186:187], off
	v_lshl_add_u64 v[186:187], v[244:245], 0, s[68:69]
	s_mov_b32 m0, s28
	s_nop 0
	global_load_lds_dwordx4 v[186:187], off
	s_waitcnt vmcnt(8)
	s_waitcnt lgkmcnt(0)
	s_barrier
	s_setprio 1
	s_waitcnt lgkmcnt(0)
	v_mfma_f32_16x16x32_bf16 v[62:65], v[156:159], v[208:211], v[62:65]
	v_mfma_f32_16x16x32_bf16 v[58:61], v[166:169], v[208:211], v[58:61]
	v_mfma_f32_16x16x32_bf16 v[46:49], v[156:159], v[216:219], v[46:49]
	v_mfma_f32_16x16x32_bf16 v[42:45], v[166:169], v[216:219], v[42:45]
	v_mfma_f32_16x16x32_bf16 v[30:33], v[156:159], v[224:227], v[30:33]
	v_mfma_f32_16x16x32_bf16 v[26:29], v[166:169], v[224:227], v[26:29]
	v_mfma_f32_16x16x32_bf16 v[14:17], v[156:159], v[232:235], v[14:17]
	v_mfma_f32_16x16x32_bf16 v[10:13], v[166:169], v[232:235], v[10:13]
	v_mfma_f32_16x16x32_bf16 v[62:65], v[162:165], v[212:215], v[62:65]
	v_mfma_f32_16x16x32_bf16 v[58:61], v[170:173], v[212:215], v[58:61]
	v_mfma_f32_16x16x32_bf16 v[46:49], v[162:165], v[220:223], v[46:49]
	v_mfma_f32_16x16x32_bf16 v[42:45], v[170:173], v[220:223], v[42:45]
	v_mfma_f32_16x16x32_bf16 v[30:33], v[162:165], v[228:231], v[30:33]
	v_mfma_f32_16x16x32_bf16 v[26:29], v[170:173], v[228:231], v[26:29]
	v_mfma_f32_16x16x32_bf16 v[14:17], v[162:165], v[236:239], v[14:17]
	v_mfma_f32_16x16x32_bf16 v[10:13], v[170:173], v[236:239], v[10:13]
	s_setprio 0
	s_setprio 1
	v_mfma_f32_16x16x32_bf16 v[54:57], v[174:177], v[208:211], v[54:57]
	v_mfma_f32_16x16x32_bf16 v[50:53], v[182:185], v[208:211], v[50:53]
	v_mfma_f32_16x16x32_bf16 v[38:41], v[174:177], v[216:219], v[38:41]
	v_mfma_f32_16x16x32_bf16 v[34:37], v[182:185], v[216:219], v[34:37]
	v_mfma_f32_16x16x32_bf16 v[22:25], v[174:177], v[224:227], v[22:25]
	v_mfma_f32_16x16x32_bf16 v[18:21], v[182:185], v[224:227], v[18:21]
	v_mfma_f32_16x16x32_bf16 v[6:9], v[174:177], v[232:235], v[6:9]
	v_mfma_f32_16x16x32_bf16 v[2:5], v[182:185], v[232:235], v[2:5]
	v_mfma_f32_16x16x32_bf16 v[54:57], v[178:181], v[212:215], v[54:57]
	v_mfma_f32_16x16x32_bf16 v[50:53], v[204:207], v[212:215], v[50:53]
	v_mfma_f32_16x16x32_bf16 v[38:41], v[178:181], v[220:223], v[38:41]
	v_mfma_f32_16x16x32_bf16 v[34:37], v[204:207], v[220:223], v[34:37]
	v_mfma_f32_16x16x32_bf16 v[22:25], v[178:181], v[228:231], v[22:25]
	v_mfma_f32_16x16x32_bf16 v[18:21], v[204:207], v[228:231], v[18:21]
	v_mfma_f32_16x16x32_bf16 v[6:9], v[178:181], v[236:239], v[6:9]
	v_mfma_f32_16x16x32_bf16 v[2:5], v[204:207], v[236:239], v[2:5]
	s_setprio 0
	s_barrier
	s_add_i32 s46, s46, 2
	s_add_u32 vcc_lo, vcc_lo, 0x100
	s_addc_u32 vcc_hi, vcc_hi, 0
	s_add_u32 s78, s78, 0x100
	s_addc_u32 s79, s79, 0
	s_cmp_gt_u32 s46, 29
	s_cbranch_scc0 .LBB0_98
	v_lshl_add_u32 v156, s73, 8, v1
	v_lshl_or_b32 v157, s54, 8, v160
	v_lshl_add_u32 v157, v156, 11, v157
	v_mov_b32_e32 v247, 0
	v_lshlrev_b32_e32 v246, 2, v157
	v_lshl_add_u64 v[162:163], s[8:9], 0, v[246:247]
	v_lshlrev_b32_e32 v246, 1, v157
	v_lshl_add_u64 v[244:245], s[70:71], 0, v[246:247]
	s_mov_b32 s41, 0
	global_load_dwordx4 v[164:167], v[162:163], off
	global_load_dwordx4 v[168:171], v[162:163], off offset:16
	global_load_dwordx4 v[172:175], v[162:163], off offset:512
	global_load_dwordx4 v[176:179], v[162:163], off offset:528
	s_mov_b32 s40, 0x20000
	v_lshl_add_u64 v[246:247], v[162:163], 0, s[40:41]
	global_load_dwordx4 v[180:183], v[246:247], off
	global_load_dwordx4 v[184:187], v[246:247], off offset:16
	global_load_dwordx4 v[204:207], v[246:247], off offset:512
	global_load_dwordx4 v[208:211], v[246:247], off offset:528
	s_mov_b32 s40, 0x40000
	v_lshl_add_u64 v[246:247], v[162:163], 0, s[40:41]
	global_load_dwordx4 v[212:215], v[246:247], off
	global_load_dwordx4 v[216:219], v[246:247], off offset:16
	global_load_dwordx4 v[220:223], v[246:247], off offset:512
	global_load_dwordx4 v[224:227], v[246:247], off offset:528
	s_mov_b32 s40, 0x60000
	v_lshl_add_u64 v[246:247], v[162:163], 0, s[40:41]
	global_load_dwordx4 v[228:231], v[246:247], off
	global_load_dwordx4 v[232:235], v[246:247], off offset:16
	global_load_dwordx4 v[236:239], v[246:247], off offset:512
	global_load_dwordx4 v[240:243], v[246:247], off offset:528
	s_and_b64 vcc, exec, s[36:37]
	s_cbranch_vccz .Lx1_nobar
	s_barrier
; __device__ __forceinline__ unsigned cvt_pk_bf16(float lo, float hi) { const f32x2c_t v = {lo, hi}; const bf16x2c_t b = __builtin_convertvector(v, bf16x2c_t); return __builtin_bit_cast(unsigned, b); }
; __device__ __forceinline__ float bf_lo(unsigned w) { return __uint_as_float(w << 16); }
; __device__ __forceinline__ float bf_hi(unsigned w) { return __uint_as_float(w & 0xffff0000u); }
;     __device__ __forceinline__ void operator()(const f32x4 (&acc)[2][2][4][2], const Unit& u, int wr, int wc, int fr, int fq) const {
;     ...
;             for (int m = 0; m < 4; ++m) { const size_t row = (size_t)(row0 + ai * HALF + m * 16); float ss = 0.f;
; #pragma unroll
;                 for (int bj = 0; bj < 2; ++bj) { const size_t off = row * DM + col0 + bj * HALF;
;                     f32x4 v0 = acc[ai][bj][m][0] + *(const f32x4*)(base + off), v1 = acc[ai][bj][m][1] + *(const f32x4*)(base + off + 4);
;                     u32x4 w; w.x = cvt_pk_bf16(v0[0], v0[1]); w.y = cvt_pk_bf16(v0[2], v0[3]); w.z = cvt_pk_bf16(v1[0], v1[1]); w.w = cvt_pk_bf16(v1[2], v1[3]);
;                     *(u32x4*)(XN + off) = w;
;                     v0 = (f32x4){bf_lo(w.x), bf_hi(w.x), bf_lo(w.y), bf_hi(w.y)}; v1 = (f32x4){bf_lo(w.z), bf_hi(w.z), bf_lo(w.w), bf_hi(w.w)};
;                     ss += (v0[0] * v0[0] + v0[1] * v0[1]) + (v0[2] * v0[2] + v0[3] * v0[3]) + (v1[0] * v1[0] + v1[1] * v1[1]) + (v1[2] * v1[2] + v1[3] * v1[3]); }
.Lx1_nobar:
	s_waitcnt vmcnt(14)
	v_pk_add_f32 v[126:127], v[126:127], v[164:165]
	v_pk_add_f32 v[128:129], v[128:129], v[166:167]
	v_pk_add_f32 v[122:123], v[122:123], v[168:169]
	v_pk_add_f32 v[124:125], v[124:125], v[170:171]
	v_cvt_pk_bf16_f32 v164, v126, v127
	v_cvt_pk_bf16_f32 v165, v128, v129
	v_cvt_pk_bf16_f32 v166, v122, v123
	v_cvt_pk_bf16_f32 v167, v124, v125
	global_store_dwordx4 v[244:245], v[164:167], off
	v_lshlrev_b32_e32 v126, 16, v164
	v_lshlrev_b32_e32 v127, 16, v165
	v_and_b32_e32 v128, 0xffff0000, v164
	v_and_b32_e32 v129, 0xffff0000, v165
	v_mul_f32_e32 v128, v128, v128
	v_mul_f32_e32 v129, v129, v129
	v_lshlrev_b32_e32 v122, 16, v166
	v_and_b32_e32 v123, 0xffff0000, v166
	v_fmac_f32_e32 v128, v126, v126
	v_fmac_f32_e32 v129, v127, v127
	v_add_f32_e32 v128, v128, v129
	v_mul_f32_e32 v129, v123, v123
	v_lshlrev_b32_e32 v124, 16, v167
	v_and_b32_e32 v125, 0xffff0000, v167
	v_fmac_f32_e32 v129, v122, v122
	v_add_f32_e32 v128, v129, v128
	v_mul_f32_e32 v129, v125, v125
	v_fmac_f32_e32 v129, v124, v124
	v_add_f32_e32 v126, v129, v128
	s_waitcnt vmcnt(13)
	v_pk_add_f32 v[118:119], v[118:119], v[172:173]
	v_pk_add_f32 v[120:121], v[120:121], v[174:175]
	v_pk_add_f32 v[114:115], v[114:115], v[176:177]
	v_pk_add_f32 v[116:117], v[116:117], v[178:179]
	v_cvt_pk_bf16_f32 v172, v118, v119
	v_cvt_pk_bf16_f32 v173, v120, v121
	v_cvt_pk_bf16_f32 v174, v114, v115
	v_cvt_pk_bf16_f32 v175, v116, v117
	global_store_dwordx4 v[244:245], v[172:175], off offset:256
	v_lshlrev_b32_e32 v118, 16, v172
	v_lshlrev_b32_e32 v119, 16, v173
	v_and_b32_e32 v120, 0xffff0000, v172
	v_and_b32_e32 v121, 0xffff0000, v173
	v_mul_f32_e32 v120, v120, v120
	v_mul_f32_e32 v121, v121, v121
	v_lshlrev_b32_e32 v114, 16, v174
	v_and_b32_e32 v115, 0xffff0000, v174
	v_fmac_f32_e32 v120, v118, v118
	v_fmac_f32_e32 v121, v119, v119
	v_add_f32_e32 v120, v120, v121
	v_mul_f32_e32 v121, v115, v115
	v_lshlrev_b32_e32 v116, 16, v175
	v_and_b32_e32 v117, 0xffff0000, v175
	v_fmac_f32_e32 v121, v114, v114
	v_add_f32_e32 v120, v121, v120
	v_mul_f32_e32 v121, v117, v117
	v_fmac_f32_e32 v121, v116, v116
	v_add_f32_e32 v120, v121, v120
	v_add_f32_e32 v126, v126, v120
	s_mov_b32 s40, 0x100000
	v_lshl_add_u64 v[246:247], v[162:163], 0, s[40:41]
	global_load_dwordx4 v[164:167], v[246:247], off
	global_load_dwordx4 v[168:171], v[246:247], off offset:16
	global_load_dwordx4 v[172:175], v[246:247], off offset:512
	global_load_dwordx4 v[176:179], v[246:247], off offset:528
	s_mov_b32 s40, 0x10000
	v_lshl_add_u64 v[158:159], v[244:245], 0, s[40:41]
	s_waitcnt vmcnt(16)
	v_pk_add_f32 v[110:111], v[110:111], v[180:181]
	v_pk_add_f32 v[112:113], v[112:113], v[182:183]
	v_pk_add_f32 v[106:107], v[106:107], v[184:185]
	v_pk_add_f32 v[108:109], v[108:109], v[186:187]
	v_cvt_pk_bf16_f32 v180, v110, v111
	v_cvt_pk_bf16_f32 v181, v112, v113
	v_cvt_pk_bf16_f32 v182, v106, v107
	v_cvt_pk_bf16_f32 v183, v108, v109
	global_store_dwordx4 v[158:159], v[180:183], off
	v_lshlrev_b32_e32 v110, 16, v180
	v_lshlrev_b32_e32 v111, 16, v181
	v_and_b32_e32 v112, 0xffff0000, v180
	v_and_b32_e32 v113, 0xffff0000, v181
	v_mul_f32_e32 v112, v112, v112
	v_mul_f32_e32 v113, v113, v113
	v_lshlrev_b32_e32 v106, 16, v182
	v_and_b32_e32 v107, 0xffff0000, v182
	v_fmac_f32_e32 v112, v110, v110
	v_fmac_f32_e32 v113, v111, v111
	v_add_f32_e32 v112, v112, v113
	v_mul_f32_e32 v113, v107, v107
	v_lshlrev_b32_e32 v108, 16, v183
	v_and_b32_e32 v109, 0xffff0000, v183
	v_fmac_f32_e32 v113, v106, v106
	v_add_f32_e32 v112, v113, v112
	v_mul_f32_e32 v113, v109, v109
	v_fmac_f32_e32 v113, v108, v108
	v_add_f32_e32 v110, v113, v112
	s_waitcnt vmcnt(15)
	v_pk_add_f32 v[102:103], v[102:103], v[204:205]
	v_pk_add_f32 v[104:105], v[104:105], v[206:207]
	v_pk_add_f32 v[98:99], v[98:99], v[208:209]
	v_pk_add_f32 v[100:101], v[100:101], v[210:211]
	v_cvt_pk_bf16_f32 v204, v102, v103
	v_cvt_pk_bf16_f32 v205, v104, v105
	v_cvt_pk_bf16_f32 v206, v98, v99
	v_cvt_pk_bf16_f32 v207, v100, v101
	global_store_dwordx4 v[158:159], v[204:207], off offset:256
	v_lshlrev_b32_e32 v102, 16, v204
	v_lshlrev_b32_e32 v103, 16, v205
	v_and_b32_e32 v104, 0xffff0000, v204
	v_and_b32_e32 v105, 0xffff0000, v205
	v_mul_f32_e32 v104, v104, v104
	v_mul_f32_e32 v105, v105, v105
	v_lshlrev_b32_e32 v98, 16, v206
	v_and_b32_e32 v99, 0xffff0000, v206
	v_fmac_f32_e32 v104, v102, v102
	v_fmac_f32_e32 v105, v103, v103
	v_add_f32_e32 v104, v104, v105
	v_mul_f32_e32 v105, v99, v99
	v_lshlrev_b32_e32 v100, 16, v207
	v_and_b32_e32 v101, 0xffff0000, v207
	v_fmac_f32_e32 v105, v98, v98
	v_add_f32_e32 v104, v105, v104
	v_mul_f32_e32 v105, v101, v101
	v_fmac_f32_e32 v105, v100, v100
	v_add_f32_e32 v104, v105, v104
	v_add_f32_e32 v110, v110, v104
	s_mov_b32 s40, 0x120000
	v_lshl_add_u64 v[246:247], v[162:163], 0, s[40:41]
	global_load_dwordx4 v[180:183], v[246:247], off
	global_load_dwordx4 v[184:187], v[246:247], off offset:16
	global_load_dwordx4 v[204:207], v[246:247], off offset:512
	global_load_dwordx4 v[208:211], v[246:247], off offset:528
	s_mov_b32 s40, 0x20000
	v_lshl_add_u64 v[158:159], v[244:245], 0, s[40:41]
	s_waitcnt vmcnt(18)
	v_pk_add_f32 v[94:95], v[94:95], v[212:213]
	v_pk_add_f32 v[96:97], v[96:97], v[214:215]
	v_pk_add_f32 v[90:91], v[90:91], v[216:217]
	v_pk_add_f32 v[92:93], v[92:93], v[218:219]
	v_cvt_pk_bf16_f32 v212, v94, v95
	v_cvt_pk_bf16_f32 v213, v96, v97
	v_cvt_pk_bf16_f32 v214, v90, v91
	v_cvt_pk_bf16_f32 v215, v92, v93
	global_store_dwordx4 v[158:159], v[212:215], off
	v_lshlrev_b32_e32 v94, 16, v212
	v_lshlrev_b32_e32 v95, 16, v213
	v_and_b32_e32 v96, 0xffff0000, v212
	v_and_b32_e32 v97, 0xffff0000, v213
	v_mul_f32_e32 v96, v96, v96
	v_mul_f32_e32 v97, v97, v97
	v_lshlrev_b32_e32 v90, 16, v214
	v_and_b32_e32 v91, 0xffff0000, v214
	v_fmac_f32_e32 v96, v94, v94
	v_fmac_f32_e32 v97, v95, v95
	v_add_f32_e32 v96, v96, v97
	v_mul_f32_e32 v97, v91, v91
	v_lshlrev_b32_e32 v92, 16, v215
	v_and_b32_e32 v93, 0xffff0000, v215
	v_fmac_f32_e32 v97, v90, v90
	v_add_f32_e32 v96, v97, v96
	v_mul_f32_e32 v97, v93, v93
	v_fmac_f32_e32 v97, v92, v92
	v_add_f32_e32 v94, v97, v96
	s_waitcnt vmcnt(17)
; __device__ __forceinline__ unsigned cvt_pk_bf16(float lo, float hi) { const f32x2c_t v = {lo, hi}; const bf16x2c_t b = __builtin_convertvector(v, bf16x2c_t); return __builtin_bit_cast(unsigned, b); }
; __device__ __forceinline__ float bf_lo(unsigned w) { return __uint_as_float(w << 16); }
; __device__ __forceinline__ float bf_hi(unsigned w) { return __uint_as_float(w & 0xffff0000u); }
;     __device__ __forceinline__ void operator()(const f32x4 (&acc)[2][2][4][2], const Unit& u, int wr, int wc, int fr, int fq) const {
;     ...
;             for (int m = 0; m < 4; ++m) { const size_t row = (size_t)(row0 + ai * HALF + m * 16); float ss = 0.f;
; #pragma unroll
;                 for (int bj = 0; bj < 2; ++bj) { const size_t off = row * DM + col0 + bj * HALF;
;                     f32x4 v0 = acc[ai][bj][m][0] + *(const f32x4*)(base + off), v1 = acc[ai][bj][m][1] + *(const f32x4*)(base + off + 4);
;                     u32x4 w; w.x = cvt_pk_bf16(v0[0], v0[1]); w.y = cvt_pk_bf16(v0[2], v0[3]); w.z = cvt_pk_bf16(v1[0], v1[1]); w.w = cvt_pk_bf16(v1[2], v1[3]);
;                     *(u32x4*)(XN + off) = w;
;                     v0 = (f32x4){bf_lo(w.x), bf_hi(w.x), bf_lo(w.y), bf_hi(w.y)}; v1 = (f32x4){bf_lo(w.z), bf_hi(w.z), bf_lo(w.w), bf_hi(w.w)};
;                     ss += (v0[0] * v0[0] + v0[1] * v0[1]) + (v0[2] * v0[2] + v0[3] * v0[3]) + (v1[0] * v1[0] + v1[1] * v1[1]) + (v1[2] * v1[2] + v1[3] * v1[3]); }
	v_pk_add_f32 v[86:87], v[86:87], v[220:221]
	v_pk_add_f32 v[88:89], v[88:89], v[222:223]
	v_pk_add_f32 v[82:83], v[82:83], v[224:225]
	v_pk_add_f32 v[84:85], v[84:85], v[226:227]
	v_cvt_pk_bf16_f32 v220, v86, v87
	v_cvt_pk_bf16_f32 v221, v88, v89
	v_cvt_pk_bf16_f32 v222, v82, v83
	v_cvt_pk_bf16_f32 v223, v84, v85
	global_store_dwordx4 v[158:159], v[220:223], off offset:256
	v_lshlrev_b32_e32 v86, 16, v220
	v_lshlrev_b32_e32 v87, 16, v221
	v_and_b32_e32 v88, 0xffff0000, v220
	v_and_b32_e32 v89, 0xffff0000, v221
	v_mul_f32_e32 v88, v88, v88
	v_mul_f32_e32 v89, v89, v89
	v_lshlrev_b32_e32 v82, 16, v222
	v_and_b32_e32 v83, 0xffff0000, v222
	v_fmac_f32_e32 v88, v86, v86
	v_fmac_f32_e32 v89, v87, v87
	v_add_f32_e32 v88, v88, v89
	v_mul_f32_e32 v89, v83, v83
	v_lshlrev_b32_e32 v84, 16, v223
	v_and_b32_e32 v85, 0xffff0000, v223
	v_fmac_f32_e32 v89, v82, v82
	v_add_f32_e32 v88, v89, v88
	v_mul_f32_e32 v89, v85, v85
	v_fmac_f32_e32 v89, v84, v84
	v_add_f32_e32 v88, v89, v88
	v_add_f32_e32 v94, v94, v88
	s_mov_b32 s40, 0x140000
	v_lshl_add_u64 v[246:247], v[162:163], 0, s[40:41]
	global_load_dwordx4 v[212:215], v[246:247], off
	global_load_dwordx4 v[216:219], v[246:247], off offset:16
	global_load_dwordx4 v[220:223], v[246:247], off offset:512
	global_load_dwordx4 v[224:227], v[246:247], off offset:528
	s_mov_b32 s40, 0x30000
	v_lshl_add_u64 v[158:159], v[244:245], 0, s[40:41]
	s_waitcnt vmcnt(20)
	v_pk_add_f32 v[78:79], v[78:79], v[228:229]
	v_pk_add_f32 v[80:81], v[80:81], v[230:231]
	v_pk_add_f32 v[74:75], v[74:75], v[232:233]
	v_pk_add_f32 v[76:77], v[76:77], v[234:235]
	v_cvt_pk_bf16_f32 v228, v78, v79
	v_cvt_pk_bf16_f32 v229, v80, v81
	v_cvt_pk_bf16_f32 v230, v74, v75
	v_cvt_pk_bf16_f32 v231, v76, v77
	global_store_dwordx4 v[158:159], v[228:231], off
	v_lshlrev_b32_e32 v78, 16, v228
	v_lshlrev_b32_e32 v79, 16, v229
	v_and_b32_e32 v80, 0xffff0000, v228
	v_and_b32_e32 v81, 0xffff0000, v229
	v_mul_f32_e32 v80, v80, v80
	v_mul_f32_e32 v81, v81, v81
	v_lshlrev_b32_e32 v74, 16, v230
	v_and_b32_e32 v75, 0xffff0000, v230
	v_fmac_f32_e32 v80, v78, v78
	v_fmac_f32_e32 v81, v79, v79
	v_add_f32_e32 v80, v80, v81
	v_mul_f32_e32 v81, v75, v75
	v_lshlrev_b32_e32 v76, 16, v231
	v_and_b32_e32 v77, 0xffff0000, v231
	v_fmac_f32_e32 v81, v74, v74
	v_add_f32_e32 v80, v81, v80
	v_mul_f32_e32 v81, v77, v77
	v_fmac_f32_e32 v81, v76, v76
	v_add_f32_e32 v78, v81, v80
	s_waitcnt vmcnt(19)
	v_pk_add_f32 v[70:71], v[70:71], v[236:237]
	v_pk_add_f32 v[72:73], v[72:73], v[238:239]
	v_pk_add_f32 v[66:67], v[66:67], v[240:241]
	v_pk_add_f32 v[68:69], v[68:69], v[242:243]
	v_cvt_pk_bf16_f32 v236, v70, v71
	v_cvt_pk_bf16_f32 v237, v72, v73
	v_cvt_pk_bf16_f32 v238, v66, v67
	v_cvt_pk_bf16_f32 v239, v68, v69
	global_store_dwordx4 v[158:159], v[236:239], off offset:256
	v_lshlrev_b32_e32 v70, 16, v236
	v_lshlrev_b32_e32 v71, 16, v237
	v_and_b32_e32 v72, 0xffff0000, v236
	v_and_b32_e32 v73, 0xffff0000, v237
	v_mul_f32_e32 v72, v72, v72
	v_mul_f32_e32 v73, v73, v73
	v_lshlrev_b32_e32 v66, 16, v238
	v_and_b32_e32 v67, 0xffff0000, v238
	v_fmac_f32_e32 v72, v70, v70
	v_fmac_f32_e32 v73, v71, v71
	v_add_f32_e32 v72, v72, v73
	v_mul_f32_e32 v73, v67, v67
	v_lshlrev_b32_e32 v68, 16, v239
	v_and_b32_e32 v69, 0xffff0000, v239
	v_fmac_f32_e32 v73, v66, v66
	v_add_f32_e32 v72, v73, v72
	v_mul_f32_e32 v73, v69, v69
	v_fmac_f32_e32 v73, v68, v68
	v_add_f32_e32 v72, v73, v72
	v_add_f32_e32 v78, v78, v72
	s_mov_b32 s40, 0x160000
	v_lshl_add_u64 v[246:247], v[162:163], 0, s[40:41]
	global_load_dwordx4 v[228:231], v[246:247], off
	global_load_dwordx4 v[232:235], v[246:247], off offset:16
	global_load_dwordx4 v[236:239], v[246:247], off offset:512
	global_load_dwordx4 v[240:243], v[246:247], off offset:528
	s_mov_b32 s40, 0x80000
	v_lshl_add_u64 v[158:159], v[244:245], 0, s[40:41]
	s_waitcnt vmcnt(20)
	v_pk_add_f32 v[62:63], v[62:63], v[164:165]
	v_pk_add_f32 v[64:65], v[64:65], v[166:167]
	v_pk_add_f32 v[58:59], v[58:59], v[168:169]
	v_pk_add_f32 v[60:61], v[60:61], v[170:171]
	v_cvt_pk_bf16_f32 v164, v62, v63
	v_cvt_pk_bf16_f32 v165, v64, v65
	v_cvt_pk_bf16_f32 v166, v58, v59
	v_cvt_pk_bf16_f32 v167, v60, v61
	global_store_dwordx4 v[158:159], v[164:167], off
	v_lshlrev_b32_e32 v62, 16, v164
	v_lshlrev_b32_e32 v63, 16, v165
	v_and_b32_e32 v64, 0xffff0000, v164
	v_and_b32_e32 v65, 0xffff0000, v165
	v_mul_f32_e32 v64, v64, v64
	v_mul_f32_e32 v65, v65, v65
	v_lshlrev_b32_e32 v58, 16, v166
	v_and_b32_e32 v59, 0xffff0000, v166
	v_fmac_f32_e32 v64, v62, v62
	v_fmac_f32_e32 v65, v63, v63
	v_add_f32_e32 v64, v64, v65
	v_mul_f32_e32 v65, v59, v59
	v_lshlrev_b32_e32 v60, 16, v167
	v_and_b32_e32 v61, 0xffff0000, v167
	v_fmac_f32_e32 v65, v58, v58
	v_add_f32_e32 v64, v65, v64
	v_mul_f32_e32 v65, v61, v61
	v_fmac_f32_e32 v65, v60, v60
	v_add_f32_e32 v62, v65, v64
	s_waitcnt vmcnt(19)
	v_pk_add_f32 v[54:55], v[54:55], v[172:173]
	v_pk_add_f32 v[56:57], v[56:57], v[174:175]
	v_pk_add_f32 v[50:51], v[50:51], v[176:177]
	v_pk_add_f32 v[52:53], v[52:53], v[178:179]
	v_cvt_pk_bf16_f32 v172, v54, v55
	v_cvt_pk_bf16_f32 v173, v56, v57
	v_cvt_pk_bf16_f32 v174, v50, v51
	v_cvt_pk_bf16_f32 v175, v52, v53
	global_store_dwordx4 v[158:159], v[172:175], off offset:256
	v_lshlrev_b32_e32 v54, 16, v172
	v_lshlrev_b32_e32 v55, 16, v173
	v_and_b32_e32 v56, 0xffff0000, v172
	v_and_b32_e32 v57, 0xffff0000, v173
	v_mul_f32_e32 v56, v56, v56
	v_mul_f32_e32 v57, v57, v57
	v_lshlrev_b32_e32 v50, 16, v174
	v_and_b32_e32 v51, 0xffff0000, v174
	v_fmac_f32_e32 v56, v54, v54
	v_fmac_f32_e32 v57, v55, v55
	v_add_f32_e32 v56, v56, v57
	v_mul_f32_e32 v57, v51, v51
	v_lshlrev_b32_e32 v52, 16, v175
	v_and_b32_e32 v53, 0xffff0000, v175
	v_fmac_f32_e32 v57, v50, v50
	v_add_f32_e32 v56, v57, v56
	v_mul_f32_e32 v57, v53, v53
	v_fmac_f32_e32 v57, v52, v52
	v_add_f32_e32 v56, v57, v56
	v_add_f32_e32 v62, v62, v56
	s_mov_b32 s40, 0x90000
	v_lshl_add_u64 v[158:159], v[244:245], 0, s[40:41]
	s_waitcnt vmcnt(16)
; __device__ __forceinline__ unsigned cvt_pk_bf16(float lo, float hi) { const f32x2c_t v = {lo, hi}; const bf16x2c_t b = __builtin_convertvector(v, bf16x2c_t); return __builtin_bit_cast(unsigned, b); }
; __device__ __forceinline__ float bf_lo(unsigned w) { return __uint_as_float(w << 16); }
; __device__ __forceinline__ float bf_hi(unsigned w) { return __uint_as_float(w & 0xffff0000u); }
;     __device__ __forceinline__ void operator()(const f32x4 (&acc)[2][2][4][2], const Unit& u, int wr, int wc, int fr, int fq) const {
;     ...
;             for (int m = 0; m < 4; ++m) { const size_t row = (size_t)(row0 + ai * HALF + m * 16); float ss = 0.f;
; #pragma unroll
;                 for (int bj = 0; bj < 2; ++bj) { const size_t off = row * DM + col0 + bj * HALF;
;                     f32x4 v0 = acc[ai][bj][m][0] + *(const f32x4*)(base + off), v1 = acc[ai][bj][m][1] + *(const f32x4*)(base + off + 4);
;                     u32x4 w; w.x = cvt_pk_bf16(v0[0], v0[1]); w.y = cvt_pk_bf16(v0[2], v0[3]); w.z = cvt_pk_bf16(v1[0], v1[1]); w.w = cvt_pk_bf16(v1[2], v1[3]);
;                     *(u32x4*)(XN + off) = w;
;                     v0 = (f32x4){bf_lo(w.x), bf_hi(w.x), bf_lo(w.y), bf_hi(w.y)}; v1 = (f32x4){bf_lo(w.z), bf_hi(w.z), bf_lo(w.w), bf_hi(w.w)};
;                     ss += (v0[0] * v0[0] + v0[1] * v0[1]) + (v0[2] * v0[2] + v0[3] * v0[3]) + (v1[0] * v1[0] + v1[1] * v1[1]) + (v1[2] * v1[2] + v1[3] * v1[3]); }
	v_pk_add_f32 v[46:47], v[46:47], v[180:181]
	v_pk_add_f32 v[48:49], v[48:49], v[182:183]
	v_pk_add_f32 v[42:43], v[42:43], v[184:185]
	v_pk_add_f32 v[44:45], v[44:45], v[186:187]
	v_cvt_pk_bf16_f32 v180, v46, v47
	v_cvt_pk_bf16_f32 v181, v48, v49
	v_cvt_pk_bf16_f32 v182, v42, v43
	v_cvt_pk_bf16_f32 v183, v44, v45
	global_store_dwordx4 v[158:159], v[180:183], off
	v_lshlrev_b32_e32 v46, 16, v180
	v_lshlrev_b32_e32 v47, 16, v181
	v_and_b32_e32 v48, 0xffff0000, v180
	v_and_b32_e32 v49, 0xffff0000, v181
	v_mul_f32_e32 v48, v48, v48
	v_mul_f32_e32 v49, v49, v49
	v_lshlrev_b32_e32 v42, 16, v182
	v_and_b32_e32 v43, 0xffff0000, v182
	v_fmac_f32_e32 v48, v46, v46
	v_fmac_f32_e32 v49, v47, v47
	v_add_f32_e32 v48, v48, v49
	v_mul_f32_e32 v49, v43, v43
	v_lshlrev_b32_e32 v44, 16, v183
	v_and_b32_e32 v45, 0xffff0000, v183
	v_fmac_f32_e32 v49, v42, v42
	v_add_f32_e32 v48, v49, v48
	v_mul_f32_e32 v49, v45, v45
	v_fmac_f32_e32 v49, v44, v44
	v_add_f32_e32 v46, v49, v48
	s_waitcnt vmcnt(15)
	v_pk_add_f32 v[38:39], v[38:39], v[204:205]
	v_pk_add_f32 v[40:41], v[40:41], v[206:207]
	v_pk_add_f32 v[34:35], v[34:35], v[208:209]
	v_pk_add_f32 v[36:37], v[36:37], v[210:211]
	v_cvt_pk_bf16_f32 v204, v38, v39
	v_cvt_pk_bf16_f32 v205, v40, v41
	v_cvt_pk_bf16_f32 v206, v34, v35
	v_cvt_pk_bf16_f32 v207, v36, v37
	global_store_dwordx4 v[158:159], v[204:207], off offset:256
	v_lshlrev_b32_e32 v38, 16, v204
	v_lshlrev_b32_e32 v39, 16, v205
	v_and_b32_e32 v40, 0xffff0000, v204
	v_and_b32_e32 v41, 0xffff0000, v205
	v_mul_f32_e32 v40, v40, v40
	v_mul_f32_e32 v41, v41, v41
	v_lshlrev_b32_e32 v34, 16, v206
	v_and_b32_e32 v35, 0xffff0000, v206
	v_fmac_f32_e32 v40, v38, v38
	v_fmac_f32_e32 v41, v39, v39
	v_add_f32_e32 v40, v40, v41
	v_mul_f32_e32 v41, v35, v35
	v_lshlrev_b32_e32 v36, 16, v207
	v_and_b32_e32 v37, 0xffff0000, v207
	v_fmac_f32_e32 v41, v34, v34
	v_add_f32_e32 v40, v41, v40
	v_mul_f32_e32 v41, v37, v37
	v_fmac_f32_e32 v41, v36, v36
	v_add_f32_e32 v40, v41, v40
	v_add_f32_e32 v46, v46, v40
	s_mov_b32 s40, 0xa0000
	v_lshl_add_u64 v[158:159], v[244:245], 0, s[40:41]
	s_waitcnt vmcnt(12)
	v_pk_add_f32 v[30:31], v[30:31], v[212:213]
	v_pk_add_f32 v[32:33], v[32:33], v[214:215]
	v_pk_add_f32 v[26:27], v[26:27], v[216:217]
	v_pk_add_f32 v[28:29], v[28:29], v[218:219]
	v_cvt_pk_bf16_f32 v212, v30, v31
	v_cvt_pk_bf16_f32 v213, v32, v33
	v_cvt_pk_bf16_f32 v214, v26, v27
	v_cvt_pk_bf16_f32 v215, v28, v29
	global_store_dwordx4 v[158:159], v[212:215], off
	v_lshlrev_b32_e32 v30, 16, v212
	v_lshlrev_b32_e32 v31, 16, v213
	v_and_b32_e32 v32, 0xffff0000, v212
	v_and_b32_e32 v33, 0xffff0000, v213
	v_mul_f32_e32 v32, v32, v32
	v_mul_f32_e32 v33, v33, v33
	v_lshlrev_b32_e32 v26, 16, v214
	v_and_b32_e32 v27, 0xffff0000, v214
	v_fmac_f32_e32 v32, v30, v30
	v_fmac_f32_e32 v33, v31, v31
	v_add_f32_e32 v32, v32, v33
	v_mul_f32_e32 v33, v27, v27
	v_lshlrev_b32_e32 v28, 16, v215
	v_and_b32_e32 v29, 0xffff0000, v215
	v_fmac_f32_e32 v33, v26, v26
	v_add_f32_e32 v32, v33, v32
	v_mul_f32_e32 v33, v29, v29
	v_fmac_f32_e32 v33, v28, v28
	v_add_f32_e32 v30, v33, v32
	s_waitcnt vmcnt(11)
	v_pk_add_f32 v[22:23], v[22:23], v[220:221]
	v_pk_add_f32 v[24:25], v[24:25], v[222:223]
	v_pk_add_f32 v[18:19], v[18:19], v[224:225]
	v_pk_add_f32 v[20:21], v[20:21], v[226:227]
	v_cvt_pk_bf16_f32 v220, v22, v23
	v_cvt_pk_bf16_f32 v221, v24, v25
	v_cvt_pk_bf16_f32 v222, v18, v19
	v_cvt_pk_bf16_f32 v223, v20, v21
	global_store_dwordx4 v[158:159], v[220:223], off offset:256
	v_lshlrev_b32_e32 v22, 16, v220
	v_lshlrev_b32_e32 v23, 16, v221
	v_and_b32_e32 v24, 0xffff0000, v220
	v_and_b32_e32 v25, 0xffff0000, v221
	v_mul_f32_e32 v24, v24, v24
	v_mul_f32_e32 v25, v25, v25
	v_lshlrev_b32_e32 v18, 16, v222
	v_and_b32_e32 v19, 0xffff0000, v222
	v_fmac_f32_e32 v24, v22, v22
	v_fmac_f32_e32 v25, v23, v23
	v_add_f32_e32 v24, v24, v25
	v_mul_f32_e32 v25, v19, v19
	v_lshlrev_b32_e32 v20, 16, v223
	v_and_b32_e32 v21, 0xffff0000, v223
	v_fmac_f32_e32 v25, v18, v18
	v_add_f32_e32 v24, v25, v24
	v_mul_f32_e32 v25, v21, v21
	v_fmac_f32_e32 v25, v20, v20
	v_add_f32_e32 v24, v25, v24
	v_add_f32_e32 v30, v30, v24
	s_mov_b32 s40, 0xb0000
	v_lshl_add_u64 v[158:159], v[244:245], 0, s[40:41]
	s_waitcnt vmcnt(8)
; __device__ __forceinline__ unsigned cvt_pk_bf16(float lo, float hi) { const f32x2c_t v = {lo, hi}; const bf16x2c_t b = __builtin_convertvector(v, bf16x2c_t); return __builtin_bit_cast(unsigned, b); }
; __device__ __forceinline__ float bf_lo(unsigned w) { return __uint_as_float(w << 16); }
; __device__ __forceinline__ float bf_hi(unsigned w) { return __uint_as_float(w & 0xffff0000u); }
;     __device__ __forceinline__ void operator()(const f32x4 (&acc)[2][2][4][2], const Unit& u, int wr, int wc, int fr, int fq) const {
;     ...
;                 for (int bj = 0; bj < 2; ++bj) { const size_t off = row * DM + col0 + bj * HALF;
;                     f32x4 v0 = acc[ai][bj][m][0] + *(const f32x4*)(base + off), v1 = acc[ai][bj][m][1] + *(const f32x4*)(base + off + 4);
;                     u32x4 w; w.x = cvt_pk_bf16(v0[0], v0[1]); w.y = cvt_pk_bf16(v0[2], v0[3]); w.z = cvt_pk_bf16(v1[0], v1[1]); w.w = cvt_pk_bf16(v1[2], v1[3]);
;                     *(u32x4*)(XN + off) = w;
;                     v0 = (f32x4){bf_lo(w.x), bf_hi(w.x), bf_lo(w.y), bf_hi(w.y)}; v1 = (f32x4){bf_lo(w.z), bf_hi(w.z), bf_lo(w.w), bf_hi(w.w)};
;                     ss += (v0[0] * v0[0] + v0[1] * v0[1]) + (v0[2] * v0[2] + v0[3] * v0[3]) + (v1[0] * v1[0] + v1[1] * v1[1]) + (v1[2] * v1[2] + v1[3] * v1[3]); }
;                 ss += __shfl_xor(ss, 16); ss += __shfl_xor(ss, 32);
;                 if (fq == 0) SS[row * 32 + u.pn * 4 + wc] = ss; }
	v_pk_add_f32 v[14:15], v[14:15], v[228:229]
	v_pk_add_f32 v[16:17], v[16:17], v[230:231]
	v_pk_add_f32 v[10:11], v[10:11], v[232:233]
	v_pk_add_f32 v[12:13], v[12:13], v[234:235]
	v_cvt_pk_bf16_f32 v228, v14, v15
	v_cvt_pk_bf16_f32 v229, v16, v17
	v_cvt_pk_bf16_f32 v230, v10, v11
	v_cvt_pk_bf16_f32 v231, v12, v13
	global_store_dwordx4 v[158:159], v[228:231], off
	v_lshlrev_b32_e32 v14, 16, v228
	v_lshlrev_b32_e32 v15, 16, v229
	v_and_b32_e32 v16, 0xffff0000, v228
	v_and_b32_e32 v17, 0xffff0000, v229
	v_mul_f32_e32 v16, v16, v16
	v_mul_f32_e32 v17, v17, v17
	v_lshlrev_b32_e32 v10, 16, v230
	v_and_b32_e32 v11, 0xffff0000, v230
	v_fmac_f32_e32 v16, v14, v14
	v_fmac_f32_e32 v17, v15, v15
	v_add_f32_e32 v16, v16, v17
	v_mul_f32_e32 v17, v11, v11
	v_lshlrev_b32_e32 v12, 16, v231
	v_and_b32_e32 v13, 0xffff0000, v231
	v_fmac_f32_e32 v17, v10, v10
	v_add_f32_e32 v16, v17, v16
	v_mul_f32_e32 v17, v13, v13
	v_fmac_f32_e32 v17, v12, v12
	v_add_f32_e32 v14, v17, v16
	s_waitcnt vmcnt(7)
	v_pk_add_f32 v[6:7], v[6:7], v[236:237]
	v_pk_add_f32 v[8:9], v[8:9], v[238:239]
	v_pk_add_f32 v[2:3], v[2:3], v[240:241]
	v_pk_add_f32 v[4:5], v[4:5], v[242:243]
	v_cvt_pk_bf16_f32 v236, v6, v7
	v_cvt_pk_bf16_f32 v237, v8, v9
	v_cvt_pk_bf16_f32 v238, v2, v3
	v_cvt_pk_bf16_f32 v239, v4, v5
	global_store_dwordx4 v[158:159], v[236:239], off offset:256
	v_lshlrev_b32_e32 v6, 16, v236
	v_lshlrev_b32_e32 v7, 16, v237
	v_and_b32_e32 v8, 0xffff0000, v236
	v_and_b32_e32 v9, 0xffff0000, v237
	v_mul_f32_e32 v8, v8, v8
	v_mul_f32_e32 v9, v9, v9
	v_lshlrev_b32_e32 v2, 16, v238
	v_and_b32_e32 v3, 0xffff0000, v238
	v_fmac_f32_e32 v8, v6, v6
	v_fmac_f32_e32 v9, v7, v7
	v_add_f32_e32 v8, v8, v9
	v_mul_f32_e32 v9, v3, v3
	v_lshlrev_b32_e32 v4, 16, v239
	v_and_b32_e32 v5, 0xffff0000, v239
	v_fmac_f32_e32 v9, v2, v2
	v_add_f32_e32 v8, v9, v8
	v_mul_f32_e32 v9, v5, v5
	v_fmac_f32_e32 v9, v4, v4
	v_add_f32_e32 v8, v9, v8
	v_add_f32_e32 v14, v14, v8
	v_xor_b32_e32 v203, 16, v192
	v_xor_b32_e32 v157, 32, v192
	v_lshlrev_b32_e32 v203, 2, v203
	v_lshlrev_b32_e32 v157, 2, v157
	ds_bpermute_b32 v127, v203, v126
	ds_bpermute_b32 v111, v203, v110
	ds_bpermute_b32 v95, v203, v94
	ds_bpermute_b32 v79, v203, v78
	ds_bpermute_b32 v63, v203, v62
	ds_bpermute_b32 v47, v203, v46
	ds_bpermute_b32 v31, v203, v30
	ds_bpermute_b32 v15, v203, v14
	s_waitcnt lgkmcnt(0)
	v_add_f32_e32 v126, v126, v127
	v_add_f32_e32 v110, v110, v111
	v_add_f32_e32 v94, v94, v95
	v_add_f32_e32 v78, v78, v79
	v_add_f32_e32 v62, v62, v63
	v_add_f32_e32 v46, v46, v47
	v_add_f32_e32 v30, v30, v31
	v_add_f32_e32 v14, v14, v15
	ds_bpermute_b32 v127, v157, v126
	ds_bpermute_b32 v111, v157, v110
	ds_bpermute_b32 v95, v157, v94
	ds_bpermute_b32 v79, v157, v78
	ds_bpermute_b32 v63, v157, v62
	ds_bpermute_b32 v47, v157, v46
	ds_bpermute_b32 v31, v157, v30
	ds_bpermute_b32 v15, v157, v14
	s_waitcnt lgkmcnt(0)
	v_add_f32_e32 v126, v126, v127
	v_add_f32_e32 v110, v110, v111
	v_add_f32_e32 v94, v94, v95
	v_add_f32_e32 v78, v78, v79
	v_add_f32_e32 v62, v62, v63
	v_add_f32_e32 v46, v46, v47
	v_add_f32_e32 v30, v30, v31
	v_add_f32_e32 v14, v14, v15
	s_lshl_b32 s40, s54, 4
	s_lshl_b32 s41, s60, 2
	s_add_i32 s40, s40, s41
	s_addk_i32 s40, 0x1000
	v_lshl_add_u32 v246, v156, 7, s40
	v_add_u32_e32 v247, 0x4000, v246
	s_and_saveexec_b64 s[40:41], s[42:43]
	global_store_dword v246, v126, s[10:11] offset:-4096
	global_store_dword v246, v110, s[10:11] offset:-2048
	global_store_dword v246, v94, s[10:11]
	global_store_dword v246, v78, s[10:11] offset:2048
	global_store_dword v247, v62, s[10:11] offset:-4096
	global_store_dword v247, v46, s[10:11] offset:-2048
	global_store_dword v247, v30, s[10:11]
	global_store_dword v247, v14, s[10:11] offset:2048
	s_or_b64 exec, exec, s[40:41]
	s_andn2_b64 vcc, exec, s[44:45]
	s_mov_b64 s[40:41], -1
	s_cbranch_vccnz .LBB0_90
	s_andn2_b64 vcc, exec, s[0:1]
	s_cbranch_vccnz .LBB0_89
	s_barrier
	s_branch .LBB0_89

; #define LAS __attribute__((address_space(3)))
; template <int PASS> __device__ __forceinline__ void phase_lru(LAS unsigned char* lds, const bf16_t* Z, const bf16_t* WL, float* LSUM, const float* LCAR, bf16_t* RNN,
;                                                               int S, int tid, int lane, int wave, int G) {
;     ...
; #pragma unroll
;         for (int q = 0; q < 4; ++q)
; #pragma unroll
;             for (int s = 0; s < 4; ++s) wf[q][s] = *(const bf16x8*)(WL + ((size_t)((n * 4 + q) * 128 + wave * 16 + c)) * 128 + 32 * s + 8 * g4);
;         LAS f32x4* kc = (LAS f32x4*)(lds + LRU_KC + wave * 11264);
; #pragma unroll
;         for (int k = 0; k < 4; ++k) kc[(6 + k) * 64 + lane] = *(const f32x4*)(conv_w + k * LW + ch0);
;         kc[10 * 64 + lane] = *(const f32x4*)(conv_b + ch0);
; #pragma unroll
;         for (int d = 0; d < 2; ++d) { kc[(3 * d + 0) * 64 + lane] = *(const f32x4*)(lba + d * LW + ch0) * (-LOG2E); kc[(3 * d + 1) * 64 + lane] = *(const f32x4*)(lbx + d * LW + ch0) * (-LOG2E);
;             const f32x4 lv = *(const f32x4*)(lam + d * LW + ch0); f32x4 sp;
; #pragma unroll
;             for (int j = 0; j < 4; ++j) sp[j] = -8.0f * LOG2E * log1pf(expf(-lv[j]));
;             kc[(3 * d + 2) * 64 + lane] = sp; }
.LBB0_174:
	s_ashr_i32 s0, s30, 6
	v_lshl_add_u32 v2, s0, 9, v143
	v_ashrrev_i32_e32 v3, 31, v2
	s_lshl_b32 s58, s0, 7
	v_lshlrev_b64 v[4:5], 8, v[2:3]
	v_add_u32_e32 v20, 0x80, v2
	v_add_u32_e32 v36, 0x100, v2
	v_add_u32_e32 v2, 0x180, v2
	v_ashrrev_i32_e32 v21, 31, v20
	v_ashrrev_i32_e32 v37, 31, v36
	v_ashrrev_i32_e32 v3, 31, v2
	v_add_u32_e32 v80, s58, v111
	v_lshlrev_b64 v[20:21], 8, v[20:21]
	v_lshlrev_b64 v[36:37], 8, v[36:37]
	v_lshlrev_b64 v[2:3], 8, v[2:3]
	v_ashrrev_i32_e32 v81, 31, v80
	v_lshl_add_u64 v[16:17], v[108:109], 0, v[4:5]
	v_lshl_add_u64 v[32:33], v[108:109], 0, v[20:21]
	v_lshl_add_u64 v[48:49], v[108:109], 0, v[36:37]
	v_lshl_add_u64 v[2:3], v[108:109], 0, v[2:3]
	v_lshlrev_b64 v[82:83], 2, v[80:81]
	global_load_dwordx4 v[4:7], v[16:17], off
	global_load_dwordx4 v[8:11], v[16:17], off offset:64
	global_load_dwordx4 v[12:15], v[16:17], off offset:128
	s_nop 0
	global_load_dwordx4 v[16:19], v[16:17], off offset:192
	s_nop 0
	global_load_dwordx4 v[20:23], v[32:33], off
	global_load_dwordx4 v[24:27], v[32:33], off offset:64
	global_load_dwordx4 v[28:31], v[32:33], off offset:128
	s_nop 0
	global_load_dwordx4 v[32:35], v[32:33], off offset:192
	s_nop 0
	global_load_dwordx4 v[36:39], v[48:49], off
	global_load_dwordx4 v[40:43], v[48:49], off offset:64
	global_load_dwordx4 v[44:47], v[48:49], off offset:128
	s_nop 0
	global_load_dwordx4 v[48:51], v[48:49], off offset:192
	s_nop 0
	global_load_dwordx4 v[52:55], v[2:3], off
	global_load_dwordx4 v[56:59], v[2:3], off offset:64
	global_load_dwordx4 v[60:63], v[2:3], off offset:128
	global_load_dwordx4 v[64:67], v[2:3], off offset:192
	s_ashr_i32 s59, s58, 31
	v_add_u32_e32 v1, 0x1800, v82
	v_add_u32_e32 v2, 0x3000, v82
	v_add_u32_e32 v3, 0x4800, v82
	global_load_dwordx4 v[68:71], v82, s[4:5]
	global_load_dwordx4 v[72:75], v1, s[4:5]
	global_load_dwordx4 v[76:79], v2, s[4:5]
	global_load_dwordx4 v[84:87], v3, s[4:5]
	global_load_dwordx4 v[88:91], v82, s[12:13]
	global_load_dwordx4 v[92:95], v82, s[36:37]
	global_load_dwordx4 v[96:99], v82, s[94:95]
	global_load_dwordx4 v[100:103], v82, s[96:97]
	global_load_dwordx4 v[104:107], v1, s[36:37]
	global_load_dwordx4 v[114:117], v1, s[94:95]
	global_load_dwordx4 v[118:121], v1, s[96:97]
	s_mov_b32 s60, 0xc1000000
	s_waitcnt vmcnt(0)
	ds_write_b128 v203, v[68:71] offset:43008
	ds_write_b128 v203, v[72:75] offset:44032
	ds_write_b128 v203, v[76:79] offset:45056
	ds_write_b128 v203, v[84:87] offset:46080
	ds_write_b128 v203, v[88:91] offset:47104
	v_pk_mul_f32 v[92:93], v[92:93], s[24:25] op_sel_hi:[1,0]
	v_pk_mul_f32 v[94:95], v[94:95], s[24:25] op_sel_hi:[1,0]
	v_pk_mul_f32 v[96:97], v[96:97], s[24:25] op_sel_hi:[1,0]
	v_pk_mul_f32 v[98:99], v[98:99], s[24:25] op_sel_hi:[1,0]
	v_pk_mul_f32 v[104:105], v[104:105], s[24:25] op_sel_hi:[1,0]
	v_pk_mul_f32 v[106:107], v[106:107], s[24:25] op_sel_hi:[1,0]
	v_pk_mul_f32 v[114:115], v[114:115], s[24:25] op_sel_hi:[1,0]
	v_pk_mul_f32 v[116:117], v[116:117], s[24:25] op_sel_hi:[1,0]
	ds_write_b128 v203, v[92:95] offset:36864
	ds_write_b128 v203, v[96:99] offset:37888
	ds_write_b128 v203, v[104:107] offset:39936
	ds_write_b128 v203, v[114:117] offset:40960
	v_mul_f32_e32 v68, s24, v100
	v_mul_f32_e32 v69, s24, v101
	v_mul_f32_e32 v70, s24, v102
	v_mul_f32_e32 v71, s24, v103
	v_mul_f32_e32 v72, s24, v118
	v_mul_f32_e32 v73, s24, v119
	v_mul_f32_e32 v74, s24, v120
	v_mul_f32_e32 v75, s24, v121
	v_exp_f32_e32 v68, v68
	v_exp_f32_e32 v69, v69
	v_exp_f32_e32 v70, v70
	v_exp_f32_e32 v71, v71
	v_exp_f32_e32 v72, v72
	v_exp_f32_e32 v73, v73
	v_exp_f32_e32 v74, v74
	v_exp_f32_e32 v75, v75
	v_add_f32_e32 v76, 1.0, v68
	v_add_f32_e32 v77, 1.0, v69
	v_add_f32_e32 v78, 1.0, v70
	v_add_f32_e32 v79, 1.0, v71
	v_add_f32_e32 v84, 1.0, v72
	v_add_f32_e32 v85, 1.0, v73
	v_add_f32_e32 v86, 1.0, v74
	v_add_f32_e32 v87, 1.0, v75
	v_add_f32_e32 v88, -1.0, v76
	v_add_f32_e32 v89, -1.0, v77
	v_add_f32_e32 v90, -1.0, v78
	v_add_f32_e32 v91, -1.0, v79
	v_add_f32_e32 v92, -1.0, v84
	v_add_f32_e32 v93, -1.0, v85
	v_add_f32_e32 v94, -1.0, v86
	v_add_f32_e32 v95, -1.0, v87
	v_log_f32_e32 v76, v76
	v_log_f32_e32 v77, v77
	v_log_f32_e32 v78, v78
	v_log_f32_e32 v79, v79
	v_log_f32_e32 v84, v84
	v_log_f32_e32 v85, v85
	v_log_f32_e32 v86, v86
	v_log_f32_e32 v87, v87
	v_max_f32_e32 v88, 0x33800000, v88
	v_max_f32_e32 v89, 0x33800000, v89
	v_max_f32_e32 v90, 0x33800000, v90
	v_max_f32_e32 v91, 0x33800000, v91
	v_max_f32_e32 v92, 0x33800000, v92
	v_max_f32_e32 v93, 0x33800000, v93
	v_max_f32_e32 v94, 0x33800000, v94
	v_max_f32_e32 v95, 0x33800000, v95
	v_rcp_f32_e32 v88, v88
	v_rcp_f32_e32 v89, v89
	v_rcp_f32_e32 v90, v90
	v_rcp_f32_e32 v91, v91
	v_rcp_f32_e32 v92, v92
	v_rcp_f32_e32 v93, v93
	v_rcp_f32_e32 v94, v94
	v_rcp_f32_e32 v95, v95
	v_mul_f32_e32 v68, v68, v88
	v_mul_f32_e32 v69, v69, v89
	v_mul_f32_e32 v70, v70, v90
	v_mul_f32_e32 v71, v71, v91
	v_mul_f32_e32 v72, v72, v92
	v_mul_f32_e32 v73, v73, v93
	v_mul_f32_e32 v74, v74, v94
	v_mul_f32_e32 v75, v75, v95
	v_mul_f32_e32 v76, v76, v68
	v_mul_f32_e32 v77, v77, v69
	v_mul_f32_e32 v78, v78, v70
	v_mul_f32_e32 v79, v79, v71
	v_mul_f32_e32 v84, v84, v72
	v_mul_f32_e32 v85, v85, v73
	v_mul_f32_e32 v86, v86, v74
	v_mul_f32_e32 v87, v87, v75
	v_mul_f32_e32 v100, s60, v76
	v_mul_f32_e32 v101, s60, v77
	v_mul_f32_e32 v102, s60, v78
	v_mul_f32_e32 v103, s60, v79
	v_mul_f32_e32 v118, s60, v84
	v_mul_f32_e32 v119, s60, v85
	v_mul_f32_e32 v120, s60, v86
	v_mul_f32_e32 v121, s60, v87
	ds_write_b128 v203, v[100:103] offset:38912
	ds_write_b128 v203, v[118:121] offset:41984
	v_lshlrev_b32_e32 v84, 1, v110
	s_lshl_b32 s0, s30, 8
	s_and_b32 s28, s0, 0x3f00
	s_and_b32 s34, s28, s18
	s_add_i32 s34, s34, -2
	v_add_u32_e32 v1, s34, v205
	v_mov_b32_e32 v2, v0
	v_mov_b32_e32 v3, v0
	v_cmp_gt_u32_e32 vcc, s62, v1
	v_mov_b32_e32 v1, v0
	v_mov_b64_e32 v[70:71], v[2:3]
	s_add_i32 s28, s28, -2
	s_and_b64 s[46:47], s[40:41], vcc
	v_mov_b64_e32 v[68:69], v[0:1]
	s_and_saveexec_b64 s[0:1], s[46:47]
	s_cbranch_execz .LBB0_176
	v_add_u32_e32 v70, s28, v205
	v_mov_b64_e32 v[68:69], s[92:93]
	v_mad_i64_i32 v[68:69], s[46:47], v70, s27, v[68:69]
	v_lshl_add_u64 v[68:69], s[58:59], 1, v[68:69]
	v_mov_b32_e32 v85, v0
	v_lshl_add_u64 v[68:69], v[68:69], 0, v[84:85]
	v_add_co_u32_e32 v68, vcc, 0x2000, v68
	s_nop 1
	v_addc_co_u32_e32 v69, vcc, 0, v69, vcc
	global_load_dwordx4 v[68:71], v[68:69], off offset:1024

; #define LAS __attribute__((address_space(3)))
; __device__ __forceinline__ void phase_attn(LAS unsigned char* lds, const bf16_t* Z, const float* rel_bias, bf16_t* OG, float* LSE, int S, int tid, int lane, int wave, int G) {
;     ...
;     for (int item = blockIdx.x; item < 3 * PER_GRP; item += G) {
;         const int grp = item / PER_GRP; int idx = item % PER_GRP;
;         const int sh = 2 * grp, L = S >> sh, nblk = L >> 7;
;         const int blk = idx % nblk; idx /= nblk; const int h = idx & 3; idx >>= 2; const int r = idx & ((1 << sh) - 1); const int b = idx >> sh;
;         const int head = grp * 4 + h, i0 = blk * 128;
;         const size_t rowbase = (size_t)b * S + r;
;         const bf16_t* Zq = Z + C_Q + head * 128; const bf16_t* Zk = Z + C_K + head * 128; const bf16_t* Zv = Z + C_V + head * 128;
; #pragma unroll
;         for (int q = 0; q < 8; ++q) {
;             const int br = 32 * wave + 4 * q + (lane >> 4); int fi = i0 - 64 + br; fi = fi < 0 ? 0 : (fi > L - 1 ? L - 1 : fi);
;             const int ch = (lane & 15) ^ (((br & 3) << 2) | ((br >> 2) & 3));
;             const size_t go = (rowbase + ((size_t)fi << sh)) * DIN + 8 * ch;
;             __builtin_amdgcn_global_load_lds((const unsigned*)(Zk + go), (LAS unsigned*)(lds + (32 * wave + 4 * q) * 256), 16, 0, 0);
;             __builtin_amdgcn_global_load_lds((const unsigned*)(Zv + go), (LAS unsigned*)(lds + 65536 + (32 * wave + 4 * q) * 256), 16, 0, 0);
;         }
;         const int q0 = i0 + 16 * wave;
;         bf16x8 qf[4];
; #pragma unroll
;         for (int s = 0; s < 4; ++s) qf[s] = *(const bf16x8*)(Zq + (rowbase + ((size_t)(q0 + c) << sh)) * DIN + 32 * s + 8 * g4);
;         __syncthreads();
.LBB0_247:
	s_ashr_i32 s0, s63, 31
	s_lshr_b32 s0, s0, 23
	s_add_i32 s1, s63, s0
	s_ashr_i32 s0, s1, 9
	s_and_b32 s1, s1, 0xfffffe00
	s_lshl_b32 s73, s0, 1
	s_sub_i32 s10, s63, s1
	s_lshr_b32 s1, s62, s73
	s_lshr_b32 s11, s1, 7
	v_cvt_f32_i32_e32 v3, s11
	s_sext_i32_i16 s4, s10
	v_cvt_f32_i32_e32 v2, s4
	s_ashr_i32 s5, s4, 30
	v_rcp_iflag_f32_e32 v4, v3
	s_or_b32 s12, s5, 1
	v_mov_b32_e32 v61, v0
	v_mul_f32_e32 v4, v2, v4
	v_trunc_f32_e32 v4, v4
	v_fma_f32 v2, -v4, v3, v2
	v_cvt_i32_f32_e32 v4, v4
	v_cmp_ge_f32_e64 s[4:5], |v2|, v3
	s_and_b64 s[4:5], s[4:5], exec
	s_cselect_b32 s4, s12, 0
	v_readfirstlane_b32 s5, v4
	s_add_i32 s4, s5, s4
	s_sext_i32_i16 s5, s4
	s_mul_i32 s4, s4, s11
	s_sub_i32 s4, s10, s4
	s_sext_i32_i16 s10, s4
	s_and_b32 s67, s5, 3
	s_ashr_i32 s4, s5, 2
	s_lshl_b32 s5, -1, s73
	s_andn2_b32 s11, s4, s5
	s_ashr_i32 s4, s4, s73
	s_lshl_b32 s5, s0, 2
	s_or_b32 s54, s67, s5
	s_ashr_i32 s5, s4, 31
	s_lshl_b32 s78, s10, 7
	s_lshl_b64 s[4:5], s[4:5], s60
	s_add_u32 s4, s4, s11
	s_addc_u32 s5, s5, 0
	s_lshl_b32 s10, s54, 7
	s_ashr_i32 s11, s10, 31
	s_lshl_b64 s[10:11], s[10:11], 1
	s_add_u32 s12, s28, s10
	s_addc_u32 s13, s30, s11
	s_add_u32 s18, s34, s10
	s_addc_u32 s19, s36, s11
	s_sub_i32 s76, s78, 64
	s_add_i32 s77, s1, -1
	v_add_u32_e32 v2, s76, v53
	v_min_i32_e32 v3, s77, v2
	v_cmp_lt_i32_e32 vcc, -1, v2
	s_add_i32 m0, s43, 0
	s_mulk_i32 s54, 0x300
	v_cndmask_b32_e32 v2, 0, v3, vcc
	v_ashrrev_i32_e32 v3, 31, v2
	v_lshlrev_b64 v[2:3], s73, v[2:3]
	v_lshl_add_u64 v[2:3], v[2:3], 0, s[4:5]
	v_mad_u64_u32 v[4:5], s[84:85], v2, s31, 0
	v_mov_b32_e32 v2, v5
	v_mad_u64_u32 v[2:3], s[84:85], v3, s31, v[2:3]
	v_or_b32_e32 v4, v4, v52
	v_mov_b32_e32 v5, v2
	v_lshlrev_b64 v[2:3], 1, v[4:5]
	v_lshl_add_u64 v[4:5], s[12:13], 0, v[2:3]
	global_load_lds_dwordx4 v[4:5], off
	v_lshl_add_u64 v[2:3], s[18:19], 0, v[2:3]
	s_add_i32 m0, s42, s43
	s_nop 0
	global_load_lds_dwordx4 v[2:3], off
	v_add_u32_e32 v2, s76, v64
	v_min_i32_e32 v3, s77, v2
	v_cmp_lt_i32_e32 vcc, -1, v2
	s_add_i32 m0, s44, 0
	s_nop 0
	v_cndmask_b32_e32 v2, 0, v3, vcc
	v_ashrrev_i32_e32 v3, 31, v2
	v_lshlrev_b64 v[2:3], s73, v[2:3]
	v_lshl_add_u64 v[2:3], v[2:3], 0, s[4:5]
	v_mad_u64_u32 v[4:5], s[84:85], v2, s31, v[54:55]
	v_mov_b32_e32 v2, v5
	v_mad_u64_u32 v[2:3], s[84:85], v3, s31, v[2:3]
	v_mov_b32_e32 v5, v2
	v_lshlrev_b64 v[2:3], 1, v[4:5]
	v_lshl_add_u64 v[4:5], s[12:13], 0, v[2:3]
	global_load_lds_dwordx4 v[4:5], off
	v_lshl_add_u64 v[2:3], s[18:19], 0, v[2:3]
	s_add_i32 m0, s42, s44
	s_nop 0
	global_load_lds_dwordx4 v[2:3], off
	v_add_u32_e32 v2, s76, v65
	v_min_i32_e32 v3, s77, v2
	v_cmp_lt_i32_e32 vcc, -1, v2
	s_add_i32 m0, s45, 0
	s_nop 0
	v_cndmask_b32_e32 v2, 0, v3, vcc
	v_ashrrev_i32_e32 v3, 31, v2
	v_lshlrev_b64 v[2:3], s73, v[2:3]
	v_lshl_add_u64 v[2:3], v[2:3], 0, s[4:5]
	v_mad_u64_u32 v[4:5], s[84:85], v2, s31, v[56:57]
	v_mov_b32_e32 v2, v5
	v_mad_u64_u32 v[2:3], s[84:85], v3, s31, v[2:3]
	v_mov_b32_e32 v5, v2
	v_lshlrev_b64 v[2:3], 1, v[4:5]
	v_lshl_add_u64 v[4:5], s[12:13], 0, v[2:3]
	global_load_lds_dwordx4 v[4:5], off
	v_lshl_add_u64 v[2:3], s[18:19], 0, v[2:3]
	s_add_i32 m0, s42, s45
	s_nop 0
	global_load_lds_dwordx4 v[2:3], off
	v_add_u32_e32 v2, s76, v66
	v_min_i32_e32 v3, s77, v2
	v_cmp_lt_i32_e32 vcc, -1, v2
	s_add_i32 m0, s46, 0
	s_nop 0
	v_cndmask_b32_e32 v2, 0, v3, vcc
	v_ashrrev_i32_e32 v3, 31, v2
	v_lshlrev_b64 v[2:3], s73, v[2:3]
	v_lshl_add_u64 v[2:3], v[2:3], 0, s[4:5]
	v_mad_u64_u32 v[4:5], s[84:85], v2, s31, v[58:59]
	v_mov_b32_e32 v2, v5
	v_mad_u64_u32 v[2:3], s[84:85], v3, s31, v[2:3]
	v_mov_b32_e32 v5, v2
	v_lshlrev_b64 v[2:3], 1, v[4:5]
	v_lshl_add_u64 v[4:5], s[12:13], 0, v[2:3]
	global_load_lds_dwordx4 v[4:5], off
	v_lshl_add_u64 v[2:3], s[18:19], 0, v[2:3]
	s_add_i32 m0, s42, s46
	s_nop 0
	global_load_lds_dwordx4 v[2:3], off
	v_add_u32_e32 v2, s76, v67
	v_min_i32_e32 v3, s77, v2
	v_cmp_lt_i32_e32 vcc, -1, v2
	s_add_i32 m0, s47, 0
	s_nop 0
	v_cndmask_b32_e32 v2, 0, v3, vcc
	v_ashrrev_i32_e32 v3, 31, v2
	v_lshlrev_b64 v[2:3], s73, v[2:3]
	v_lshl_add_u64 v[2:3], v[2:3], 0, s[4:5]
	v_mad_u64_u32 v[4:5], s[84:85], v2, s31, 0
	v_mov_b32_e32 v2, v5
	v_mad_u64_u32 v[2:3], s[84:85], v3, s31, v[2:3]
	v_or_b32_e32 v4, v4, v52
	v_mov_b32_e32 v5, v2
	v_lshlrev_b64 v[2:3], 1, v[4:5]
	v_lshl_add_u64 v[4:5], s[12:13], 0, v[2:3]
	global_load_lds_dwordx4 v[4:5], off
	v_lshl_add_u64 v[2:3], s[18:19], 0, v[2:3]
	s_add_i32 m0, s42, s47
	s_nop 0
	global_load_lds_dwordx4 v[2:3], off
	v_add_u32_e32 v2, s76, v68
	v_min_i32_e32 v3, s77, v2
	v_cmp_lt_i32_e32 vcc, -1, v2
	s_add_i32 m0, s57, 0
	s_nop 0
	v_cndmask_b32_e32 v2, 0, v3, vcc
	v_ashrrev_i32_e32 v3, 31, v2
	v_lshlrev_b64 v[2:3], s73, v[2:3]
	v_lshl_add_u64 v[2:3], v[2:3], 0, s[4:5]
	v_mad_u64_u32 v[4:5], s[84:85], v2, s31, v[54:55]
	v_mov_b32_e32 v2, v5
	v_mad_u64_u32 v[2:3], s[84:85], v3, s31, v[2:3]
	v_mov_b32_e32 v5, v2
	v_lshlrev_b64 v[2:3], 1, v[4:5]
	v_lshl_add_u64 v[4:5], s[12:13], 0, v[2:3]
	global_load_lds_dwordx4 v[4:5], off
	v_lshl_add_u64 v[2:3], s[18:19], 0, v[2:3]
	s_add_i32 m0, s42, s57
	s_nop 0
	global_load_lds_dwordx4 v[2:3], off
	v_add_u32_e32 v2, s76, v69
	v_min_i32_e32 v3, s77, v2
	v_cmp_lt_i32_e32 vcc, -1, v2
	s_add_i32 m0, s58, 0
	s_nop 0
	v_cndmask_b32_e32 v2, 0, v3, vcc
	v_ashrrev_i32_e32 v3, 31, v2
	v_lshlrev_b64 v[2:3], s73, v[2:3]
	v_lshl_add_u64 v[2:3], v[2:3], 0, s[4:5]
	v_mad_u64_u32 v[4:5], s[84:85], v2, s31, v[56:57]
	v_mov_b32_e32 v2, v5
	v_mad_u64_u32 v[2:3], s[84:85], v3, s31, v[2:3]
	v_mov_b32_e32 v5, v2
	v_lshlrev_b64 v[2:3], 1, v[4:5]
	v_lshl_add_u64 v[4:5], s[12:13], 0, v[2:3]
	global_load_lds_dwordx4 v[4:5], off
	v_lshl_add_u64 v[2:3], s[18:19], 0, v[2:3]
	s_add_i32 m0, s42, s58
	s_nop 0
	global_load_lds_dwordx4 v[2:3], off
	v_add_u32_e32 v2, s76, v70
	v_min_i32_e32 v3, s77, v2
	v_cmp_lt_i32_e32 vcc, -1, v2
	s_add_i32 m0, s59, 0
	s_nop 0
	v_cndmask_b32_e32 v2, 0, v3, vcc
	v_ashrrev_i32_e32 v3, 31, v2
	v_lshlrev_b64 v[2:3], s73, v[2:3]
	v_lshl_add_u64 v[2:3], v[2:3], 0, s[4:5]
	v_mad_u64_u32 v[4:5], s[84:85], v2, s31, v[58:59]
	v_mov_b32_e32 v2, v5
	v_mad_u64_u32 v[2:3], s[84:85], v3, s31, v[2:3]
	v_mov_b32_e32 v5, v2
	v_lshlrev_b64 v[2:3], 1, v[4:5]
	v_lshl_add_u64 v[4:5], s[12:13], 0, v[2:3]
	global_load_lds_dwordx4 v[4:5], off
	s_add_i32 m0, s42, s59
	s_add_u32 s12, s92, s10
	v_lshl_add_u64 v[2:3], s[18:19], 0, v[2:3]
	s_addc_u32 s13, s93, s11
	s_add_i32 s10, s78, s37
	global_load_lds_dwordx4 v[2:3], off
	v_or_b32_e32 v2, s10, v103
	v_ashrrev_i32_e32 v3, 31, v2
	v_lshlrev_b64 v[2:3], s73, v[2:3]
	v_lshl_add_u64 v[62:63], s[4:5], 0, v[2:3]
	v_mov_b64_e32 v[2:3], s[12:13]
	v_mad_u64_u32 v[2:3], s[4:5], v62, s27, v[2:3]
	v_mov_b32_e32 v4, v3
	v_mad_u64_u32 v[4:5], s[4:5], v63, s27, v[4:5]
	v_mov_b32_e32 v3, v4
	v_lshl_add_u64 v[2:3], v[2:3], 0, v[60:61]
	global_load_dwordx4 v[46:49], v[2:3], off
	global_load_dwordx4 v[42:45], v[2:3], off offset:64
	global_load_dwordx4 v[38:41], v[2:3], off offset:128
	global_load_dwordx4 v[34:37], v[2:3], off offset:192
	s_waitcnt vmcnt(0) lgkmcnt(0)
	s_barrier
; #define LAS __attribute__((address_space(3)))
; __device__ __forceinline__ void phase_attn(LAS unsigned char* lds, const bf16_t* Z, const float* rel_bias, bf16_t* OG, float* LSE, int S, int tid, int lane, int wave, int G) {
;     ...
;         for (int kt = 0; kt < 9; ++kt) { f32x4 acc = (f32x4){0.f, 0.f, 0.f, 0.f};
; #pragma unroll
;             for (int s = 0; s < 4; ++s) { const bf16x8 kf = *(const LAS bf16x8*)(lds + off_b(w16 + 16 * kt + c, 4 * s + g4));
;                 acc = __builtin_amdgcn_mfma_f32_16x16x32_bf16(kf, qf[s], acc, 0, 0, 0); }
;             sa[kt] = acc; }
;         const LAS float* tb = tab + head * 192 + 95 - 64 - c;
;         const bool edge = (q0 < 64) || (q0 + 80 > L);
; #pragma unroll
;         for (int kt = 0; kt < 9; ++kt) { const f32x4 bv = *(const LAS f32x4*)(tb + 16 * kt + 4 * g4); sa[kt] = sa[kt] + bv; }
	s_add_i32 s4, s10, 0x50
	s_cmp_gt_i32 s4, s1
	s_cselect_b64 s[4:5], -1, 0
	s_cmp_lt_i32 s10, 64
	s_cselect_b64 s[12:13], -1, 0
	s_or_b64 s[4:5], s[12:13], s[4:5]
	v_add_u32_e32 v250, s54, v92
	ds_read_b128 v[162:165], v250 offset:124
	ds_read_b128 v[166:169], v250 offset:188
	ds_read_b128 v[170:173], v250 offset:252
	ds_read_b128 v[174:177], v250 offset:316
	ds_read_b128 v[178:181], v250 offset:380
	ds_read_b128 v[182:185], v250 offset:444
	ds_read_b128 v[236:239], v250 offset:508
	ds_read_b128 v[204:207], v93
	ds_read_b128 v[208:211], v94
	ds_read_b128 v[212:215], v95
	ds_read_b128 v[216:219], v96
	ds_read_b128 v[220:223], v93 offset:4096
	ds_read_b128 v[224:227], v94 offset:4096
	ds_read_b128 v[228:231], v95 offset:4096
	ds_read_b128 v[232:235], v96 offset:4096
	s_andn2_b64 vcc, exec, s[4:5]
	s_waitcnt lgkmcnt(7)
	v_mfma_f32_16x16x32_bf16 v[30:33], v[204:207], v[46:49], 0
	s_waitcnt lgkmcnt(6)
	v_mfma_f32_16x16x32_bf16 v[30:33], v[208:211], v[42:45], v[30:33]
	s_waitcnt lgkmcnt(5)
	v_mfma_f32_16x16x32_bf16 v[30:33], v[212:215], v[38:41], v[30:33]
	s_waitcnt lgkmcnt(4)
	v_mfma_f32_16x16x32_bf16 v[30:33], v[216:219], v[34:37], v[30:33]
	ds_read_b128 v[204:207], v93 offset:8192
	ds_read_b128 v[208:211], v94 offset:8192
	ds_read_b128 v[212:215], v95 offset:8192
	ds_read_b128 v[216:219], v96 offset:8192
	s_waitcnt lgkmcnt(7)
	v_mfma_f32_16x16x32_bf16 v[26:29], v[220:223], v[46:49], 0
	s_waitcnt lgkmcnt(6)
	v_mfma_f32_16x16x32_bf16 v[26:29], v[224:227], v[42:45], v[26:29]
	s_waitcnt lgkmcnt(5)
	v_mfma_f32_16x16x32_bf16 v[26:29], v[228:231], v[38:41], v[26:29]
	s_waitcnt lgkmcnt(4)
	v_mfma_f32_16x16x32_bf16 v[26:29], v[232:235], v[34:37], v[26:29]
	ds_read_b128 v[220:223], v93 offset:12288
	ds_read_b128 v[224:227], v94 offset:12288
	ds_read_b128 v[228:231], v95 offset:12288
	ds_read_b128 v[232:235], v96 offset:12288
	s_waitcnt lgkmcnt(7)
	v_mfma_f32_16x16x32_bf16 v[22:25], v[204:207], v[46:49], 0
	s_waitcnt lgkmcnt(6)
	v_mfma_f32_16x16x32_bf16 v[22:25], v[208:211], v[42:45], v[22:25]
	s_waitcnt lgkmcnt(5)
	v_mfma_f32_16x16x32_bf16 v[22:25], v[212:215], v[38:41], v[22:25]
	s_waitcnt lgkmcnt(4)
	v_mfma_f32_16x16x32_bf16 v[22:25], v[216:219], v[34:37], v[22:25]
	ds_read_b128 v[204:207], v93 offset:16384
	ds_read_b128 v[208:211], v94 offset:16384
	ds_read_b128 v[212:215], v95 offset:16384
	ds_read_b128 v[216:219], v96 offset:16384
	s_waitcnt lgkmcnt(7)
	v_mfma_f32_16x16x32_bf16 v[18:21], v[220:223], v[46:49], 0
	s_waitcnt lgkmcnt(6)
	v_mfma_f32_16x16x32_bf16 v[18:21], v[224:227], v[42:45], v[18:21]
	s_waitcnt lgkmcnt(5)
	v_mfma_f32_16x16x32_bf16 v[18:21], v[228:231], v[38:41], v[18:21]
	s_waitcnt lgkmcnt(4)
	v_mfma_f32_16x16x32_bf16 v[18:21], v[232:235], v[34:37], v[18:21]
	ds_read_b128 v[220:223], v93 offset:20480
	ds_read_b128 v[224:227], v94 offset:20480
	ds_read_b128 v[228:231], v95 offset:20480
	ds_read_b128 v[232:235], v96 offset:20480
	s_waitcnt lgkmcnt(7)
	v_mfma_f32_16x16x32_bf16 v[14:17], v[204:207], v[46:49], 0
	s_waitcnt lgkmcnt(6)
	v_mfma_f32_16x16x32_bf16 v[14:17], v[208:211], v[42:45], v[14:17]
	s_waitcnt lgkmcnt(5)
	v_mfma_f32_16x16x32_bf16 v[14:17], v[212:215], v[38:41], v[14:17]
	s_waitcnt lgkmcnt(4)
	v_mfma_f32_16x16x32_bf16 v[14:17], v[216:219], v[34:37], v[14:17]
	ds_read_b128 v[204:207], v93 offset:24576
	ds_read_b128 v[208:211], v94 offset:24576
	ds_read_b128 v[212:215], v95 offset:24576
	ds_read_b128 v[216:219], v96 offset:24576
	s_waitcnt lgkmcnt(7)
	v_mfma_f32_16x16x32_bf16 v[10:13], v[220:223], v[46:49], 0
	s_waitcnt lgkmcnt(6)
	v_mfma_f32_16x16x32_bf16 v[10:13], v[224:227], v[42:45], v[10:13]
	s_waitcnt lgkmcnt(5)
	v_mfma_f32_16x16x32_bf16 v[10:13], v[228:231], v[38:41], v[10:13]
	s_waitcnt lgkmcnt(4)
	v_mfma_f32_16x16x32_bf16 v[10:13], v[232:235], v[34:37], v[10:13]
	ds_read_b128 v[220:223], v93 offset:28672
	ds_read_b128 v[224:227], v94 offset:28672
	ds_read_b128 v[228:231], v95 offset:28672
	ds_read_b128 v[232:235], v96 offset:28672
	s_waitcnt lgkmcnt(7)
	v_mfma_f32_16x16x32_bf16 v[6:9], v[204:207], v[46:49], 0
	s_waitcnt lgkmcnt(6)
	v_mfma_f32_16x16x32_bf16 v[6:9], v[208:211], v[42:45], v[6:9]
	s_waitcnt lgkmcnt(5)
	v_mfma_f32_16x16x32_bf16 v[6:9], v[212:215], v[38:41], v[6:9]
	s_waitcnt lgkmcnt(4)
	v_mfma_f32_16x16x32_bf16 v[6:9], v[216:219], v[34:37], v[6:9]
	ds_read_b128 v[204:207], v93 offset:32768
	ds_read_b128 v[208:211], v94 offset:32768
	ds_read_b128 v[212:215], v95 offset:32768
	ds_read_b128 v[216:219], v96 offset:32768
	s_waitcnt lgkmcnt(7)
	v_mfma_f32_16x16x32_bf16 v[2:5], v[220:223], v[46:49], 0
	s_waitcnt lgkmcnt(6)
	v_mfma_f32_16x16x32_bf16 v[2:5], v[224:227], v[42:45], v[2:5]
	s_waitcnt lgkmcnt(5)
	v_mfma_f32_16x16x32_bf16 v[2:5], v[228:231], v[38:41], v[2:5]
	s_waitcnt lgkmcnt(4)
	v_mfma_f32_16x16x32_bf16 v[2:5], v[232:235], v[34:37], v[2:5]
	ds_read_b128 v[240:243], v250 offset:572
	ds_read_b128 v[244:247], v250 offset:636
	s_waitcnt lgkmcnt(5)
	v_mfma_f32_16x16x32_bf16 v[46:49], v[204:207], v[46:49], 0
	s_waitcnt lgkmcnt(4)
	v_mfma_f32_16x16x32_bf16 v[42:45], v[208:211], v[42:45], v[46:49]
	s_waitcnt lgkmcnt(3)
	v_mfma_f32_16x16x32_bf16 v[38:41], v[212:215], v[38:41], v[42:45]
	s_waitcnt lgkmcnt(2)
	v_mfma_f32_16x16x32_bf16 v[34:37], v[216:219], v[34:37], v[38:41]
	s_waitcnt lgkmcnt(0)
	v_pk_add_f32 v[32:33], v[32:33], v[164:165]
	v_pk_add_f32 v[30:31], v[30:31], v[162:163]
	v_pk_add_f32 v[28:29], v[28:29], v[168:169]
	v_pk_add_f32 v[26:27], v[26:27], v[166:167]
	v_pk_add_f32 v[24:25], v[24:25], v[172:173]
	v_pk_add_f32 v[22:23], v[22:23], v[170:171]
	v_pk_add_f32 v[20:21], v[20:21], v[176:177]
	v_pk_add_f32 v[18:19], v[18:19], v[174:175]
	v_pk_add_f32 v[16:17], v[16:17], v[180:181]
	v_pk_add_f32 v[14:15], v[14:15], v[178:179]
	v_pk_add_f32 v[12:13], v[12:13], v[184:185]
	v_pk_add_f32 v[10:11], v[10:11], v[182:183]
	v_pk_add_f32 v[8:9], v[8:9], v[238:239]
	v_pk_add_f32 v[6:7], v[6:7], v[236:237]
	v_pk_add_f32 v[4:5], v[4:5], v[242:243]
	v_pk_add_f32 v[2:3], v[2:3], v[240:241]
	s_nop 7
	v_pk_add_f32 v[36:37], v[36:37], v[246:247]
	v_pk_add_f32 v[34:35], v[34:35], v[244:245]
	s_cbranch_vccnz .LBB0_249
; #define LAS __attribute__((address_space(3)))
; __device__ __forceinline__ void phase_attn(LAS unsigned char* lds, const bf16_t* Z, const float* rel_bias, bf16_t* OG, float* LSE, int S, int tid, int lane, int wave, int G) {
;     ...
;         const bool edge = (q0 < 64) || (q0 + 80 > L);
; #pragma unroll
;         for (int kt = 0; kt < 9; ++kt) { const f32x4 bv = *(const LAS f32x4*)(tb + 16 * kt + 4 * g4); sa[kt] = sa[kt] + bv; }
;         if (edge) {
; #pragma unroll
;             for (int kt = 0; kt < 9; ++kt)
; #pragma unroll
;                 for (int j = 0; j < 4; ++j) { const int fi = q0 - 64 + 16 * kt + 4 * g4 + j; if (fi < 0 || fi >= L) sa[kt][j] = -1e30f; }
;         }
	s_cmp_gt_i32 s10, 63
	v_add_u32_e32 v39, s10, v84
	s_cselect_b64 s[4:5], -1, 0
	v_cmp_gt_i32_e32 vcc, s1, v39
	s_mov_b32 s11, 0xf149f2ca
	v_mov_b32_e32 v38, s11
	s_and_b64 vcc, s[4:5], vcc
	v_cndmask_b32_e32 v30, v38, v30, vcc
	v_or_b32_e32 v38, 1, v39
	v_cmp_gt_i32_e32 vcc, s1, v38
	s_and_b64 vcc, s[4:5], vcc
	v_or_b32_e32 v38, 2, v39
	v_cndmask_b32_e32 v31, v200, v31, vcc
	v_cmp_gt_i32_e32 vcc, s1, v38
	s_and_b64 vcc, s[4:5], vcc
	v_or_b32_e32 v38, 3, v39
	v_cndmask_b32_e32 v32, v200, v32, vcc
	v_cmp_gt_i32_e32 vcc, s1, v38
	s_and_b64 vcc, s[4:5], vcc
	s_cmp_gt_i32 s10, 47
	v_add_u32_e32 v39, s10, v85
	v_cndmask_b32_e32 v33, v200, v33, vcc
	s_cselect_b64 s[4:5], -1, 0
	v_cmp_gt_i32_e32 vcc, s1, v39
	v_mov_b32_e32 v38, s11
	s_and_b64 vcc, s[4:5], vcc
	v_cndmask_b32_e32 v26, v38, v26, vcc
	v_or_b32_e32 v38, 1, v39
	v_cmp_gt_i32_e32 vcc, s1, v38
	s_and_b64 vcc, s[4:5], vcc
	v_or_b32_e32 v38, 2, v39
	v_cndmask_b32_e32 v27, v200, v27, vcc
	v_cmp_gt_i32_e32 vcc, s1, v38
	s_and_b64 vcc, s[4:5], vcc
	v_or_b32_e32 v38, 3, v39
	v_cndmask_b32_e32 v28, v200, v28, vcc
	v_cmp_gt_i32_e32 vcc, s1, v38
	s_and_b64 vcc, s[4:5], vcc
	s_cmp_gt_i32 s10, 31
	v_add_u32_e32 v39, s10, v86
	v_cndmask_b32_e32 v29, v200, v29, vcc
	s_cselect_b64 s[4:5], -1, 0
	v_cmp_gt_i32_e32 vcc, s1, v39
	v_mov_b32_e32 v38, s11
	s_and_b64 vcc, s[4:5], vcc
	v_cndmask_b32_e32 v22, v38, v22, vcc
	v_or_b32_e32 v38, 1, v39
	v_cmp_gt_i32_e32 vcc, s1, v38
	s_and_b64 vcc, s[4:5], vcc
	v_or_b32_e32 v38, 2, v39
	v_cndmask_b32_e32 v23, v200, v23, vcc
	v_cmp_gt_i32_e32 vcc, s1, v38
	s_and_b64 vcc, s[4:5], vcc
	v_or_b32_e32 v38, 3, v39
	v_cndmask_b32_e32 v24, v200, v24, vcc
	v_cmp_gt_i32_e32 vcc, s1, v38
	s_and_b64 vcc, s[4:5], vcc
	s_cmp_gt_i32 s10, 15
	v_add_u32_e32 v39, s10, v87
	v_cndmask_b32_e32 v25, v200, v25, vcc
	s_cselect_b64 s[4:5], -1, 0
	v_cmp_gt_i32_e32 vcc, s1, v39
	v_mov_b32_e32 v38, s11
	s_and_b64 vcc, s[4:5], vcc
	v_cndmask_b32_e32 v18, v38, v18, vcc
	v_or_b32_e32 v38, 1, v39
	v_cmp_gt_i32_e32 vcc, s1, v38
	s_and_b64 vcc, s[4:5], vcc
	v_or_b32_e32 v38, 2, v39
	v_cndmask_b32_e32 v19, v200, v19, vcc
	v_cmp_gt_i32_e32 vcc, s1, v38
	s_and_b64 vcc, s[4:5], vcc
	v_or_b32_e32 v38, 3, v39
	v_cndmask_b32_e32 v20, v200, v20, vcc
	v_cmp_gt_i32_e32 vcc, s1, v38
	s_and_b64 vcc, s[4:5], vcc
	s_cmp_gt_i32 s10, -1
	v_or_b32_e32 v39, s10, v50
	v_cndmask_b32_e32 v21, v200, v21, vcc
	s_cselect_b64 s[4:5], -1, 0
	v_cmp_gt_i32_e32 vcc, s1, v39
	v_mov_b32_e32 v38, s11
	s_and_b64 vcc, s[4:5], vcc
	v_cndmask_b32_e32 v14, v38, v14, vcc
	v_or_b32_e32 v38, 1, v39
	v_cmp_gt_i32_e32 vcc, s1, v38
	s_and_b64 vcc, s[4:5], vcc
	v_or_b32_e32 v38, 2, v39
	v_cndmask_b32_e32 v15, v200, v15, vcc
	v_cmp_gt_i32_e32 vcc, s1, v38
	s_and_b64 vcc, s[4:5], vcc
	v_or_b32_e32 v38, 3, v39
	v_cndmask_b32_e32 v16, v200, v16, vcc
	v_cmp_gt_i32_e32 vcc, s1, v38
	s_and_b64 vcc, s[4:5], vcc
	s_cmpk_gt_i32 s10, 0xffef
	v_add_u32_e32 v39, s10, v88
	v_cndmask_b32_e32 v17, v200, v17, vcc
	s_cselect_b64 s[4:5], -1, 0
	v_cmp_gt_i32_e32 vcc, s1, v39
	v_mov_b32_e32 v38, s11
	s_and_b64 vcc, s[4:5], vcc
	v_cndmask_b32_e32 v10, v38, v10, vcc
	v_or_b32_e32 v38, 1, v39
	v_cmp_gt_i32_e32 vcc, s1, v38
	s_and_b64 vcc, s[4:5], vcc
	v_or_b32_e32 v38, 2, v39
	v_cndmask_b32_e32 v11, v200, v11, vcc
	v_cmp_gt_i32_e32 vcc, s1, v38
	s_and_b64 vcc, s[4:5], vcc
	v_or_b32_e32 v38, 3, v39
	v_cndmask_b32_e32 v12, v200, v12, vcc
	v_cmp_gt_i32_e32 vcc, s1, v38
	s_and_b64 vcc, s[4:5], vcc
	s_cmpk_gt_i32 s10, 0xffdf
	v_add_u32_e32 v39, s10, v89
	v_cndmask_b32_e32 v13, v200, v13, vcc
	s_cselect_b64 s[4:5], -1, 0
	v_cmp_gt_i32_e32 vcc, s1, v39
	v_mov_b32_e32 v38, s11
	s_and_b64 vcc, s[4:5], vcc
	v_cndmask_b32_e32 v6, v38, v6, vcc
	v_or_b32_e32 v38, 1, v39
	v_cmp_gt_i32_e32 vcc, s1, v38
	s_and_b64 vcc, s[4:5], vcc
	v_or_b32_e32 v38, 2, v39
	v_cndmask_b32_e32 v7, v200, v7, vcc
	v_cmp_gt_i32_e32 vcc, s1, v38
	s_and_b64 vcc, s[4:5], vcc
	v_or_b32_e32 v38, 3, v39
	v_cndmask_b32_e32 v8, v200, v8, vcc
	v_cmp_gt_i32_e32 vcc, s1, v38
	s_and_b64 vcc, s[4:5], vcc
	s_cmpk_gt_i32 s10, 0xffcf
	v_add_u32_e32 v39, s10, v90
	v_cndmask_b32_e32 v9, v200, v9, vcc
	s_cselect_b64 s[4:5], -1, 0
	v_cmp_gt_i32_e32 vcc, s1, v39
	v_mov_b32_e32 v38, s11
	s_and_b64 vcc, s[4:5], vcc
	v_cndmask_b32_e32 v2, v38, v2, vcc
	v_or_b32_e32 v38, 1, v39
	v_cmp_gt_i32_e32 vcc, s1, v38
	s_and_b64 vcc, s[4:5], vcc
	v_or_b32_e32 v38, 2, v39
	v_cndmask_b32_e32 v3, v200, v3, vcc
	v_cmp_gt_i32_e32 vcc, s1, v38
	s_and_b64 vcc, s[4:5], vcc
	v_or_b32_e32 v38, 3, v39
	v_cndmask_b32_e32 v4, v200, v4, vcc
	v_cmp_gt_i32_e32 vcc, s1, v38
	s_and_b64 vcc, s[4:5], vcc
	s_cmpk_gt_i32 s10, 0xffbf
	v_add_u32_e32 v39, s10, v91
	v_cndmask_b32_e32 v5, v200, v5, vcc
	s_cselect_b64 s[4:5], -1, 0
	v_cmp_gt_i32_e32 vcc, s1, v39
	v_mov_b32_e32 v38, s11
	s_and_b64 vcc, s[4:5], vcc
	v_cndmask_b32_e32 v34, v38, v34, vcc
	v_or_b32_e32 v38, 1, v39
	v_cmp_gt_i32_e32 vcc, s1, v38
	s_and_b64 vcc, s[4:5], vcc
	v_or_b32_e32 v38, 2, v39
	v_cndmask_b32_e32 v35, v200, v35, vcc
	v_cmp_gt_i32_e32 vcc, s1, v38
	s_and_b64 vcc, s[4:5], vcc
	v_or_b32_e32 v38, 3, v39
	v_cndmask_b32_e32 v36, v200, v36, vcc
	v_cmp_gt_i32_e32 vcc, s1, v38
	s_and_b64 vcc, s[4:5], vcc
	s_nop 0
	v_cndmask_b32_e32 v37, v200, v37, vcc
